# GEMM K-loops: mid-segment s_setprio 0/1 flip pair between the two 16-MFMA groups removed, on top of setprio-0-after-barrier
# baseline (speedup 1.0000x reference)
; #define PG8_STAGE(bufoff, gbase, voff) do { _Pragma("unroll") for (int _i = 0; _i < 2; ++_i) \
;         __builtin_amdgcn_global_load_lds((const unsigned*)((const char*)(gbase) + (voff)[_i]), (LAS unsigned*)(lds + (bufoff) + ldsw + _i * 8192), 16, 0, 0); } while (0)
; #define PG8_LDA(dst, b, h) do { _Pragma("unroll") for (int m = 0; m < 4; ++m) _Pragma("unroll") for (int k = 0; k < 2; ++k) dst[m][k] = *(const LAS bf16x8*)(lds + PG8_SA(b, h) + aoff + m * 2048 + k * 1024); } while (0)
; #define PG8_LDB(dst, b, h) do { _Pragma("unroll") for (int n = 0; n < 2; ++n) _Pragma("unroll") for (int k = 0; k < 2; ++k) dst[n][k] = *(const LAS bf16x8*)(lds + PG8_SB(b, h) + boff + n * 2048 + k * 1024); } while (0)
; #define PG8_MMA(ai, bj, At, Bt) do { __builtin_amdgcn_s_setprio(1); _Pragma("unroll") for (int m = 0; m < 4; ++m) _Pragma("unroll") for (int n = 0; n < 2; ++n) _Pragma("unroll") for (int k = 0; k < 2; ++k) \
;         acc[ai][bj][m][n] = __builtin_amdgcn_mfma_f32_16x16x32_bf16(Bt[n][k], At[m][k], acc[ai][bj][m][n], 0, 0, 0); __builtin_amdgcn_s_setprio(0); } while (0)
; #define PG8_WAIT_V(n) asm volatile("s_waitcnt vmcnt(" #n ")" ::: "memory")
; #define PG8_WAIT_L(n) asm volatile("s_waitcnt lgkmcnt(" #n ")" ::: "memory")
; template <class Epi, class Sched, bool ALIGN_EPI, bool LAST_FUSED = false, bool PERM = false, bool CARRY = false>
; __device__ __forceinline__ void gemm_phase(LAS unsigned char* lds, const int tid, const int K, const int lda, const int ldb, const Sched& S, const Epi& E) {
;     ...
;         for (int t = 0; t < nt; t += 2) {
;             const bool last = (t == nt - 2);
;             const char* a1 = cA + (size_t)(t + 1) * kstep;
;             const char* a2 = last ? nA : cA + (size_t)(t + 2) * kstep; const char* b2 = last ? nB : cB + (size_t)(t + 2) * kstep;
;             const char* a3 = a2 + kstep; const char* b3 = b2 + kstep;
;             PG8_LDB(B0, 0, 0); PG8_LDB(B1, 0, 1); PG8_SCHED; PG8_LDA(At, 0, 0); PG8_STAGE(PG8_SA(1, 1), a1 + hstepA, voffA);
;             PG8_WAIT_V(8); PG8_WAIT_L(0); PG8_BAR; PG8_MMA(0, 0, At, B0); PG8_MMA(0, 1, At, B1); PG8_BAR; PG8_SCHED;
;             PG8_LDA(At, 0, 1); PG8_STAGE(PG8_SB(0, 0), b2, voffB); PG8_STAGE(PG8_SB(0, 1), b2 + hstepB, voffB); PG8_STAGE(PG8_SA(0, 0), a2, voffA);
;             PG8_WAIT_V(8); PG8_WAIT_L(0); PG8_BAR; PG8_MMA(1, 0, At, B0); PG8_MMA(1, 1, At, B1); PG8_BAR; PG8_SCHED;
.LBB0_279:
	s_add_u32 s4, s2, 0xfff80080
	s_addc_u32 s5, s3, -1
	s_add_i32 s28, 0, 0x10000
	s_cmp_eq_u32 s27, 28
	s_cselect_b32 s37, s43, s5
	s_cselect_b32 s36, s42, s4
	s_cselect_b32 s5, s71, s23
	s_cselect_b32 s4, s70, s22
	s_add_i32 s31, 0, 0x14000
	v_add_u32_e32 v154, s28, v144
	v_add_u32_e32 v170, s31, v144
	ds_read_b128 v[136:139], v154
	ds_read_b128 v[146:149], v154 offset:1024
	ds_read_b128 v[150:153], v154 offset:2048
	ds_read_b128 v[154:157], v154 offset:3072
	ds_read_b128 v[158:161], v170
	ds_read_b128 v[162:165], v170 offset:1024
	ds_read_b128 v[166:169], v170 offset:2048
	ds_read_b128 v[170:173], v170 offset:3072
	v_lshl_add_u64 v[206:207], s[2:3], 0, v[132:133]
	s_add_i32 m0, s52, 0xc000
	ds_read_b128 v[174:177], v145
	ds_read_b128 v[178:181], v145 offset:1024
	ds_read_b128 v[182:185], v145 offset:2048
	ds_read_b128 v[186:189], v145 offset:3072
	ds_read_b128 v[190:193], v145 offset:4096
	ds_read_b128 v[194:197], v145 offset:5120
	ds_read_b128 v[198:201], v145 offset:6144
	ds_read_b128 v[202:205], v145 offset:7168
	global_load_lds_dwordx4 v[206:207], off
	v_lshl_add_u64 v[206:207], s[2:3], 0, v[134:135]
	s_add_i32 m0, s52, 0xe000
	s_nop 0
	global_load_lds_dwordx4 v[206:207], off
	s_waitcnt vmcnt(8)
	s_waitcnt lgkmcnt(0)
	s_barrier
	s_setprio 1
	v_mfma_f32_16x16x32_bf16 v[126:129], v[136:139], v[174:177], v[126:129]
	v_mfma_f32_16x16x32_bf16 v[122:125], v[150:153], v[174:177], v[122:125]
	v_mfma_f32_16x16x32_bf16 v[110:113], v[136:139], v[182:185], v[110:113]
	v_mfma_f32_16x16x32_bf16 v[106:109], v[150:153], v[182:185], v[106:109]
	v_mfma_f32_16x16x32_bf16 v[94:97], v[136:139], v[190:193], v[94:97]
	v_mfma_f32_16x16x32_bf16 v[90:93], v[150:153], v[190:193], v[90:93]
	v_mfma_f32_16x16x32_bf16 v[78:81], v[136:139], v[198:201], v[78:81]
	v_mfma_f32_16x16x32_bf16 v[74:77], v[150:153], v[198:201], v[74:77]
	v_mfma_f32_16x16x32_bf16 v[126:129], v[146:149], v[178:181], v[126:129]
	v_mfma_f32_16x16x32_bf16 v[122:125], v[154:157], v[178:181], v[122:125]
	v_mfma_f32_16x16x32_bf16 v[110:113], v[146:149], v[186:189], v[110:113]
	v_mfma_f32_16x16x32_bf16 v[106:109], v[154:157], v[186:189], v[106:109]
	v_mfma_f32_16x16x32_bf16 v[94:97], v[146:149], v[194:197], v[94:97]
	v_mfma_f32_16x16x32_bf16 v[90:93], v[154:157], v[194:197], v[90:93]
	v_mfma_f32_16x16x32_bf16 v[78:81], v[146:149], v[202:205], v[78:81]
	v_mfma_f32_16x16x32_bf16 v[74:77], v[154:157], v[202:205], v[74:77]
	v_mfma_f32_16x16x32_bf16 v[118:121], v[158:161], v[174:177], v[118:121]
	v_mfma_f32_16x16x32_bf16 v[114:117], v[166:169], v[174:177], v[114:117]
	v_mfma_f32_16x16x32_bf16 v[102:105], v[158:161], v[182:185], v[102:105]
	v_mfma_f32_16x16x32_bf16 v[98:101], v[166:169], v[182:185], v[98:101]
	v_mfma_f32_16x16x32_bf16 v[86:89], v[158:161], v[190:193], v[86:89]
	v_mfma_f32_16x16x32_bf16 v[82:85], v[166:169], v[190:193], v[82:85]
	v_mfma_f32_16x16x32_bf16 v[70:73], v[158:161], v[198:201], v[70:73]
	v_mfma_f32_16x16x32_bf16 v[66:69], v[166:169], v[198:201], v[66:69]
	v_mfma_f32_16x16x32_bf16 v[118:121], v[162:165], v[178:181], v[118:121]
	v_mfma_f32_16x16x32_bf16 v[114:117], v[170:173], v[178:181], v[114:117]
	v_mfma_f32_16x16x32_bf16 v[102:105], v[162:165], v[186:189], v[102:105]
	v_mfma_f32_16x16x32_bf16 v[98:101], v[170:173], v[186:189], v[98:101]
	v_mfma_f32_16x16x32_bf16 v[86:89], v[162:165], v[194:197], v[86:89]
	v_mfma_f32_16x16x32_bf16 v[82:85], v[170:173], v[194:197], v[82:85]
	v_mfma_f32_16x16x32_bf16 v[70:73], v[162:165], v[202:205], v[70:73]
	v_mfma_f32_16x16x32_bf16 v[66:69], v[170:173], v[202:205], v[66:69]
	s_barrier
	s_setprio 0
	s_add_i32 s28, s28, s51
	v_lshl_add_u64 v[206:207], s[4:5], 0, v[0:1]
	s_mov_b32 m0, s28
	ds_read_b128 v[174:177], v145 offset:16384
	ds_read_b128 v[178:181], v145 offset:17408
	ds_read_b128 v[182:185], v145 offset:18432
	ds_read_b128 v[186:189], v145 offset:19456
	ds_read_b128 v[190:193], v145 offset:20480
	ds_read_b128 v[194:197], v145 offset:21504
	ds_read_b128 v[198:201], v145 offset:22528
	ds_read_b128 v[202:205], v145 offset:23552
	global_load_lds_dwordx4 v[206:207], off
	s_add_i32 m0, s28, 0x2000
	s_add_u32 s28, s4, 0x80000
	v_lshl_add_u64 v[208:209], s[4:5], 0, v[130:131]
	s_addc_u32 s29, s5, 0
	s_add_i32 s31, s31, s51
	global_load_lds_dwordx4 v[208:209], off
	v_lshl_add_u64 v[210:211], s[28:29], 0, v[0:1]
	s_mov_b32 m0, s31
	v_lshl_add_u64 v[212:213], s[36:37], 0, v[130:131]
	global_load_lds_dwordx4 v[210:211], off
	v_lshl_add_u64 v[210:211], s[28:29], 0, v[130:131]
	s_add_i32 m0, s31, 0x2000
	s_nop 0
	global_load_lds_dwordx4 v[210:211], off
	v_lshl_add_u64 v[210:211], s[36:37], 0, v[0:1]
	s_mov_b32 m0, s52
	s_nop 0
	global_load_lds_dwordx4 v[210:211], off
	s_mov_b32 m0, s53
	s_nop 0
	global_load_lds_dwordx4 v[212:213], off
	s_waitcnt vmcnt(8)
	s_waitcnt lgkmcnt(0)
	s_barrier
; #define PG8_STAGE(bufoff, gbase, voff) do { _Pragma("unroll") for (int _i = 0; _i < 2; ++_i) \
;         __builtin_amdgcn_global_load_lds((const unsigned*)((const char*)(gbase) + (voff)[_i]), (LAS unsigned*)(lds + (bufoff) + ldsw + _i * 8192), 16, 0, 0); } while (0)
; #define PG8_LDA(dst, b, h) do { _Pragma("unroll") for (int m = 0; m < 4; ++m) _Pragma("unroll") for (int k = 0; k < 2; ++k) dst[m][k] = *(const LAS bf16x8*)(lds + PG8_SA(b, h) + aoff + m * 2048 + k * 1024); } while (0)
; #define PG8_LDB(dst, b, h) do { _Pragma("unroll") for (int n = 0; n < 2; ++n) _Pragma("unroll") for (int k = 0; k < 2; ++k) dst[n][k] = *(const LAS bf16x8*)(lds + PG8_SB(b, h) + boff + n * 2048 + k * 1024); } while (0)
; #define PG8_MMA(ai, bj, At, Bt) do { __builtin_amdgcn_s_setprio(1); _Pragma("unroll") for (int m = 0; m < 4; ++m) _Pragma("unroll") for (int n = 0; n < 2; ++n) _Pragma("unroll") for (int k = 0; k < 2; ++k) \
;         acc[ai][bj][m][n] = __builtin_amdgcn_mfma_f32_16x16x32_bf16(Bt[n][k], At[m][k], acc[ai][bj][m][n], 0, 0, 0); __builtin_amdgcn_s_setprio(0); } while (0)
; #define PG8_WAIT_V(n) asm volatile("s_waitcnt vmcnt(" #n ")" ::: "memory")
; #define PG8_WAIT_L(n) asm volatile("s_waitcnt lgkmcnt(" #n ")" ::: "memory")
; #define PG8_BAR __builtin_amdgcn_s_barrier()
; #define PG8_SCHED __builtin_amdgcn_sched_barrier(0)
; template <class Epi, class Sched, bool ALIGN_EPI, bool LAST_FUSED = false, bool PERM = false, bool CARRY = false>
; __device__ __forceinline__ void gemm_phase(LAS unsigned char* lds, const int tid, const int K, const int lda, const int ldb, const Sched& S, const Epi& E) {
;     ...
;             PG8_WAIT_V(8); PG8_WAIT_L(0); PG8_BAR; PG8_MMA(1, 0, At, B0); PG8_MMA(1, 1, At, B1); PG8_BAR; PG8_SCHED;
;             PG8_LDB(B0, 1, 0); PG8_LDB(B1, 1, 1); PG8_SCHED; PG8_LDA(At, 1, 0); PG8_STAGE(PG8_SA(0, 1), a2 + hstepA, voffA);
;             PG8_WAIT_V(8); PG8_WAIT_L(0); PG8_BAR; PG8_MMA(0, 0, At, B0); PG8_MMA(0, 1, At, B1); PG8_BAR; PG8_SCHED;
;             PG8_LDA(At, 1, 1); PG8_STAGE(PG8_SB(1, 0), b3, voffB); PG8_STAGE(PG8_SB(1, 1), b3 + hstepB, voffB); PG8_STAGE(PG8_SA(1, 0), a3, voffA);
;             PG8_WAIT_V(8); PG8_WAIT_L(0); PG8_BAR; PG8_MMA(1, 0, At, B0); PG8_MMA(1, 1, At, B1); PG8_BAR; PG8_SCHED;
	s_setprio 1
	v_mfma_f32_16x16x32_bf16 v[62:65], v[136:139], v[174:177], v[62:65]
	v_mfma_f32_16x16x32_bf16 v[58:61], v[150:153], v[174:177], v[58:61]
	v_mfma_f32_16x16x32_bf16 v[46:49], v[136:139], v[182:185], v[46:49]
	v_mfma_f32_16x16x32_bf16 v[42:45], v[150:153], v[182:185], v[42:45]
	v_mfma_f32_16x16x32_bf16 v[30:33], v[136:139], v[190:193], v[30:33]
	v_mfma_f32_16x16x32_bf16 v[26:29], v[150:153], v[190:193], v[26:29]
	v_mfma_f32_16x16x32_bf16 v[14:17], v[136:139], v[198:201], v[14:17]
	v_mfma_f32_16x16x32_bf16 v[10:13], v[150:153], v[198:201], v[10:13]
	v_mfma_f32_16x16x32_bf16 v[62:65], v[146:149], v[178:181], v[62:65]
	v_mfma_f32_16x16x32_bf16 v[58:61], v[154:157], v[178:181], v[58:61]
	v_mfma_f32_16x16x32_bf16 v[46:49], v[146:149], v[186:189], v[46:49]
	v_mfma_f32_16x16x32_bf16 v[42:45], v[154:157], v[186:189], v[42:45]
	v_mfma_f32_16x16x32_bf16 v[30:33], v[146:149], v[194:197], v[30:33]
	v_mfma_f32_16x16x32_bf16 v[26:29], v[154:157], v[194:197], v[26:29]
	v_mfma_f32_16x16x32_bf16 v[14:17], v[146:149], v[202:205], v[14:17]
	v_mfma_f32_16x16x32_bf16 v[10:13], v[154:157], v[202:205], v[10:13]
	v_mfma_f32_16x16x32_bf16 v[54:57], v[158:161], v[174:177], v[54:57]
	v_mfma_f32_16x16x32_bf16 v[50:53], v[166:169], v[174:177], v[50:53]
	v_mfma_f32_16x16x32_bf16 v[38:41], v[158:161], v[182:185], v[38:41]
	v_mfma_f32_16x16x32_bf16 v[34:37], v[166:169], v[182:185], v[34:37]
	v_mfma_f32_16x16x32_bf16 v[22:25], v[158:161], v[190:193], v[22:25]
	v_mfma_f32_16x16x32_bf16 v[18:21], v[166:169], v[190:193], v[18:21]
	v_mfma_f32_16x16x32_bf16 v[6:9], v[158:161], v[198:201], v[6:9]
	v_mfma_f32_16x16x32_bf16 v[2:5], v[166:169], v[198:201], v[2:5]
	v_mfma_f32_16x16x32_bf16 v[54:57], v[162:165], v[178:181], v[54:57]
	v_mfma_f32_16x16x32_bf16 v[50:53], v[170:173], v[178:181], v[50:53]
	v_mfma_f32_16x16x32_bf16 v[38:41], v[162:165], v[186:189], v[38:41]
	v_mfma_f32_16x16x32_bf16 v[34:37], v[170:173], v[186:189], v[34:37]
	v_mfma_f32_16x16x32_bf16 v[22:25], v[162:165], v[194:197], v[22:25]
	v_mfma_f32_16x16x32_bf16 v[18:21], v[170:173], v[194:197], v[18:21]
	v_mfma_f32_16x16x32_bf16 v[6:9], v[162:165], v[202:205], v[6:9]
	v_mfma_f32_16x16x32_bf16 v[2:5], v[170:173], v[202:205], v[2:5]
	s_barrier
	s_setprio 0
	s_add_i32 s31, 0, 0x18000
	s_add_i32 s35, 0, 0x1c000
	v_add_u32_e32 v154, s31, v144
	v_add_u32_e32 v170, s35, v144
	ds_read_b128 v[136:139], v154
	ds_read_b128 v[146:149], v154 offset:1024
	ds_read_b128 v[150:153], v154 offset:2048
	ds_read_b128 v[154:157], v154 offset:3072
	ds_read_b128 v[158:161], v170
	ds_read_b128 v[162:165], v170 offset:1024
	ds_read_b128 v[166:169], v170 offset:2048
	ds_read_b128 v[170:173], v170 offset:3072
	s_add_u32 s28, s36, 0x80000
	s_addc_u32 s29, s37, 0
	s_mov_b32 m0, s54
	v_lshl_add_u64 v[214:215], s[28:29], 0, v[0:1]
	ds_read_b128 v[174:177], v145 offset:32768
	ds_read_b128 v[178:181], v145 offset:33792
	ds_read_b128 v[182:185], v145 offset:34816
	ds_read_b128 v[186:189], v145 offset:35840
	ds_read_b128 v[190:193], v145 offset:36864
	ds_read_b128 v[194:197], v145 offset:37888
	ds_read_b128 v[198:201], v145 offset:38912
	ds_read_b128 v[202:205], v145 offset:39936
	global_load_lds_dwordx4 v[214:215], off
	v_lshl_add_u64 v[214:215], s[28:29], 0, v[130:131]
	s_mov_b32 m0, s55
	s_nop 0
	global_load_lds_dwordx4 v[214:215], off
	s_waitcnt vmcnt(8)
	s_waitcnt lgkmcnt(0)
	s_barrier
	s_setprio 1
	v_mfma_f32_16x16x32_bf16 v[126:129], v[136:139], v[174:177], v[126:129]
	v_mfma_f32_16x16x32_bf16 v[122:125], v[150:153], v[174:177], v[122:125]
	v_mfma_f32_16x16x32_bf16 v[110:113], v[136:139], v[182:185], v[110:113]
	v_mfma_f32_16x16x32_bf16 v[106:109], v[150:153], v[182:185], v[106:109]
	v_mfma_f32_16x16x32_bf16 v[94:97], v[136:139], v[190:193], v[94:97]
	v_mfma_f32_16x16x32_bf16 v[90:93], v[150:153], v[190:193], v[90:93]
	v_mfma_f32_16x16x32_bf16 v[78:81], v[136:139], v[198:201], v[78:81]
	v_mfma_f32_16x16x32_bf16 v[74:77], v[150:153], v[198:201], v[74:77]
	v_mfma_f32_16x16x32_bf16 v[126:129], v[146:149], v[178:181], v[126:129]
	v_mfma_f32_16x16x32_bf16 v[122:125], v[154:157], v[178:181], v[122:125]
	v_mfma_f32_16x16x32_bf16 v[110:113], v[146:149], v[186:189], v[110:113]
	v_mfma_f32_16x16x32_bf16 v[106:109], v[154:157], v[186:189], v[106:109]
	v_mfma_f32_16x16x32_bf16 v[94:97], v[146:149], v[194:197], v[94:97]
	v_mfma_f32_16x16x32_bf16 v[90:93], v[154:157], v[194:197], v[90:93]
	v_mfma_f32_16x16x32_bf16 v[78:81], v[146:149], v[202:205], v[78:81]
	v_mfma_f32_16x16x32_bf16 v[74:77], v[154:157], v[202:205], v[74:77]
	v_mfma_f32_16x16x32_bf16 v[118:121], v[158:161], v[174:177], v[118:121]
	v_mfma_f32_16x16x32_bf16 v[114:117], v[166:169], v[174:177], v[114:117]
	v_mfma_f32_16x16x32_bf16 v[102:105], v[158:161], v[182:185], v[102:105]
	v_mfma_f32_16x16x32_bf16 v[98:101], v[166:169], v[182:185], v[98:101]
	v_mfma_f32_16x16x32_bf16 v[86:89], v[158:161], v[190:193], v[86:89]
	v_mfma_f32_16x16x32_bf16 v[82:85], v[166:169], v[190:193], v[82:85]
	v_mfma_f32_16x16x32_bf16 v[70:73], v[158:161], v[198:201], v[70:73]
	v_mfma_f32_16x16x32_bf16 v[66:69], v[166:169], v[198:201], v[66:69]
	v_mfma_f32_16x16x32_bf16 v[118:121], v[162:165], v[178:181], v[118:121]
	v_mfma_f32_16x16x32_bf16 v[114:117], v[170:173], v[178:181], v[114:117]
	v_mfma_f32_16x16x32_bf16 v[102:105], v[162:165], v[186:189], v[102:105]
	v_mfma_f32_16x16x32_bf16 v[98:101], v[170:173], v[186:189], v[98:101]
	v_mfma_f32_16x16x32_bf16 v[86:89], v[162:165], v[194:197], v[86:89]
	v_mfma_f32_16x16x32_bf16 v[82:85], v[170:173], v[194:197], v[82:85]
	v_mfma_f32_16x16x32_bf16 v[70:73], v[162:165], v[202:205], v[70:73]
	v_mfma_f32_16x16x32_bf16 v[66:69], v[170:173], v[202:205], v[66:69]
	s_barrier
; #define PG8_STAGE(bufoff, gbase, voff) do { _Pragma("unroll") for (int _i = 0; _i < 2; ++_i) \
;         __builtin_amdgcn_global_load_lds((const unsigned*)((const char*)(gbase) + (voff)[_i]), (LAS unsigned*)(lds + (bufoff) + ldsw + _i * 8192), 16, 0, 0); } while (0)
; #define PG8_LDA(dst, b, h) do { _Pragma("unroll") for (int m = 0; m < 4; ++m) _Pragma("unroll") for (int k = 0; k < 2; ++k) dst[m][k] = *(const LAS bf16x8*)(lds + PG8_SA(b, h) + aoff + m * 2048 + k * 1024); } while (0)
; #define PG8_MMA(ai, bj, At, Bt) do { __builtin_amdgcn_s_setprio(1); _Pragma("unroll") for (int m = 0; m < 4; ++m) _Pragma("unroll") for (int n = 0; n < 2; ++n) _Pragma("unroll") for (int k = 0; k < 2; ++k) \
;         acc[ai][bj][m][n] = __builtin_amdgcn_mfma_f32_16x16x32_bf16(Bt[n][k], At[m][k], acc[ai][bj][m][n], 0, 0, 0); __builtin_amdgcn_s_setprio(0); } while (0)
; #define PG8_WAIT_V(n) asm volatile("s_waitcnt vmcnt(" #n ")" ::: "memory")
; #define PG8_WAIT_L(n) asm volatile("s_waitcnt lgkmcnt(" #n ")" ::: "memory")
; #define PG8_BAR __builtin_amdgcn_s_barrier()
; #define PG8_SCHED __builtin_amdgcn_sched_barrier(0)
; template <class Epi, class Sched, bool ALIGN_EPI, bool LAST_FUSED = false, bool PERM = false, bool CARRY = false>
; __device__ __forceinline__ void gemm_phase(LAS unsigned char* lds, const int tid, const int K, const int lda, const int ldb, const Sched& S, const Epi& E) {
;     ...
;             PG8_LDA(At, 1, 1); PG8_STAGE(PG8_SB(1, 0), b3, voffB); PG8_STAGE(PG8_SB(1, 1), b3 + hstepB, voffB); PG8_STAGE(PG8_SA(1, 0), a3, voffA);
;             PG8_WAIT_V(8); PG8_WAIT_L(0); PG8_BAR; PG8_MMA(1, 0, At, B0); PG8_MMA(1, 1, At, B1); PG8_BAR; PG8_SCHED;
;         }
;         if constexpr (ALIGN_EPI) { if (wr == 0) PG8_BAR; }
	s_setprio 0
	s_add_i32 s28, s31, s51
	v_lshl_add_u64 v[206:207], v[206:207], 0, s[68:69]
	s_mov_b32 m0, s28
	ds_read_b128 v[174:177], v145 offset:49152
	ds_read_b128 v[178:181], v145 offset:50176
	ds_read_b128 v[182:185], v145 offset:51200
	ds_read_b128 v[186:189], v145 offset:52224
	ds_read_b128 v[190:193], v145 offset:53248
	ds_read_b128 v[194:197], v145 offset:54272
	ds_read_b128 v[198:201], v145 offset:55296
	ds_read_b128 v[202:205], v145 offset:56320
	global_load_lds_dwordx4 v[206:207], off
	s_add_i32 m0, s28, 0x2000
	s_add_u32 s4, s4, 0x80080
	v_lshl_add_u64 v[206:207], v[208:209], 0, s[68:69]
	s_addc_u32 s5, s5, 0
	s_add_i32 s28, s35, s51
	global_load_lds_dwordx4 v[206:207], off
	v_lshl_add_u64 v[206:207], s[4:5], 0, v[0:1]
	s_mov_b32 m0, s28
	s_nop 0
	global_load_lds_dwordx4 v[206:207], off
	v_lshl_add_u64 v[206:207], s[4:5], 0, v[130:131]
	s_add_i32 m0, s28, 0x2000
	s_nop 0
	global_load_lds_dwordx4 v[206:207], off
	v_lshl_add_u64 v[206:207], v[210:211], 0, s[68:69]
	s_mov_b32 m0, s57
	s_nop 0
	global_load_lds_dwordx4 v[206:207], off
	v_lshl_add_u64 v[206:207], v[212:213], 0, s[68:69]
	s_mov_b32 m0, s58
	s_nop 0
	global_load_lds_dwordx4 v[206:207], off
	s_waitcnt vmcnt(8)
	s_waitcnt lgkmcnt(0)
	s_barrier
	s_setprio 1
	v_mfma_f32_16x16x32_bf16 v[62:65], v[136:139], v[174:177], v[62:65]
	v_mfma_f32_16x16x32_bf16 v[58:61], v[150:153], v[174:177], v[58:61]
	v_mfma_f32_16x16x32_bf16 v[46:49], v[136:139], v[182:185], v[46:49]
	v_mfma_f32_16x16x32_bf16 v[42:45], v[150:153], v[182:185], v[42:45]
	v_mfma_f32_16x16x32_bf16 v[30:33], v[136:139], v[190:193], v[30:33]
	v_mfma_f32_16x16x32_bf16 v[26:29], v[150:153], v[190:193], v[26:29]
	v_mfma_f32_16x16x32_bf16 v[14:17], v[136:139], v[198:201], v[14:17]
	v_mfma_f32_16x16x32_bf16 v[10:13], v[150:153], v[198:201], v[10:13]
	v_mfma_f32_16x16x32_bf16 v[62:65], v[146:149], v[178:181], v[62:65]
	v_mfma_f32_16x16x32_bf16 v[58:61], v[154:157], v[178:181], v[58:61]
	v_mfma_f32_16x16x32_bf16 v[46:49], v[146:149], v[186:189], v[46:49]
	v_mfma_f32_16x16x32_bf16 v[42:45], v[154:157], v[186:189], v[42:45]
	v_mfma_f32_16x16x32_bf16 v[30:33], v[146:149], v[194:197], v[30:33]
	v_mfma_f32_16x16x32_bf16 v[26:29], v[154:157], v[194:197], v[26:29]
	v_mfma_f32_16x16x32_bf16 v[14:17], v[146:149], v[202:205], v[14:17]
	v_mfma_f32_16x16x32_bf16 v[10:13], v[154:157], v[202:205], v[10:13]
	v_mfma_f32_16x16x32_bf16 v[54:57], v[158:161], v[174:177], v[54:57]
	v_mfma_f32_16x16x32_bf16 v[50:53], v[166:169], v[174:177], v[50:53]
	v_mfma_f32_16x16x32_bf16 v[38:41], v[158:161], v[182:185], v[38:41]
	v_mfma_f32_16x16x32_bf16 v[34:37], v[166:169], v[182:185], v[34:37]
	v_mfma_f32_16x16x32_bf16 v[22:25], v[158:161], v[190:193], v[22:25]
	v_mfma_f32_16x16x32_bf16 v[18:21], v[166:169], v[190:193], v[18:21]
	v_mfma_f32_16x16x32_bf16 v[6:9], v[158:161], v[198:201], v[6:9]
	v_mfma_f32_16x16x32_bf16 v[2:5], v[166:169], v[198:201], v[2:5]
	v_mfma_f32_16x16x32_bf16 v[54:57], v[162:165], v[178:181], v[54:57]
	v_mfma_f32_16x16x32_bf16 v[50:53], v[170:173], v[178:181], v[50:53]
	v_mfma_f32_16x16x32_bf16 v[38:41], v[162:165], v[186:189], v[38:41]
	v_mfma_f32_16x16x32_bf16 v[34:37], v[170:173], v[186:189], v[34:37]
	v_mfma_f32_16x16x32_bf16 v[22:25], v[162:165], v[194:197], v[22:25]
	v_mfma_f32_16x16x32_bf16 v[18:21], v[170:173], v[194:197], v[18:21]
	v_mfma_f32_16x16x32_bf16 v[6:9], v[162:165], v[202:205], v[6:9]
	v_mfma_f32_16x16x32_bf16 v[2:5], v[170:173], v[202:205], v[2:5]
	s_barrier
	s_setprio 0
	s_add_i32 s27, s27, 2
	s_add_u32 s2, s2, 0x100
	s_addc_u32 s3, s3, 0
	s_add_u32 s22, s22, 0x100
	s_addc_u32 s23, s23, 0
	s_cmp_gt_u32 s27, 29
	s_cbranch_scc0 .LBB0_279
	s_and_b64 vcc, exec, s[18:19]
	s_cbranch_vccz .LBB0_282
	s_barrier

; #define PG8_STAGE(bufoff, gbase, voff) do { _Pragma("unroll") for (int _i = 0; _i < 2; ++_i) \
;         __builtin_amdgcn_global_load_lds((const unsigned*)((const char*)(gbase) + (voff)[_i]), (LAS unsigned*)(lds + (bufoff) + ldsw + _i * 8192), 16, 0, 0); } while (0)
; #define PG8_LDA(dst, b, h) do { _Pragma("unroll") for (int m = 0; m < 4; ++m) _Pragma("unroll") for (int k = 0; k < 2; ++k) dst[m][k] = *(const LAS bf16x8*)(lds + PG8_SA(b, h) + aoff + m * 2048 + k * 1024); } while (0)
; #define PG8_LDB(dst, b, h) do { _Pragma("unroll") for (int n = 0; n < 2; ++n) _Pragma("unroll") for (int k = 0; k < 2; ++k) dst[n][k] = *(const LAS bf16x8*)(lds + PG8_SB(b, h) + boff + n * 2048 + k * 1024); } while (0)
; #define PG8_MMA(ai, bj, At, Bt) do { __builtin_amdgcn_s_setprio(1); _Pragma("unroll") for (int m = 0; m < 4; ++m) _Pragma("unroll") for (int n = 0; n < 2; ++n) _Pragma("unroll") for (int k = 0; k < 2; ++k) \
;         acc[ai][bj][m][n] = __builtin_amdgcn_mfma_f32_16x16x32_bf16(Bt[n][k], At[m][k], acc[ai][bj][m][n], 0, 0, 0); __builtin_amdgcn_s_setprio(0); } while (0)
; #define PG8_WAIT_V(n) asm volatile("s_waitcnt vmcnt(" #n ")" ::: "memory")
; #define PG8_WAIT_L(n) asm volatile("s_waitcnt lgkmcnt(" #n ")" ::: "memory")
; template <class Epi, class Sched, bool ALIGN_EPI, bool LAST_FUSED = false, bool PERM = false, bool CARRY = false>
; __device__ __forceinline__ void gemm_phase(LAS unsigned char* lds, const int tid, const int K, const int lda, const int ldb, const Sched& S, const Epi& E) {
;     ...
;         for (int t = 0; t < nt; t += 2) {
;             const bool last = (t == nt - 2);
;             const char* a1 = cA + (size_t)(t + 1) * kstep;
;             const char* a2 = last ? nA : cA + (size_t)(t + 2) * kstep; const char* b2 = last ? nB : cB + (size_t)(t + 2) * kstep;
;             const char* a3 = a2 + kstep; const char* b3 = b2 + kstep;
;             PG8_LDB(B0, 0, 0); PG8_LDB(B1, 0, 1); PG8_SCHED; PG8_LDA(At, 0, 0); PG8_STAGE(PG8_SA(1, 1), a1 + hstepA, voffA);
;             PG8_WAIT_V(8); PG8_WAIT_L(0); PG8_BAR; PG8_MMA(0, 0, At, B0); PG8_MMA(0, 1, At, B1); PG8_BAR; PG8_SCHED;
;             PG8_LDA(At, 0, 1); PG8_STAGE(PG8_SB(0, 0), b2, voffB); PG8_STAGE(PG8_SB(0, 1), b2 + hstepB, voffB); PG8_STAGE(PG8_SA(0, 0), a2, voffA);
;             PG8_WAIT_V(8); PG8_WAIT_L(0); PG8_BAR; PG8_MMA(1, 0, At, B0); PG8_MMA(1, 1, At, B1); PG8_BAR; PG8_SCHED;
.LBB0_512:
	s_add_u32 s28, s4, 0xfff80080
	s_addc_u32 s29, s5, -1
	s_add_i32 s31, 0, 0x10000
	s_cmp_eq_u32 s24, 28
	s_cselect_b32 s41, s87, s29
	s_cselect_b32 s40, s86, s28
	v_add_u32_e32 v148, s31, v160
	s_cselect_b32 s37, s39, s23
	s_cselect_b32 s36, s38, s22
	s_add_i32 s35, 0, 0x14000
	ds_read_b128 v[140:143], v148
	ds_read_b128 v[144:147], v148 offset:1024
	ds_read_b128 v[162:165], v148 offset:2048
	ds_read_b128 v[166:169], v148 offset:3072
	v_add_u32_e32 v148, s35, v160
	ds_read_b128 v[170:173], v148
	ds_read_b128 v[174:177], v148 offset:1024
	ds_read_b128 v[178:181], v148 offset:2048
	ds_read_b128 v[182:185], v148 offset:3072
	v_lshl_add_u64 v[148:149], s[4:5], 0, v[136:137]
	s_add_i32 m0, s54, 0xc000
	ds_read_b128 v[186:189], v161
	ds_read_b128 v[190:193], v161 offset:1024
	ds_read_b128 v[194:197], v161 offset:2048
	ds_read_b128 v[198:201], v161 offset:3072
	ds_read_b128 v[202:205], v161 offset:4096
	ds_read_b128 v[206:209], v161 offset:5120
	ds_read_b128 v[210:213], v161 offset:6144
	ds_read_b128 v[214:217], v161 offset:7168
	global_load_lds_dwordx4 v[148:149], off
	v_lshl_add_u64 v[148:149], s[4:5], 0, v[138:139]
	s_add_i32 m0, s54, 0xe000
	s_nop 0
	global_load_lds_dwordx4 v[148:149], off
	s_waitcnt vmcnt(8)
	s_waitcnt lgkmcnt(0)
	s_barrier
	s_setprio 1
	v_mfma_f32_16x16x32_bf16 v[126:129], v[140:143], v[186:189], v[126:129]
	v_mfma_f32_16x16x32_bf16 v[122:125], v[162:165], v[186:189], v[122:125]
	v_mfma_f32_16x16x32_bf16 v[110:113], v[140:143], v[194:197], v[110:113]
	v_mfma_f32_16x16x32_bf16 v[106:109], v[162:165], v[194:197], v[106:109]
	v_mfma_f32_16x16x32_bf16 v[94:97], v[140:143], v[202:205], v[94:97]
	v_mfma_f32_16x16x32_bf16 v[90:93], v[162:165], v[202:205], v[90:93]
	v_mfma_f32_16x16x32_bf16 v[78:81], v[140:143], v[210:213], v[78:81]
	v_mfma_f32_16x16x32_bf16 v[74:77], v[162:165], v[210:213], v[74:77]
	v_mfma_f32_16x16x32_bf16 v[126:129], v[144:147], v[190:193], v[126:129]
	v_mfma_f32_16x16x32_bf16 v[122:125], v[166:169], v[190:193], v[122:125]
	v_mfma_f32_16x16x32_bf16 v[110:113], v[144:147], v[198:201], v[110:113]
	v_mfma_f32_16x16x32_bf16 v[106:109], v[166:169], v[198:201], v[106:109]
	v_mfma_f32_16x16x32_bf16 v[94:97], v[144:147], v[206:209], v[94:97]
	v_mfma_f32_16x16x32_bf16 v[90:93], v[166:169], v[206:209], v[90:93]
	v_mfma_f32_16x16x32_bf16 v[78:81], v[144:147], v[214:217], v[78:81]
	v_mfma_f32_16x16x32_bf16 v[74:77], v[166:169], v[214:217], v[74:77]
	v_mfma_f32_16x16x32_bf16 v[118:121], v[170:173], v[186:189], v[118:121]
	v_mfma_f32_16x16x32_bf16 v[114:117], v[178:181], v[186:189], v[114:117]
	v_mfma_f32_16x16x32_bf16 v[102:105], v[170:173], v[194:197], v[102:105]
	v_mfma_f32_16x16x32_bf16 v[98:101], v[178:181], v[194:197], v[98:101]
	v_mfma_f32_16x16x32_bf16 v[86:89], v[170:173], v[202:205], v[86:89]
	v_mfma_f32_16x16x32_bf16 v[82:85], v[178:181], v[202:205], v[82:85]
	v_mfma_f32_16x16x32_bf16 v[70:73], v[170:173], v[210:213], v[70:73]
	v_mfma_f32_16x16x32_bf16 v[66:69], v[178:181], v[210:213], v[66:69]
	v_mfma_f32_16x16x32_bf16 v[118:121], v[174:177], v[190:193], v[118:121]
	v_mfma_f32_16x16x32_bf16 v[114:117], v[182:185], v[190:193], v[114:117]
	v_mfma_f32_16x16x32_bf16 v[102:105], v[174:177], v[198:201], v[102:105]
	v_mfma_f32_16x16x32_bf16 v[98:101], v[182:185], v[198:201], v[98:101]
	v_mfma_f32_16x16x32_bf16 v[86:89], v[174:177], v[206:209], v[86:89]
	v_mfma_f32_16x16x32_bf16 v[82:85], v[182:185], v[206:209], v[82:85]
	v_mfma_f32_16x16x32_bf16 v[70:73], v[174:177], v[214:217], v[70:73]
	v_mfma_f32_16x16x32_bf16 v[66:69], v[182:185], v[214:217], v[66:69]
	s_barrier
	s_setprio 0
	s_add_i32 s28, s31, s52
	v_lshl_add_u64 v[148:149], s[36:37], 0, v[0:1]
	s_mov_b32 m0, s28
	ds_read_b128 v[186:189], v161 offset:16384
	ds_read_b128 v[190:193], v161 offset:17408
	ds_read_b128 v[194:197], v161 offset:18432
	ds_read_b128 v[198:201], v161 offset:19456
	ds_read_b128 v[202:205], v161 offset:20480
	ds_read_b128 v[206:209], v161 offset:21504
	ds_read_b128 v[210:213], v161 offset:22528
	ds_read_b128 v[214:217], v161 offset:23552
	global_load_lds_dwordx4 v[148:149], off
	s_add_i32 m0, s28, 0x2000
	s_add_u32 s28, s36, 0x80000
	v_lshl_add_u64 v[152:153], s[36:37], 0, v[130:131]
	s_addc_u32 s29, s37, 0
	s_add_i32 s31, s35, s52
	global_load_lds_dwordx4 v[152:153], off
	v_lshl_add_u64 v[156:157], s[28:29], 0, v[0:1]
	s_mov_b32 m0, s31
	v_lshl_add_u64 v[218:219], s[40:41], 0, v[132:133]
	global_load_lds_dwordx4 v[156:157], off
	v_lshl_add_u64 v[156:157], s[28:29], 0, v[130:131]
	s_add_i32 m0, s31, 0x2000
	s_nop 0
	global_load_lds_dwordx4 v[156:157], off
	v_lshl_add_u64 v[156:157], s[40:41], 0, v[134:135]
	s_mov_b32 m0, s54
	s_nop 0
	global_load_lds_dwordx4 v[156:157], off
	s_mov_b32 m0, s55
	s_nop 0
	global_load_lds_dwordx4 v[218:219], off
	s_waitcnt vmcnt(8)
	s_waitcnt lgkmcnt(0)
	s_barrier
; #define PG8_STAGE(bufoff, gbase, voff) do { _Pragma("unroll") for (int _i = 0; _i < 2; ++_i) \
;         __builtin_amdgcn_global_load_lds((const unsigned*)((const char*)(gbase) + (voff)[_i]), (LAS unsigned*)(lds + (bufoff) + ldsw + _i * 8192), 16, 0, 0); } while (0)
; #define PG8_LDA(dst, b, h) do { _Pragma("unroll") for (int m = 0; m < 4; ++m) _Pragma("unroll") for (int k = 0; k < 2; ++k) dst[m][k] = *(const LAS bf16x8*)(lds + PG8_SA(b, h) + aoff + m * 2048 + k * 1024); } while (0)
; #define PG8_LDB(dst, b, h) do { _Pragma("unroll") for (int n = 0; n < 2; ++n) _Pragma("unroll") for (int k = 0; k < 2; ++k) dst[n][k] = *(const LAS bf16x8*)(lds + PG8_SB(b, h) + boff + n * 2048 + k * 1024); } while (0)
; #define PG8_MMA(ai, bj, At, Bt) do { __builtin_amdgcn_s_setprio(1); _Pragma("unroll") for (int m = 0; m < 4; ++m) _Pragma("unroll") for (int n = 0; n < 2; ++n) _Pragma("unroll") for (int k = 0; k < 2; ++k) \
;         acc[ai][bj][m][n] = __builtin_amdgcn_mfma_f32_16x16x32_bf16(Bt[n][k], At[m][k], acc[ai][bj][m][n], 0, 0, 0); __builtin_amdgcn_s_setprio(0); } while (0)
; #define PG8_WAIT_V(n) asm volatile("s_waitcnt vmcnt(" #n ")" ::: "memory")
; #define PG8_WAIT_L(n) asm volatile("s_waitcnt lgkmcnt(" #n ")" ::: "memory")
; #define PG8_BAR __builtin_amdgcn_s_barrier()
; #define PG8_SCHED __builtin_amdgcn_sched_barrier(0)
; template <class Epi, class Sched, bool ALIGN_EPI, bool LAST_FUSED = false, bool PERM = false, bool CARRY = false>
; __device__ __forceinline__ void gemm_phase(LAS unsigned char* lds, const int tid, const int K, const int lda, const int ldb, const Sched& S, const Epi& E) {
;     ...
;             PG8_WAIT_V(8); PG8_WAIT_L(0); PG8_BAR; PG8_MMA(1, 0, At, B0); PG8_MMA(1, 1, At, B1); PG8_BAR; PG8_SCHED;
;             PG8_LDB(B0, 1, 0); PG8_LDB(B1, 1, 1); PG8_SCHED; PG8_LDA(At, 1, 0); PG8_STAGE(PG8_SA(0, 1), a2 + hstepA, voffA);
;             PG8_WAIT_V(8); PG8_WAIT_L(0); PG8_BAR; PG8_MMA(0, 0, At, B0); PG8_MMA(0, 1, At, B1); PG8_BAR; PG8_SCHED;
;             PG8_LDA(At, 1, 1); PG8_STAGE(PG8_SB(1, 0), b3, voffB); PG8_STAGE(PG8_SB(1, 1), b3 + hstepB, voffB); PG8_STAGE(PG8_SA(1, 0), a3, voffA);
;             PG8_WAIT_V(8); PG8_WAIT_L(0); PG8_BAR; PG8_MMA(1, 0, At, B0); PG8_MMA(1, 1, At, B1); PG8_BAR; PG8_SCHED;
	s_setprio 1
	v_mfma_f32_16x16x32_bf16 v[62:65], v[140:143], v[186:189], v[62:65]
	v_mfma_f32_16x16x32_bf16 v[58:61], v[162:165], v[186:189], v[58:61]
	v_mfma_f32_16x16x32_bf16 v[46:49], v[140:143], v[194:197], v[46:49]
	v_mfma_f32_16x16x32_bf16 v[42:45], v[162:165], v[194:197], v[42:45]
	v_mfma_f32_16x16x32_bf16 v[30:33], v[140:143], v[202:205], v[30:33]
	v_mfma_f32_16x16x32_bf16 v[26:29], v[162:165], v[202:205], v[26:29]
	v_mfma_f32_16x16x32_bf16 v[14:17], v[140:143], v[210:213], v[14:17]
	v_mfma_f32_16x16x32_bf16 v[10:13], v[162:165], v[210:213], v[10:13]
	v_mfma_f32_16x16x32_bf16 v[62:65], v[144:147], v[190:193], v[62:65]
	v_mfma_f32_16x16x32_bf16 v[58:61], v[166:169], v[190:193], v[58:61]
	v_mfma_f32_16x16x32_bf16 v[46:49], v[144:147], v[198:201], v[46:49]
	v_mfma_f32_16x16x32_bf16 v[42:45], v[166:169], v[198:201], v[42:45]
	v_mfma_f32_16x16x32_bf16 v[30:33], v[144:147], v[206:209], v[30:33]
	v_mfma_f32_16x16x32_bf16 v[26:29], v[166:169], v[206:209], v[26:29]
	v_mfma_f32_16x16x32_bf16 v[14:17], v[144:147], v[214:217], v[14:17]
	v_mfma_f32_16x16x32_bf16 v[10:13], v[166:169], v[214:217], v[10:13]
	v_mfma_f32_16x16x32_bf16 v[54:57], v[170:173], v[186:189], v[54:57]
	v_mfma_f32_16x16x32_bf16 v[50:53], v[178:181], v[186:189], v[50:53]
	v_mfma_f32_16x16x32_bf16 v[38:41], v[170:173], v[194:197], v[38:41]
	v_mfma_f32_16x16x32_bf16 v[34:37], v[178:181], v[194:197], v[34:37]
	v_mfma_f32_16x16x32_bf16 v[22:25], v[170:173], v[202:205], v[22:25]
	v_mfma_f32_16x16x32_bf16 v[18:21], v[178:181], v[202:205], v[18:21]
	v_mfma_f32_16x16x32_bf16 v[6:9], v[170:173], v[210:213], v[6:9]
	v_mfma_f32_16x16x32_bf16 v[2:5], v[178:181], v[210:213], v[2:5]
	v_mfma_f32_16x16x32_bf16 v[54:57], v[174:177], v[190:193], v[54:57]
	v_mfma_f32_16x16x32_bf16 v[50:53], v[182:185], v[190:193], v[50:53]
	v_mfma_f32_16x16x32_bf16 v[38:41], v[174:177], v[198:201], v[38:41]
	v_mfma_f32_16x16x32_bf16 v[34:37], v[182:185], v[198:201], v[34:37]
	v_mfma_f32_16x16x32_bf16 v[22:25], v[174:177], v[206:209], v[22:25]
	v_mfma_f32_16x16x32_bf16 v[18:21], v[182:185], v[206:209], v[18:21]
	v_mfma_f32_16x16x32_bf16 v[6:9], v[174:177], v[214:217], v[6:9]
	v_mfma_f32_16x16x32_bf16 v[2:5], v[182:185], v[214:217], v[2:5]
	s_barrier
	s_setprio 0
	s_add_i32 s31, 0, 0x18000
	v_add_u32_e32 v150, s31, v160
	s_add_i32 s35, 0, 0x1c000
	ds_read_b128 v[140:143], v150
	ds_read_b128 v[144:147], v150 offset:1024
	ds_read_b128 v[162:165], v150 offset:2048
	ds_read_b128 v[166:169], v150 offset:3072
	v_add_u32_e32 v150, s35, v160
	ds_read_b128 v[170:173], v150
	ds_read_b128 v[174:177], v150 offset:1024
	ds_read_b128 v[178:181], v150 offset:2048
	ds_read_b128 v[182:185], v150 offset:3072
	s_add_u32 s28, s40, 0x80000
	s_addc_u32 s29, s41, 0
	s_mov_b32 m0, s56
	v_lshl_add_u64 v[220:221], s[28:29], 0, v[134:135]
	ds_read_b128 v[186:189], v161 offset:32768
	ds_read_b128 v[190:193], v161 offset:33792
	ds_read_b128 v[194:197], v161 offset:34816
	ds_read_b128 v[198:201], v161 offset:35840
	ds_read_b128 v[202:205], v161 offset:36864
	ds_read_b128 v[206:209], v161 offset:37888
	ds_read_b128 v[210:213], v161 offset:38912
	ds_read_b128 v[214:217], v161 offset:39936
	global_load_lds_dwordx4 v[220:221], off
	v_lshl_add_u64 v[220:221], s[28:29], 0, v[132:133]
	s_mov_b32 m0, s57
	s_nop 0
	global_load_lds_dwordx4 v[220:221], off
	s_waitcnt vmcnt(8)
	s_waitcnt lgkmcnt(0)
	s_barrier
	s_setprio 1
	v_mfma_f32_16x16x32_bf16 v[126:129], v[140:143], v[186:189], v[126:129]
	v_mfma_f32_16x16x32_bf16 v[122:125], v[162:165], v[186:189], v[122:125]
	v_mfma_f32_16x16x32_bf16 v[110:113], v[140:143], v[194:197], v[110:113]
	v_mfma_f32_16x16x32_bf16 v[106:109], v[162:165], v[194:197], v[106:109]
	v_mfma_f32_16x16x32_bf16 v[94:97], v[140:143], v[202:205], v[94:97]
	v_mfma_f32_16x16x32_bf16 v[90:93], v[162:165], v[202:205], v[90:93]
	v_mfma_f32_16x16x32_bf16 v[78:81], v[140:143], v[210:213], v[78:81]
	v_mfma_f32_16x16x32_bf16 v[74:77], v[162:165], v[210:213], v[74:77]
	v_mfma_f32_16x16x32_bf16 v[126:129], v[144:147], v[190:193], v[126:129]
	v_mfma_f32_16x16x32_bf16 v[122:125], v[166:169], v[190:193], v[122:125]
	v_mfma_f32_16x16x32_bf16 v[110:113], v[144:147], v[198:201], v[110:113]
	v_mfma_f32_16x16x32_bf16 v[106:109], v[166:169], v[198:201], v[106:109]
	v_mfma_f32_16x16x32_bf16 v[94:97], v[144:147], v[206:209], v[94:97]
	v_mfma_f32_16x16x32_bf16 v[90:93], v[166:169], v[206:209], v[90:93]
	v_mfma_f32_16x16x32_bf16 v[78:81], v[144:147], v[214:217], v[78:81]
	v_mfma_f32_16x16x32_bf16 v[74:77], v[166:169], v[214:217], v[74:77]
	v_mfma_f32_16x16x32_bf16 v[118:121], v[170:173], v[186:189], v[118:121]
	v_mfma_f32_16x16x32_bf16 v[114:117], v[178:181], v[186:189], v[114:117]
	v_mfma_f32_16x16x32_bf16 v[102:105], v[170:173], v[194:197], v[102:105]
	v_mfma_f32_16x16x32_bf16 v[98:101], v[178:181], v[194:197], v[98:101]
	v_mfma_f32_16x16x32_bf16 v[86:89], v[170:173], v[202:205], v[86:89]
	v_mfma_f32_16x16x32_bf16 v[82:85], v[178:181], v[202:205], v[82:85]
	v_mfma_f32_16x16x32_bf16 v[70:73], v[170:173], v[210:213], v[70:73]
	v_mfma_f32_16x16x32_bf16 v[66:69], v[178:181], v[210:213], v[66:69]
	v_mfma_f32_16x16x32_bf16 v[118:121], v[174:177], v[190:193], v[118:121]
	v_mfma_f32_16x16x32_bf16 v[114:117], v[182:185], v[190:193], v[114:117]
	v_mfma_f32_16x16x32_bf16 v[102:105], v[174:177], v[198:201], v[102:105]
	v_mfma_f32_16x16x32_bf16 v[98:101], v[182:185], v[198:201], v[98:101]
	v_mfma_f32_16x16x32_bf16 v[86:89], v[174:177], v[206:209], v[86:89]
	v_mfma_f32_16x16x32_bf16 v[82:85], v[182:185], v[206:209], v[82:85]
	v_mfma_f32_16x16x32_bf16 v[70:73], v[174:177], v[214:217], v[70:73]
	v_mfma_f32_16x16x32_bf16 v[66:69], v[182:185], v[214:217], v[66:69]
	s_barrier
; #define PG8_STAGE(bufoff, gbase, voff) do { _Pragma("unroll") for (int _i = 0; _i < 2; ++_i) \
;         __builtin_amdgcn_global_load_lds((const unsigned*)((const char*)(gbase) + (voff)[_i]), (LAS unsigned*)(lds + (bufoff) + ldsw + _i * 8192), 16, 0, 0); } while (0)
; #define PG8_LDA(dst, b, h) do { _Pragma("unroll") for (int m = 0; m < 4; ++m) _Pragma("unroll") for (int k = 0; k < 2; ++k) dst[m][k] = *(const LAS bf16x8*)(lds + PG8_SA(b, h) + aoff + m * 2048 + k * 1024); } while (0)
; #define PG8_MMA(ai, bj, At, Bt) do { __builtin_amdgcn_s_setprio(1); _Pragma("unroll") for (int m = 0; m < 4; ++m) _Pragma("unroll") for (int n = 0; n < 2; ++n) _Pragma("unroll") for (int k = 0; k < 2; ++k) \
;         acc[ai][bj][m][n] = __builtin_amdgcn_mfma_f32_16x16x32_bf16(Bt[n][k], At[m][k], acc[ai][bj][m][n], 0, 0, 0); __builtin_amdgcn_s_setprio(0); } while (0)
; #define PG8_WAIT_V(n) asm volatile("s_waitcnt vmcnt(" #n ")" ::: "memory")
; #define PG8_WAIT_L(n) asm volatile("s_waitcnt lgkmcnt(" #n ")" ::: "memory")
; #define PG8_BAR __builtin_amdgcn_s_barrier()
; #define PG8_SCHED __builtin_amdgcn_sched_barrier(0)
; template <class Epi, class Sched, bool ALIGN_EPI, bool LAST_FUSED = false, bool PERM = false, bool CARRY = false>
; __device__ __forceinline__ void gemm_phase(LAS unsigned char* lds, const int tid, const int K, const int lda, const int ldb, const Sched& S, const Epi& E) {
;     ...
;             PG8_LDA(At, 1, 1); PG8_STAGE(PG8_SB(1, 0), b3, voffB); PG8_STAGE(PG8_SB(1, 1), b3 + hstepB, voffB); PG8_STAGE(PG8_SA(1, 0), a3, voffA);
;             PG8_WAIT_V(8); PG8_WAIT_L(0); PG8_BAR; PG8_MMA(1, 0, At, B0); PG8_MMA(1, 1, At, B1); PG8_BAR; PG8_SCHED;
;         }
;         if constexpr (ALIGN_EPI) { if (wr == 0) PG8_BAR; }
	s_setprio 0
	s_add_i32 s28, s31, s52
	v_lshl_add_u64 v[148:149], v[148:149], 0, s[68:69]
	s_mov_b32 m0, s28
	ds_read_b128 v[186:189], v161 offset:49152
	ds_read_b128 v[190:193], v161 offset:50176
	ds_read_b128 v[194:197], v161 offset:51200
	ds_read_b128 v[198:201], v161 offset:52224
	ds_read_b128 v[202:205], v161 offset:53248
	ds_read_b128 v[206:209], v161 offset:54272
	ds_read_b128 v[210:213], v161 offset:55296
	ds_read_b128 v[214:217], v161 offset:56320
	global_load_lds_dwordx4 v[148:149], off
	s_add_i32 m0, s28, 0x2000
	s_add_u32 s28, s36, 0x80080
	v_lshl_add_u64 v[148:149], v[152:153], 0, s[68:69]
	s_addc_u32 s29, s37, 0
	s_add_i32 s31, s35, s52
	global_load_lds_dwordx4 v[148:149], off
	v_lshl_add_u64 v[148:149], s[28:29], 0, v[0:1]
	s_mov_b32 m0, s31
	s_nop 0
	global_load_lds_dwordx4 v[148:149], off
	v_lshl_add_u64 v[148:149], s[28:29], 0, v[130:131]
	s_add_i32 m0, s31, 0x2000
	s_nop 0
	global_load_lds_dwordx4 v[148:149], off
	v_lshl_add_u64 v[148:149], v[156:157], 0, s[68:69]
	s_mov_b32 m0, s59
	s_nop 0
	global_load_lds_dwordx4 v[148:149], off
	v_lshl_add_u64 v[148:149], v[218:219], 0, s[68:69]
	s_mov_b32 m0, s60
	s_nop 0
	global_load_lds_dwordx4 v[148:149], off
	s_waitcnt vmcnt(8)
	s_waitcnt lgkmcnt(0)
	s_barrier
	s_setprio 1
	v_mfma_f32_16x16x32_bf16 v[62:65], v[140:143], v[186:189], v[62:65]
	v_mfma_f32_16x16x32_bf16 v[58:61], v[162:165], v[186:189], v[58:61]
	v_mfma_f32_16x16x32_bf16 v[46:49], v[140:143], v[194:197], v[46:49]
	v_mfma_f32_16x16x32_bf16 v[42:45], v[162:165], v[194:197], v[42:45]
	v_mfma_f32_16x16x32_bf16 v[30:33], v[140:143], v[202:205], v[30:33]
	v_mfma_f32_16x16x32_bf16 v[26:29], v[162:165], v[202:205], v[26:29]
	v_mfma_f32_16x16x32_bf16 v[14:17], v[140:143], v[210:213], v[14:17]
	v_mfma_f32_16x16x32_bf16 v[10:13], v[162:165], v[210:213], v[10:13]
	v_mfma_f32_16x16x32_bf16 v[62:65], v[144:147], v[190:193], v[62:65]
	v_mfma_f32_16x16x32_bf16 v[58:61], v[166:169], v[190:193], v[58:61]
	v_mfma_f32_16x16x32_bf16 v[46:49], v[144:147], v[198:201], v[46:49]
	v_mfma_f32_16x16x32_bf16 v[42:45], v[166:169], v[198:201], v[42:45]
	v_mfma_f32_16x16x32_bf16 v[30:33], v[144:147], v[206:209], v[30:33]
	v_mfma_f32_16x16x32_bf16 v[26:29], v[166:169], v[206:209], v[26:29]
	v_mfma_f32_16x16x32_bf16 v[14:17], v[144:147], v[214:217], v[14:17]
	v_mfma_f32_16x16x32_bf16 v[10:13], v[166:169], v[214:217], v[10:13]
	v_mfma_f32_16x16x32_bf16 v[54:57], v[170:173], v[186:189], v[54:57]
	v_mfma_f32_16x16x32_bf16 v[50:53], v[178:181], v[186:189], v[50:53]
	v_mfma_f32_16x16x32_bf16 v[38:41], v[170:173], v[194:197], v[38:41]
	v_mfma_f32_16x16x32_bf16 v[34:37], v[178:181], v[194:197], v[34:37]
	v_mfma_f32_16x16x32_bf16 v[22:25], v[170:173], v[202:205], v[22:25]
	v_mfma_f32_16x16x32_bf16 v[18:21], v[178:181], v[202:205], v[18:21]
	v_mfma_f32_16x16x32_bf16 v[6:9], v[170:173], v[210:213], v[6:9]
	v_mfma_f32_16x16x32_bf16 v[2:5], v[178:181], v[210:213], v[2:5]
	v_mfma_f32_16x16x32_bf16 v[54:57], v[174:177], v[190:193], v[54:57]
	v_mfma_f32_16x16x32_bf16 v[50:53], v[182:185], v[190:193], v[50:53]
	v_mfma_f32_16x16x32_bf16 v[38:41], v[174:177], v[198:201], v[38:41]
	v_mfma_f32_16x16x32_bf16 v[34:37], v[182:185], v[198:201], v[34:37]
	v_mfma_f32_16x16x32_bf16 v[22:25], v[174:177], v[206:209], v[22:25]
	v_mfma_f32_16x16x32_bf16 v[18:21], v[182:185], v[206:209], v[18:21]
	v_mfma_f32_16x16x32_bf16 v[6:9], v[174:177], v[214:217], v[6:9]
	v_mfma_f32_16x16x32_bf16 v[2:5], v[182:185], v[214:217], v[2:5]
	s_barrier
	s_setprio 0
	s_add_i32 s24, s24, 2
	s_add_u32 s4, s4, 0x100
	s_addc_u32 s5, s5, 0
	s_add_u32 s22, s22, 0x100
	s_addc_u32 s23, s23, 0
	s_cmp_gt_u32 s24, 29
	s_cbranch_scc0 .LBB0_512
	s_and_b64 vcc, exec, s[78:79]
	s_cbranch_vccz .LBB0_515
	s_barrier

; #define PG8_STAGE(bufoff, gbase, voff) do { _Pragma("unroll") for (int _i = 0; _i < 2; ++_i) \
;         __builtin_amdgcn_global_load_lds((const unsigned*)((const char*)(gbase) + (voff)[_i]), (LAS unsigned*)(lds + (bufoff) + ldsw + _i * 8192), 16, 0, 0); } while (0)
; #define PG8_LDA(dst, b, h) do { _Pragma("unroll") for (int m = 0; m < 4; ++m) _Pragma("unroll") for (int k = 0; k < 2; ++k) dst[m][k] = *(const LAS bf16x8*)(lds + PG8_SA(b, h) + aoff + m * 2048 + k * 1024); } while (0)
; #define PG8_LDB(dst, b, h) do { _Pragma("unroll") for (int n = 0; n < 2; ++n) _Pragma("unroll") for (int k = 0; k < 2; ++k) dst[n][k] = *(const LAS bf16x8*)(lds + PG8_SB(b, h) + boff + n * 2048 + k * 1024); } while (0)
; #define PG8_WAIT_V(n) asm volatile("s_waitcnt vmcnt(" #n ")" ::: "memory")
; #define PG8_WAIT_L(n) asm volatile("s_waitcnt lgkmcnt(" #n ")" ::: "memory")
; #define PG8_BAR __builtin_amdgcn_s_barrier()
; #define PG8_SCHED __builtin_amdgcn_sched_barrier(0)
; template <class Epi, class Sched, bool ALIGN_EPI, bool LAST_FUSED = false, bool PERM = false, bool CARRY = false>
; __device__ __forceinline__ void gemm_phase(LAS unsigned char* lds, const int tid, const int K, const int lda, const int ldb, const Sched& S, const Epi& E) {
;     ...
;         const bool has_next = S.next(KD_IDX(ui + 1), nxt);
;         const char* nA = has_next ? nxt.a : cA; const char* nB = has_next ? nxt.b : cB; const int nt = cur.nt;
; #pragma unroll 1
;         for (int t = 0; t < nt; t += 2) {
;             const bool last = (t == nt - 2);
;             const char* a1 = cA + (size_t)(t + 1) * kstep;
;             const char* a2 = last ? nA : cA + (size_t)(t + 2) * kstep; const char* b2 = last ? nB : cB + (size_t)(t + 2) * kstep;
;             const char* a3 = a2 + kstep; const char* b3 = b2 + kstep;
;             PG8_LDB(B0, 0, 0); PG8_LDB(B1, 0, 1); PG8_SCHED; PG8_LDA(At, 0, 0); PG8_STAGE(PG8_SA(1, 1), a1 + hstepA, voffA);
;             PG8_WAIT_V(8); PG8_WAIT_L(0); PG8_BAR; PG8_MMA(0, 0, At, B0); PG8_MMA(0, 1, At, B1); PG8_BAR; PG8_SCHED;
;             PG8_LDA(At, 0, 1); PG8_STAGE(PG8_SB(0, 0), b2, voffB); PG8_STAGE(PG8_SB(0, 1), b2 + hstepB, voffB); PG8_STAGE(PG8_SA(0, 0), a2, voffA);
;             PG8_WAIT_V(8); PG8_WAIT_L(0); PG8_BAR; PG8_MMA(1, 0, At, B0); PG8_MMA(1, 1, At, B1); PG8_BAR; PG8_SCHED;
.LBB0_601:
	s_add_u32 s23, s30, s15
	s_addc_u32 s27, s31, 0
	s_add_u32 s35, s23, 0x100
	s_addc_u32 s42, s27, 0
	s_and_b64 s[28:29], s[40:41], exec
	s_cselect_b32 s47, s17, s42
	s_cselect_b32 s46, s16, s35
	s_add_u32 s15, s36, s15
	s_addc_u32 s28, s37, 0
	s_add_u32 s15, s15, 0x100
	s_addc_u32 s35, s28, 0
	s_add_i32 s75, 0, 0x10000
	s_and_b64 s[28:29], s[40:41], exec
	s_cselect_b32 s49, s19, s35
	s_cselect_b32 s48, s18, s15
	s_add_i32 s41, 0, 0x14000
	s_add_u32 s52, s23, 0x80080
	s_addc_u32 s53, s27, 0
	s_add_i32 s45, s75, s59
	s_add_i32 m0, s60, 0xc000
	s_add_i32 s77, s60, 0xe000
	s_add_i32 s29, s45, 0x2000
	s_add_u32 s50, s48, 0x80000
	v_add_u32_e32 v154, s75, v144
	v_add_u32_e32 v170, s41, v144
	s_addc_u32 s51, s49, 0
	s_add_i32 s44, s41, s59
	ds_read_b128 v[136:139], v154
	ds_read_b128 v[146:149], v154 offset:1024
	ds_read_b128 v[150:153], v154 offset:2048
	ds_read_b128 v[154:157], v154 offset:3072
	ds_read_b128 v[158:161], v170
	ds_read_b128 v[162:165], v170 offset:1024
	ds_read_b128 v[166:169], v170 offset:2048
	ds_read_b128 v[170:173], v170 offset:3072
	s_add_i32 s35, s44, 0x2000
	s_add_i32 s28, 0, 0x18000
	s_add_i32 s27, 0, 0x1c000
	s_add_u32 s42, s46, 0x80000
	s_addc_u32 s43, s47, 0
	s_add_i32 s23, s28, s59
	s_add_i32 s15, s23, 0x2000
	s_add_u32 s40, s48, 0x80080
	s_addc_u32 s41, s49, 0
	s_add_i32 s76, s27, s59
	s_add_i32 s75, s76, 0x2000
	v_lshl_add_u64 v[206:207], s[52:53], 0, v[134:135]
	ds_read_b128 v[174:177], v145
	ds_read_b128 v[178:181], v145 offset:1024
	ds_read_b128 v[182:185], v145 offset:2048
	ds_read_b128 v[186:189], v145 offset:3072
	ds_read_b128 v[190:193], v145 offset:4096
	ds_read_b128 v[194:197], v145 offset:5120
	ds_read_b128 v[198:201], v145 offset:6144
	ds_read_b128 v[202:205], v145 offset:7168
	global_load_lds_dwordx4 v[206:207], off
	v_lshl_add_u64 v[206:207], s[52:53], 0, v[132:133]
	s_mov_b32 m0, s77
	s_nop 0
	global_load_lds_dwordx4 v[206:207], off
	s_waitcnt vmcnt(8)
	s_waitcnt lgkmcnt(0)
	s_barrier
	s_setprio 1
	v_mfma_f32_16x16x32_bf16 v[126:129], v[136:139], v[174:177], v[126:129]
	v_mfma_f32_16x16x32_bf16 v[122:125], v[150:153], v[174:177], v[122:125]
	v_mfma_f32_16x16x32_bf16 v[110:113], v[136:139], v[182:185], v[110:113]
	v_mfma_f32_16x16x32_bf16 v[106:109], v[150:153], v[182:185], v[106:109]
	v_mfma_f32_16x16x32_bf16 v[94:97], v[136:139], v[190:193], v[94:97]
	v_mfma_f32_16x16x32_bf16 v[90:93], v[150:153], v[190:193], v[90:93]
	v_mfma_f32_16x16x32_bf16 v[78:81], v[136:139], v[198:201], v[78:81]
	v_mfma_f32_16x16x32_bf16 v[74:77], v[150:153], v[198:201], v[74:77]
	v_mfma_f32_16x16x32_bf16 v[126:129], v[146:149], v[178:181], v[126:129]
	v_mfma_f32_16x16x32_bf16 v[122:125], v[154:157], v[178:181], v[122:125]
	v_mfma_f32_16x16x32_bf16 v[110:113], v[146:149], v[186:189], v[110:113]
	v_mfma_f32_16x16x32_bf16 v[106:109], v[154:157], v[186:189], v[106:109]
	v_mfma_f32_16x16x32_bf16 v[94:97], v[146:149], v[194:197], v[94:97]
	v_mfma_f32_16x16x32_bf16 v[90:93], v[154:157], v[194:197], v[90:93]
	v_mfma_f32_16x16x32_bf16 v[78:81], v[146:149], v[202:205], v[78:81]
	v_mfma_f32_16x16x32_bf16 v[74:77], v[154:157], v[202:205], v[74:77]
	v_mfma_f32_16x16x32_bf16 v[118:121], v[158:161], v[174:177], v[118:121]
	v_mfma_f32_16x16x32_bf16 v[114:117], v[166:169], v[174:177], v[114:117]
	v_mfma_f32_16x16x32_bf16 v[102:105], v[158:161], v[182:185], v[102:105]
	v_mfma_f32_16x16x32_bf16 v[98:101], v[166:169], v[182:185], v[98:101]
	v_mfma_f32_16x16x32_bf16 v[86:89], v[158:161], v[190:193], v[86:89]
	v_mfma_f32_16x16x32_bf16 v[82:85], v[166:169], v[190:193], v[82:85]
	v_mfma_f32_16x16x32_bf16 v[70:73], v[158:161], v[198:201], v[70:73]
	v_mfma_f32_16x16x32_bf16 v[66:69], v[166:169], v[198:201], v[66:69]
	v_mfma_f32_16x16x32_bf16 v[118:121], v[162:165], v[178:181], v[118:121]
	v_mfma_f32_16x16x32_bf16 v[114:117], v[170:173], v[178:181], v[114:117]
	v_mfma_f32_16x16x32_bf16 v[102:105], v[162:165], v[186:189], v[102:105]
	v_mfma_f32_16x16x32_bf16 v[98:101], v[170:173], v[186:189], v[98:101]
	v_mfma_f32_16x16x32_bf16 v[86:89], v[162:165], v[194:197], v[86:89]
	v_mfma_f32_16x16x32_bf16 v[82:85], v[170:173], v[194:197], v[82:85]
	v_mfma_f32_16x16x32_bf16 v[70:73], v[162:165], v[202:205], v[70:73]
	v_mfma_f32_16x16x32_bf16 v[66:69], v[170:173], v[202:205], v[66:69]
	s_barrier
	s_setprio 0
	s_mov_b32 m0, s45
	v_lshl_add_u64 v[206:207], s[48:49], 0, v[0:1]
	ds_read_b128 v[174:177], v145 offset:16384
	ds_read_b128 v[178:181], v145 offset:17408
	ds_read_b128 v[182:185], v145 offset:18432
	ds_read_b128 v[186:189], v145 offset:19456
	ds_read_b128 v[190:193], v145 offset:20480
	ds_read_b128 v[194:197], v145 offset:21504
	ds_read_b128 v[198:201], v145 offset:22528
	ds_read_b128 v[202:205], v145 offset:23552
	global_load_lds_dwordx4 v[206:207], off
	v_lshl_add_u64 v[208:209], s[48:49], 0, v[130:131]
	s_mov_b32 m0, s29
	v_lshl_add_u64 v[210:211], s[50:51], 0, v[0:1]
	global_load_lds_dwordx4 v[208:209], off
	s_mov_b32 m0, s44
	v_lshl_add_u64 v[212:213], s[46:47], 0, v[132:133]
	global_load_lds_dwordx4 v[210:211], off
	v_lshl_add_u64 v[210:211], s[50:51], 0, v[130:131]
	s_mov_b32 m0, s35
	s_nop 0
	global_load_lds_dwordx4 v[210:211], off
	v_lshl_add_u64 v[210:211], s[46:47], 0, v[134:135]
	s_mov_b32 m0, s60
	s_nop 0
	global_load_lds_dwordx4 v[210:211], off
	s_mov_b32 m0, s61
	s_nop 0
	global_load_lds_dwordx4 v[212:213], off
	s_waitcnt vmcnt(8)
	s_waitcnt lgkmcnt(0)
	s_barrier
; #define PG8_STAGE(bufoff, gbase, voff) do { _Pragma("unroll") for (int _i = 0; _i < 2; ++_i) \
;         __builtin_amdgcn_global_load_lds((const unsigned*)((const char*)(gbase) + (voff)[_i]), (LAS unsigned*)(lds + (bufoff) + ldsw + _i * 8192), 16, 0, 0); } while (0)
; #define PG8_LDA(dst, b, h) do { _Pragma("unroll") for (int m = 0; m < 4; ++m) _Pragma("unroll") for (int k = 0; k < 2; ++k) dst[m][k] = *(const LAS bf16x8*)(lds + PG8_SA(b, h) + aoff + m * 2048 + k * 1024); } while (0)
; #define PG8_LDB(dst, b, h) do { _Pragma("unroll") for (int n = 0; n < 2; ++n) _Pragma("unroll") for (int k = 0; k < 2; ++k) dst[n][k] = *(const LAS bf16x8*)(lds + PG8_SB(b, h) + boff + n * 2048 + k * 1024); } while (0)
; #define PG8_MMA(ai, bj, At, Bt) do { __builtin_amdgcn_s_setprio(1); _Pragma("unroll") for (int m = 0; m < 4; ++m) _Pragma("unroll") for (int n = 0; n < 2; ++n) _Pragma("unroll") for (int k = 0; k < 2; ++k) \
;         acc[ai][bj][m][n] = __builtin_amdgcn_mfma_f32_16x16x32_bf16(Bt[n][k], At[m][k], acc[ai][bj][m][n], 0, 0, 0); __builtin_amdgcn_s_setprio(0); } while (0)
; #define PG8_WAIT_V(n) asm volatile("s_waitcnt vmcnt(" #n ")" ::: "memory")
; #define PG8_WAIT_L(n) asm volatile("s_waitcnt lgkmcnt(" #n ")" ::: "memory")
; #define PG8_BAR __builtin_amdgcn_s_barrier()
; #define PG8_SCHED __builtin_amdgcn_sched_barrier(0)
; template <class Epi, class Sched, bool ALIGN_EPI, bool LAST_FUSED = false, bool PERM = false, bool CARRY = false>
; __device__ __forceinline__ void gemm_phase(LAS unsigned char* lds, const int tid, const int K, const int lda, const int ldb, const Sched& S, const Epi& E) {
;     ...
;             PG8_WAIT_V(8); PG8_WAIT_L(0); PG8_BAR; PG8_MMA(1, 0, At, B0); PG8_MMA(1, 1, At, B1); PG8_BAR; PG8_SCHED;
;             PG8_LDB(B0, 1, 0); PG8_LDB(B1, 1, 1); PG8_SCHED; PG8_LDA(At, 1, 0); PG8_STAGE(PG8_SA(0, 1), a2 + hstepA, voffA);
;             PG8_WAIT_V(8); PG8_WAIT_L(0); PG8_BAR; PG8_MMA(0, 0, At, B0); PG8_MMA(0, 1, At, B1); PG8_BAR; PG8_SCHED;
	s_setprio 1
	v_mfma_f32_16x16x32_bf16 v[62:65], v[136:139], v[174:177], v[62:65]
	v_mfma_f32_16x16x32_bf16 v[58:61], v[150:153], v[174:177], v[58:61]
	v_mfma_f32_16x16x32_bf16 v[46:49], v[136:139], v[182:185], v[46:49]
	v_mfma_f32_16x16x32_bf16 v[42:45], v[150:153], v[182:185], v[42:45]
	v_mfma_f32_16x16x32_bf16 v[30:33], v[136:139], v[190:193], v[30:33]
	v_mfma_f32_16x16x32_bf16 v[26:29], v[150:153], v[190:193], v[26:29]
	v_mfma_f32_16x16x32_bf16 v[14:17], v[136:139], v[198:201], v[14:17]
	v_mfma_f32_16x16x32_bf16 v[10:13], v[150:153], v[198:201], v[10:13]
	v_mfma_f32_16x16x32_bf16 v[62:65], v[146:149], v[178:181], v[62:65]
	v_mfma_f32_16x16x32_bf16 v[58:61], v[154:157], v[178:181], v[58:61]
	v_mfma_f32_16x16x32_bf16 v[46:49], v[146:149], v[186:189], v[46:49]
	v_mfma_f32_16x16x32_bf16 v[42:45], v[154:157], v[186:189], v[42:45]
	v_mfma_f32_16x16x32_bf16 v[30:33], v[146:149], v[194:197], v[30:33]
	v_mfma_f32_16x16x32_bf16 v[26:29], v[154:157], v[194:197], v[26:29]
	v_mfma_f32_16x16x32_bf16 v[14:17], v[146:149], v[202:205], v[14:17]
	v_mfma_f32_16x16x32_bf16 v[10:13], v[154:157], v[202:205], v[10:13]
	v_mfma_f32_16x16x32_bf16 v[54:57], v[158:161], v[174:177], v[54:57]
	v_mfma_f32_16x16x32_bf16 v[50:53], v[166:169], v[174:177], v[50:53]
	v_mfma_f32_16x16x32_bf16 v[38:41], v[158:161], v[182:185], v[38:41]
	v_mfma_f32_16x16x32_bf16 v[34:37], v[166:169], v[182:185], v[34:37]
	v_mfma_f32_16x16x32_bf16 v[22:25], v[158:161], v[190:193], v[22:25]
	v_mfma_f32_16x16x32_bf16 v[18:21], v[166:169], v[190:193], v[18:21]
	v_mfma_f32_16x16x32_bf16 v[6:9], v[158:161], v[198:201], v[6:9]
	v_mfma_f32_16x16x32_bf16 v[2:5], v[166:169], v[198:201], v[2:5]
	v_mfma_f32_16x16x32_bf16 v[54:57], v[162:165], v[178:181], v[54:57]
	v_mfma_f32_16x16x32_bf16 v[50:53], v[170:173], v[178:181], v[50:53]
	v_mfma_f32_16x16x32_bf16 v[38:41], v[162:165], v[186:189], v[38:41]
	v_mfma_f32_16x16x32_bf16 v[34:37], v[170:173], v[186:189], v[34:37]
	v_mfma_f32_16x16x32_bf16 v[22:25], v[162:165], v[194:197], v[22:25]
	v_mfma_f32_16x16x32_bf16 v[18:21], v[170:173], v[194:197], v[18:21]
	v_mfma_f32_16x16x32_bf16 v[6:9], v[162:165], v[202:205], v[6:9]
	v_mfma_f32_16x16x32_bf16 v[2:5], v[170:173], v[202:205], v[2:5]
	s_barrier
	s_setprio 0
	v_add_u32_e32 v154, s28, v144
	v_add_u32_e32 v170, s27, v144
	ds_read_b128 v[136:139], v154
	ds_read_b128 v[146:149], v154 offset:1024
	ds_read_b128 v[150:153], v154 offset:2048
	ds_read_b128 v[154:157], v154 offset:3072
	ds_read_b128 v[158:161], v170
	ds_read_b128 v[162:165], v170 offset:1024
	ds_read_b128 v[166:169], v170 offset:2048
	ds_read_b128 v[170:173], v170 offset:3072
	s_mov_b32 m0, s62
	v_lshl_add_u64 v[214:215], s[42:43], 0, v[134:135]
	ds_read_b128 v[174:177], v145 offset:32768
	ds_read_b128 v[178:181], v145 offset:33792
	ds_read_b128 v[182:185], v145 offset:34816
	ds_read_b128 v[186:189], v145 offset:35840
	ds_read_b128 v[190:193], v145 offset:36864
	ds_read_b128 v[194:197], v145 offset:37888
	ds_read_b128 v[198:201], v145 offset:38912
	ds_read_b128 v[202:205], v145 offset:39936
	global_load_lds_dwordx4 v[214:215], off
	v_lshl_add_u64 v[214:215], s[42:43], 0, v[132:133]
	s_mov_b32 m0, s63
	s_nop 0
	global_load_lds_dwordx4 v[214:215], off
	s_waitcnt vmcnt(8)
	s_waitcnt lgkmcnt(0)
	s_barrier
	s_setprio 1
	v_mfma_f32_16x16x32_bf16 v[126:129], v[136:139], v[174:177], v[126:129]
	v_mfma_f32_16x16x32_bf16 v[122:125], v[150:153], v[174:177], v[122:125]
	v_mfma_f32_16x16x32_bf16 v[110:113], v[136:139], v[182:185], v[110:113]
	v_mfma_f32_16x16x32_bf16 v[106:109], v[150:153], v[182:185], v[106:109]
	v_mfma_f32_16x16x32_bf16 v[94:97], v[136:139], v[190:193], v[94:97]
	v_mfma_f32_16x16x32_bf16 v[90:93], v[150:153], v[190:193], v[90:93]
	v_mfma_f32_16x16x32_bf16 v[78:81], v[136:139], v[198:201], v[78:81]
	v_mfma_f32_16x16x32_bf16 v[74:77], v[150:153], v[198:201], v[74:77]
	v_mfma_f32_16x16x32_bf16 v[126:129], v[146:149], v[178:181], v[126:129]
	v_mfma_f32_16x16x32_bf16 v[122:125], v[154:157], v[178:181], v[122:125]
	v_mfma_f32_16x16x32_bf16 v[110:113], v[146:149], v[186:189], v[110:113]
	v_mfma_f32_16x16x32_bf16 v[106:109], v[154:157], v[186:189], v[106:109]
	v_mfma_f32_16x16x32_bf16 v[94:97], v[146:149], v[194:197], v[94:97]
	v_mfma_f32_16x16x32_bf16 v[90:93], v[154:157], v[194:197], v[90:93]
	v_mfma_f32_16x16x32_bf16 v[78:81], v[146:149], v[202:205], v[78:81]
	v_mfma_f32_16x16x32_bf16 v[74:77], v[154:157], v[202:205], v[74:77]
	v_mfma_f32_16x16x32_bf16 v[118:121], v[158:161], v[174:177], v[118:121]
	v_mfma_f32_16x16x32_bf16 v[114:117], v[166:169], v[174:177], v[114:117]
	v_mfma_f32_16x16x32_bf16 v[102:105], v[158:161], v[182:185], v[102:105]
	v_mfma_f32_16x16x32_bf16 v[98:101], v[166:169], v[182:185], v[98:101]
	v_mfma_f32_16x16x32_bf16 v[86:89], v[158:161], v[190:193], v[86:89]
	v_mfma_f32_16x16x32_bf16 v[82:85], v[166:169], v[190:193], v[82:85]
	v_mfma_f32_16x16x32_bf16 v[70:73], v[158:161], v[198:201], v[70:73]
	v_mfma_f32_16x16x32_bf16 v[66:69], v[166:169], v[198:201], v[66:69]
	v_mfma_f32_16x16x32_bf16 v[118:121], v[162:165], v[178:181], v[118:121]
	v_mfma_f32_16x16x32_bf16 v[114:117], v[170:173], v[178:181], v[114:117]
	v_mfma_f32_16x16x32_bf16 v[102:105], v[162:165], v[186:189], v[102:105]
	v_mfma_f32_16x16x32_bf16 v[98:101], v[170:173], v[186:189], v[98:101]
	v_mfma_f32_16x16x32_bf16 v[86:89], v[162:165], v[194:197], v[86:89]
	v_mfma_f32_16x16x32_bf16 v[82:85], v[170:173], v[194:197], v[82:85]
	v_mfma_f32_16x16x32_bf16 v[70:73], v[162:165], v[202:205], v[70:73]
	v_mfma_f32_16x16x32_bf16 v[66:69], v[170:173], v[202:205], v[66:69]
	s_barrier
; #define PG8_STAGE(bufoff, gbase, voff) do { _Pragma("unroll") for (int _i = 0; _i < 2; ++_i) \
;         __builtin_amdgcn_global_load_lds((const unsigned*)((const char*)(gbase) + (voff)[_i]), (LAS unsigned*)(lds + (bufoff) + ldsw + _i * 8192), 16, 0, 0); } while (0)
; #define PG8_LDA(dst, b, h) do { _Pragma("unroll") for (int m = 0; m < 4; ++m) _Pragma("unroll") for (int k = 0; k < 2; ++k) dst[m][k] = *(const LAS bf16x8*)(lds + PG8_SA(b, h) + aoff + m * 2048 + k * 1024); } while (0)
; #define PG8_MMA(ai, bj, At, Bt) do { __builtin_amdgcn_s_setprio(1); _Pragma("unroll") for (int m = 0; m < 4; ++m) _Pragma("unroll") for (int n = 0; n < 2; ++n) _Pragma("unroll") for (int k = 0; k < 2; ++k) \
;         acc[ai][bj][m][n] = __builtin_amdgcn_mfma_f32_16x16x32_bf16(Bt[n][k], At[m][k], acc[ai][bj][m][n], 0, 0, 0); __builtin_amdgcn_s_setprio(0); } while (0)
; #define PG8_WAIT_V(n) asm volatile("s_waitcnt vmcnt(" #n ")" ::: "memory")
; #define PG8_WAIT_L(n) asm volatile("s_waitcnt lgkmcnt(" #n ")" ::: "memory")
; #define PG8_BAR __builtin_amdgcn_s_barrier()
; #define PG8_SCHED __builtin_amdgcn_sched_barrier(0)
; template <class Epi, class Sched, bool ALIGN_EPI, bool LAST_FUSED = false, bool PERM = false, bool CARRY = false>
; __device__ __forceinline__ void gemm_phase(LAS unsigned char* lds, const int tid, const int K, const int lda, const int ldb, const Sched& S, const Epi& E) {
;     ...
;             PG8_LDA(At, 1, 1); PG8_STAGE(PG8_SB(1, 0), b3, voffB); PG8_STAGE(PG8_SB(1, 1), b3 + hstepB, voffB); PG8_STAGE(PG8_SA(1, 0), a3, voffA);
;             PG8_WAIT_V(8); PG8_WAIT_L(0); PG8_BAR; PG8_MMA(1, 0, At, B0); PG8_MMA(1, 1, At, B1); PG8_BAR; PG8_SCHED;
;         }
;         if constexpr (ALIGN_EPI) { if (wr == 0) PG8_BAR; }
	s_setprio 0
	s_mov_b32 m0, s23
	v_lshl_add_u64 v[206:207], v[206:207], 0, s[68:69]
	ds_read_b128 v[174:177], v145 offset:49152
	ds_read_b128 v[178:181], v145 offset:50176
	ds_read_b128 v[182:185], v145 offset:51200
	ds_read_b128 v[186:189], v145 offset:52224
	ds_read_b128 v[190:193], v145 offset:53248
	ds_read_b128 v[194:197], v145 offset:54272
	ds_read_b128 v[198:201], v145 offset:55296
	ds_read_b128 v[202:205], v145 offset:56320
	global_load_lds_dwordx4 v[206:207], off
	v_lshl_add_u64 v[206:207], v[208:209], 0, s[68:69]
	s_mov_b32 m0, s15
	s_nop 0
	global_load_lds_dwordx4 v[206:207], off
	v_lshl_add_u64 v[206:207], s[40:41], 0, v[0:1]
	s_mov_b32 m0, s76
	s_nop 0
	global_load_lds_dwordx4 v[206:207], off
	v_lshl_add_u64 v[206:207], s[40:41], 0, v[130:131]
	s_mov_b32 m0, s75
	s_nop 0
	global_load_lds_dwordx4 v[206:207], off
	v_lshl_add_u64 v[206:207], v[210:211], 0, s[68:69]
	s_mov_b32 m0, s66
	s_nop 0
	global_load_lds_dwordx4 v[206:207], off
	v_lshl_add_u64 v[206:207], v[212:213], 0, s[68:69]
	s_mov_b32 m0, s67
	s_nop 0
	global_load_lds_dwordx4 v[206:207], off
	s_waitcnt vmcnt(8)
	s_waitcnt lgkmcnt(0)
	s_barrier
	s_setprio 1
	v_mfma_f32_16x16x32_bf16 v[62:65], v[136:139], v[174:177], v[62:65]
	v_mfma_f32_16x16x32_bf16 v[58:61], v[150:153], v[174:177], v[58:61]
	v_mfma_f32_16x16x32_bf16 v[46:49], v[136:139], v[182:185], v[46:49]
	v_mfma_f32_16x16x32_bf16 v[42:45], v[150:153], v[182:185], v[42:45]
	v_mfma_f32_16x16x32_bf16 v[30:33], v[136:139], v[190:193], v[30:33]
	v_mfma_f32_16x16x32_bf16 v[26:29], v[150:153], v[190:193], v[26:29]
	v_mfma_f32_16x16x32_bf16 v[14:17], v[136:139], v[198:201], v[14:17]
	v_mfma_f32_16x16x32_bf16 v[10:13], v[150:153], v[198:201], v[10:13]
	v_mfma_f32_16x16x32_bf16 v[62:65], v[146:149], v[178:181], v[62:65]
	v_mfma_f32_16x16x32_bf16 v[58:61], v[154:157], v[178:181], v[58:61]
	v_mfma_f32_16x16x32_bf16 v[46:49], v[146:149], v[186:189], v[46:49]
	v_mfma_f32_16x16x32_bf16 v[42:45], v[154:157], v[186:189], v[42:45]
	v_mfma_f32_16x16x32_bf16 v[30:33], v[146:149], v[194:197], v[30:33]
	v_mfma_f32_16x16x32_bf16 v[26:29], v[154:157], v[194:197], v[26:29]
	v_mfma_f32_16x16x32_bf16 v[14:17], v[146:149], v[202:205], v[14:17]
	v_mfma_f32_16x16x32_bf16 v[10:13], v[154:157], v[202:205], v[10:13]
	v_mfma_f32_16x16x32_bf16 v[54:57], v[158:161], v[174:177], v[54:57]
	v_mfma_f32_16x16x32_bf16 v[50:53], v[166:169], v[174:177], v[50:53]
	v_mfma_f32_16x16x32_bf16 v[38:41], v[158:161], v[182:185], v[38:41]
	v_mfma_f32_16x16x32_bf16 v[34:37], v[166:169], v[182:185], v[34:37]
	v_mfma_f32_16x16x32_bf16 v[22:25], v[158:161], v[190:193], v[22:25]
	v_mfma_f32_16x16x32_bf16 v[18:21], v[166:169], v[190:193], v[18:21]
	v_mfma_f32_16x16x32_bf16 v[6:9], v[158:161], v[198:201], v[6:9]
	v_mfma_f32_16x16x32_bf16 v[2:5], v[166:169], v[198:201], v[2:5]
	v_mfma_f32_16x16x32_bf16 v[54:57], v[162:165], v[178:181], v[54:57]
	v_mfma_f32_16x16x32_bf16 v[50:53], v[170:173], v[178:181], v[50:53]
	v_mfma_f32_16x16x32_bf16 v[38:41], v[162:165], v[186:189], v[38:41]
	v_mfma_f32_16x16x32_bf16 v[34:37], v[170:173], v[186:189], v[34:37]
	v_mfma_f32_16x16x32_bf16 v[22:25], v[162:165], v[194:197], v[22:25]
	v_mfma_f32_16x16x32_bf16 v[18:21], v[170:173], v[194:197], v[18:21]
	v_mfma_f32_16x16x32_bf16 v[6:9], v[162:165], v[202:205], v[6:9]
	v_mfma_f32_16x16x32_bf16 v[2:5], v[170:173], v[202:205], v[2:5]
	s_barrier
	s_setprio 0
	s_movk_i32 s15, 0x100
	s_andn2_b64 vcc, exec, s[38:39]
	s_mov_b64 s[40:41], -1
	s_mov_b64 s[38:39], 0
	s_cbranch_vccz .LBB0_601
	s_and_b64 vcc, exec, s[12:13]
	s_cbranch_vccz .LBB0_604
	s_barrier

; #define PG8_STAGE(bufoff, gbase, voff) do { _Pragma("unroll") for (int _i = 0; _i < 2; ++_i) \
;         __builtin_amdgcn_global_load_lds((const unsigned*)((const char*)(gbase) + (voff)[_i]), (LAS unsigned*)(lds + (bufoff) + ldsw + _i * 8192), 16, 0, 0); } while (0)
; #define PG8_LDA(dst, b, h) do { _Pragma("unroll") for (int m = 0; m < 4; ++m) _Pragma("unroll") for (int k = 0; k < 2; ++k) dst[m][k] = *(const LAS bf16x8*)(lds + PG8_SA(b, h) + aoff + m * 2048 + k * 1024); } while (0)
; #define PG8_LDB(dst, b, h) do { _Pragma("unroll") for (int n = 0; n < 2; ++n) _Pragma("unroll") for (int k = 0; k < 2; ++k) dst[n][k] = *(const LAS bf16x8*)(lds + PG8_SB(b, h) + boff + n * 2048 + k * 1024); } while (0)
; #define PG8_WAIT_V(n) asm volatile("s_waitcnt vmcnt(" #n ")" ::: "memory")
; #define PG8_WAIT_L(n) asm volatile("s_waitcnt lgkmcnt(" #n ")" ::: "memory")
; #define PG8_BAR __builtin_amdgcn_s_barrier()
; #define PG8_SCHED __builtin_amdgcn_sched_barrier(0)
; template <class Epi, class Sched, bool ALIGN_EPI, bool LAST_FUSED = false, bool PERM = false, bool CARRY = false>
; __device__ __forceinline__ void gemm_phase(LAS unsigned char* lds, const int tid, const int K, const int lda, const int ldb, const Sched& S, const Epi& E) {
;     ...
;         const bool has_next = S.next(KD_IDX(ui + 1), nxt);
;         const char* nA = has_next ? nxt.a : cA; const char* nB = has_next ? nxt.b : cB; const int nt = cur.nt;
; #pragma unroll 1
;         for (int t = 0; t < nt; t += 2) {
;             const bool last = (t == nt - 2);
;             const char* a1 = cA + (size_t)(t + 1) * kstep;
;             const char* a2 = last ? nA : cA + (size_t)(t + 2) * kstep; const char* b2 = last ? nB : cB + (size_t)(t + 2) * kstep;
;             const char* a3 = a2 + kstep; const char* b3 = b2 + kstep;
;             PG8_LDB(B0, 0, 0); PG8_LDB(B1, 0, 1); PG8_SCHED; PG8_LDA(At, 0, 0); PG8_STAGE(PG8_SA(1, 1), a1 + hstepA, voffA);
;             PG8_WAIT_V(8); PG8_WAIT_L(0); PG8_BAR; PG8_MMA(0, 0, At, B0); PG8_MMA(0, 1, At, B1); PG8_BAR; PG8_SCHED;
;             PG8_LDA(At, 0, 1); PG8_STAGE(PG8_SB(0, 0), b2, voffB); PG8_STAGE(PG8_SB(0, 1), b2 + hstepB, voffB); PG8_STAGE(PG8_SA(0, 0), a2, voffA);
;             PG8_WAIT_V(8); PG8_WAIT_L(0); PG8_BAR; PG8_MMA(1, 0, At, B0); PG8_MMA(1, 1, At, B1); PG8_BAR; PG8_SCHED;
.LBB0_622:
	s_add_u32 s48, s30, s24
	s_addc_u32 s49, s31, 0
	s_add_u32 s42, s48, 0x100
	s_addc_u32 s43, s49, 0
	s_and_b64 s[40:41], s[38:39], exec
	s_cselect_b32 s43, s15, s43
	s_cselect_b32 s42, s14, s42
	s_add_u32 s24, s26, s24
	s_addc_u32 s40, s27, 0
	s_add_u32 s24, s24, 0x100
	s_addc_u32 s40, s40, 0
	s_add_i32 s62, 0, 0x10000
	s_and_b64 s[38:39], s[38:39], exec
	s_cselect_b32 s47, s17, s40
	s_cselect_b32 s46, s16, s24
	s_add_i32 s39, 0, 0x14000
	s_add_u32 s64, s48, 0x30080
	s_addc_u32 s65, s49, 0
	s_add_i32 s67, s62, s29
	s_add_i32 m0, s45, 0xc000
	s_add_i32 s66, s45, 0xe000
	s_add_i32 s70, s67, 0x2000
	s_add_u32 s48, s46, 0x10000
	v_add_u32_e32 v152, s62, v140
	v_add_u32_e32 v168, s39, v140
	s_addc_u32 s49, s47, 0
	s_add_i32 s71, s39, s29
	ds_read_b128 v[136:139], v152
	ds_read_b128 v[144:147], v152 offset:1024
	ds_read_b128 v[148:151], v152 offset:2048
	ds_read_b128 v[152:155], v152 offset:3072
	ds_read_b128 v[156:159], v168
	ds_read_b128 v[160:163], v168 offset:1024
	ds_read_b128 v[164:167], v168 offset:2048
	ds_read_b128 v[168:171], v168 offset:3072
	s_add_i32 s74, s71, 0x2000
	s_add_i32 s75, 0, 0x18000
	s_add_i32 s76, 0, 0x1c000
	s_add_u32 s40, s42, 0x30000
	s_addc_u32 s41, s43, 0
	s_add_i32 s61, s75, s29
	s_add_i32 s24, s61, 0x2000
	s_add_u32 s38, s46, 0x10080
	s_addc_u32 s39, s47, 0
	s_add_i32 s63, s76, s29
	s_add_i32 s62, s63, 0x2000
	v_lshl_add_u64 v[204:205], s[64:65], 0, v[130:131]
	ds_read_b128 v[172:175], v143
	ds_read_b128 v[176:179], v143 offset:1024
	ds_read_b128 v[180:183], v143 offset:2048
	ds_read_b128 v[184:187], v143 offset:3072
	ds_read_b128 v[188:191], v143 offset:4096
	ds_read_b128 v[192:195], v143 offset:5120
	ds_read_b128 v[196:199], v143 offset:6144
	ds_read_b128 v[200:203], v143 offset:7168
	global_load_lds_dwordx4 v[204:205], off
	v_lshl_add_u64 v[204:205], s[64:65], 0, v[132:133]
	s_mov_b32 m0, s66
	s_nop 0
	global_load_lds_dwordx4 v[204:205], off
	s_waitcnt vmcnt(8)
	s_waitcnt lgkmcnt(0)
	s_barrier
	s_setprio 1
	v_mfma_f32_16x16x32_bf16 v[126:129], v[136:139], v[172:175], v[126:129]
	v_mfma_f32_16x16x32_bf16 v[122:125], v[148:151], v[172:175], v[122:125]
	v_mfma_f32_16x16x32_bf16 v[118:121], v[136:139], v[180:183], v[118:121]
	v_mfma_f32_16x16x32_bf16 v[114:117], v[148:151], v[180:183], v[114:117]
	v_mfma_f32_16x16x32_bf16 v[110:113], v[136:139], v[188:191], v[110:113]
	v_mfma_f32_16x16x32_bf16 v[106:109], v[148:151], v[188:191], v[106:109]
	v_mfma_f32_16x16x32_bf16 v[102:105], v[136:139], v[196:199], v[102:105]
	v_mfma_f32_16x16x32_bf16 v[98:101], v[148:151], v[196:199], v[98:101]
	v_mfma_f32_16x16x32_bf16 v[126:129], v[144:147], v[176:179], v[126:129]
	v_mfma_f32_16x16x32_bf16 v[122:125], v[152:155], v[176:179], v[122:125]
	v_mfma_f32_16x16x32_bf16 v[118:121], v[144:147], v[184:187], v[118:121]
	v_mfma_f32_16x16x32_bf16 v[114:117], v[152:155], v[184:187], v[114:117]
	v_mfma_f32_16x16x32_bf16 v[110:113], v[144:147], v[192:195], v[110:113]
	v_mfma_f32_16x16x32_bf16 v[106:109], v[152:155], v[192:195], v[106:109]
	v_mfma_f32_16x16x32_bf16 v[102:105], v[144:147], v[200:203], v[102:105]
	v_mfma_f32_16x16x32_bf16 v[98:101], v[152:155], v[200:203], v[98:101]
	v_mfma_f32_16x16x32_bf16 v[94:97], v[156:159], v[172:175], v[94:97]
	v_mfma_f32_16x16x32_bf16 v[90:93], v[164:167], v[172:175], v[90:93]
	v_mfma_f32_16x16x32_bf16 v[86:89], v[156:159], v[180:183], v[86:89]
	v_mfma_f32_16x16x32_bf16 v[82:85], v[164:167], v[180:183], v[82:85]
	v_mfma_f32_16x16x32_bf16 v[78:81], v[156:159], v[188:191], v[78:81]
	v_mfma_f32_16x16x32_bf16 v[74:77], v[164:167], v[188:191], v[74:77]
	v_mfma_f32_16x16x32_bf16 v[70:73], v[156:159], v[196:199], v[70:73]
	v_mfma_f32_16x16x32_bf16 v[66:69], v[164:167], v[196:199], v[66:69]
	v_mfma_f32_16x16x32_bf16 v[94:97], v[160:163], v[176:179], v[94:97]
	v_mfma_f32_16x16x32_bf16 v[90:93], v[168:171], v[176:179], v[90:93]
	v_mfma_f32_16x16x32_bf16 v[86:89], v[160:163], v[184:187], v[86:89]
	v_mfma_f32_16x16x32_bf16 v[82:85], v[168:171], v[184:187], v[82:85]
	v_mfma_f32_16x16x32_bf16 v[78:81], v[160:163], v[192:195], v[78:81]
	v_mfma_f32_16x16x32_bf16 v[74:77], v[168:171], v[192:195], v[74:77]
	v_mfma_f32_16x16x32_bf16 v[70:73], v[160:163], v[200:203], v[70:73]
	v_mfma_f32_16x16x32_bf16 v[66:69], v[168:171], v[200:203], v[66:69]
	s_barrier
	s_setprio 0
	s_mov_b32 m0, s67
	v_lshl_add_u64 v[204:205], s[46:47], 0, v[0:1]
	ds_read_b128 v[172:175], v143 offset:16384
	ds_read_b128 v[176:179], v143 offset:17408
	ds_read_b128 v[180:183], v143 offset:18432
	ds_read_b128 v[184:187], v143 offset:19456
	ds_read_b128 v[188:191], v143 offset:20480
	ds_read_b128 v[192:195], v143 offset:21504
	ds_read_b128 v[196:199], v143 offset:22528
	ds_read_b128 v[200:203], v143 offset:23552
	global_load_lds_dwordx4 v[204:205], off
	v_lshl_add_u64 v[206:207], s[46:47], 0, v[134:135]
	s_mov_b32 m0, s70
	v_lshl_add_u64 v[208:209], s[48:49], 0, v[0:1]
	global_load_lds_dwordx4 v[206:207], off
	s_mov_b32 m0, s71
	v_lshl_add_u64 v[210:211], s[42:43], 0, v[132:133]
	global_load_lds_dwordx4 v[208:209], off
	v_lshl_add_u64 v[208:209], s[48:49], 0, v[134:135]
	s_mov_b32 m0, s74
	s_nop 0
	global_load_lds_dwordx4 v[208:209], off
	v_lshl_add_u64 v[208:209], s[42:43], 0, v[130:131]
	s_mov_b32 m0, s45
	s_nop 0
	global_load_lds_dwordx4 v[208:209], off
	s_mov_b32 m0, s50
	s_nop 0
	global_load_lds_dwordx4 v[210:211], off
	s_waitcnt vmcnt(8)
	s_waitcnt lgkmcnt(0)
	s_barrier
; #define PG8_STAGE(bufoff, gbase, voff) do { _Pragma("unroll") for (int _i = 0; _i < 2; ++_i) \
;         __builtin_amdgcn_global_load_lds((const unsigned*)((const char*)(gbase) + (voff)[_i]), (LAS unsigned*)(lds + (bufoff) + ldsw + _i * 8192), 16, 0, 0); } while (0)
; #define PG8_LDA(dst, b, h) do { _Pragma("unroll") for (int m = 0; m < 4; ++m) _Pragma("unroll") for (int k = 0; k < 2; ++k) dst[m][k] = *(const LAS bf16x8*)(lds + PG8_SA(b, h) + aoff + m * 2048 + k * 1024); } while (0)
; #define PG8_LDB(dst, b, h) do { _Pragma("unroll") for (int n = 0; n < 2; ++n) _Pragma("unroll") for (int k = 0; k < 2; ++k) dst[n][k] = *(const LAS bf16x8*)(lds + PG8_SB(b, h) + boff + n * 2048 + k * 1024); } while (0)
; #define PG8_MMA(ai, bj, At, Bt) do { __builtin_amdgcn_s_setprio(1); _Pragma("unroll") for (int m = 0; m < 4; ++m) _Pragma("unroll") for (int n = 0; n < 2; ++n) _Pragma("unroll") for (int k = 0; k < 2; ++k) \
;         acc[ai][bj][m][n] = __builtin_amdgcn_mfma_f32_16x16x32_bf16(Bt[n][k], At[m][k], acc[ai][bj][m][n], 0, 0, 0); __builtin_amdgcn_s_setprio(0); } while (0)
; #define PG8_WAIT_V(n) asm volatile("s_waitcnt vmcnt(" #n ")" ::: "memory")
; #define PG8_WAIT_L(n) asm volatile("s_waitcnt lgkmcnt(" #n ")" ::: "memory")
; #define PG8_BAR __builtin_amdgcn_s_barrier()
; #define PG8_SCHED __builtin_amdgcn_sched_barrier(0)
; template <class Epi, class Sched, bool ALIGN_EPI, bool LAST_FUSED = false, bool PERM = false, bool CARRY = false>
; __device__ __forceinline__ void gemm_phase(LAS unsigned char* lds, const int tid, const int K, const int lda, const int ldb, const Sched& S, const Epi& E) {
;     ...
;             PG8_WAIT_V(8); PG8_WAIT_L(0); PG8_BAR; PG8_MMA(1, 0, At, B0); PG8_MMA(1, 1, At, B1); PG8_BAR; PG8_SCHED;
;             PG8_LDB(B0, 1, 0); PG8_LDB(B1, 1, 1); PG8_SCHED; PG8_LDA(At, 1, 0); PG8_STAGE(PG8_SA(0, 1), a2 + hstepA, voffA);
;             PG8_WAIT_V(8); PG8_WAIT_L(0); PG8_BAR; PG8_MMA(0, 0, At, B0); PG8_MMA(0, 1, At, B1); PG8_BAR; PG8_SCHED;
	s_setprio 1
	v_mfma_f32_16x16x32_bf16 v[62:65], v[136:139], v[172:175], v[62:65]
	v_mfma_f32_16x16x32_bf16 v[58:61], v[148:151], v[172:175], v[58:61]
	v_mfma_f32_16x16x32_bf16 v[54:57], v[136:139], v[180:183], v[54:57]
	v_mfma_f32_16x16x32_bf16 v[50:53], v[148:151], v[180:183], v[50:53]
	v_mfma_f32_16x16x32_bf16 v[46:49], v[136:139], v[188:191], v[46:49]
	v_mfma_f32_16x16x32_bf16 v[42:45], v[148:151], v[188:191], v[42:45]
	v_mfma_f32_16x16x32_bf16 v[38:41], v[136:139], v[196:199], v[38:41]
	v_mfma_f32_16x16x32_bf16 v[34:37], v[148:151], v[196:199], v[34:37]
	v_mfma_f32_16x16x32_bf16 v[62:65], v[144:147], v[176:179], v[62:65]
	v_mfma_f32_16x16x32_bf16 v[58:61], v[152:155], v[176:179], v[58:61]
	v_mfma_f32_16x16x32_bf16 v[54:57], v[144:147], v[184:187], v[54:57]
	v_mfma_f32_16x16x32_bf16 v[50:53], v[152:155], v[184:187], v[50:53]
	v_mfma_f32_16x16x32_bf16 v[46:49], v[144:147], v[192:195], v[46:49]
	v_mfma_f32_16x16x32_bf16 v[42:45], v[152:155], v[192:195], v[42:45]
	v_mfma_f32_16x16x32_bf16 v[38:41], v[144:147], v[200:203], v[38:41]
	v_mfma_f32_16x16x32_bf16 v[34:37], v[152:155], v[200:203], v[34:37]
	v_mfma_f32_16x16x32_bf16 v[30:33], v[156:159], v[172:175], v[30:33]
	v_mfma_f32_16x16x32_bf16 v[26:29], v[164:167], v[172:175], v[26:29]
	v_mfma_f32_16x16x32_bf16 v[22:25], v[156:159], v[180:183], v[22:25]
	v_mfma_f32_16x16x32_bf16 v[18:21], v[164:167], v[180:183], v[18:21]
	v_mfma_f32_16x16x32_bf16 v[14:17], v[156:159], v[188:191], v[14:17]
	v_mfma_f32_16x16x32_bf16 v[10:13], v[164:167], v[188:191], v[10:13]
	v_mfma_f32_16x16x32_bf16 v[6:9], v[156:159], v[196:199], v[6:9]
	v_mfma_f32_16x16x32_bf16 v[2:5], v[164:167], v[196:199], v[2:5]
	v_mfma_f32_16x16x32_bf16 v[30:33], v[160:163], v[176:179], v[30:33]
	v_mfma_f32_16x16x32_bf16 v[26:29], v[168:171], v[176:179], v[26:29]
	v_mfma_f32_16x16x32_bf16 v[22:25], v[160:163], v[184:187], v[22:25]
	v_mfma_f32_16x16x32_bf16 v[18:21], v[168:171], v[184:187], v[18:21]
	v_mfma_f32_16x16x32_bf16 v[14:17], v[160:163], v[192:195], v[14:17]
	v_mfma_f32_16x16x32_bf16 v[10:13], v[168:171], v[192:195], v[10:13]
	v_mfma_f32_16x16x32_bf16 v[6:9], v[160:163], v[200:203], v[6:9]
	v_mfma_f32_16x16x32_bf16 v[2:5], v[168:171], v[200:203], v[2:5]
	s_barrier
	s_setprio 0
	v_add_u32_e32 v152, s75, v140
	v_add_u32_e32 v168, s76, v140
	ds_read_b128 v[136:139], v152
	ds_read_b128 v[144:147], v152 offset:1024
	ds_read_b128 v[148:151], v152 offset:2048
	ds_read_b128 v[152:155], v152 offset:3072
	ds_read_b128 v[156:159], v168
	ds_read_b128 v[160:163], v168 offset:1024
	ds_read_b128 v[164:167], v168 offset:2048
	ds_read_b128 v[168:171], v168 offset:3072
	s_mov_b32 m0, s51
	v_lshl_add_u64 v[212:213], s[40:41], 0, v[130:131]
	ds_read_b128 v[172:175], v143 offset:32768
	ds_read_b128 v[176:179], v143 offset:33792
	ds_read_b128 v[180:183], v143 offset:34816
	ds_read_b128 v[184:187], v143 offset:35840
	ds_read_b128 v[188:191], v143 offset:36864
	ds_read_b128 v[192:195], v143 offset:37888
	ds_read_b128 v[196:199], v143 offset:38912
	ds_read_b128 v[200:203], v143 offset:39936
	global_load_lds_dwordx4 v[212:213], off
	v_lshl_add_u64 v[212:213], s[40:41], 0, v[132:133]
	s_mov_b32 m0, s52
	s_nop 0
	global_load_lds_dwordx4 v[212:213], off
	s_waitcnt vmcnt(8)
	s_waitcnt lgkmcnt(0)
	s_barrier
	s_setprio 1
	v_mfma_f32_16x16x32_bf16 v[126:129], v[136:139], v[172:175], v[126:129]
	v_mfma_f32_16x16x32_bf16 v[122:125], v[148:151], v[172:175], v[122:125]
	v_mfma_f32_16x16x32_bf16 v[118:121], v[136:139], v[180:183], v[118:121]
	v_mfma_f32_16x16x32_bf16 v[114:117], v[148:151], v[180:183], v[114:117]
	v_mfma_f32_16x16x32_bf16 v[110:113], v[136:139], v[188:191], v[110:113]
	v_mfma_f32_16x16x32_bf16 v[106:109], v[148:151], v[188:191], v[106:109]
	v_mfma_f32_16x16x32_bf16 v[102:105], v[136:139], v[196:199], v[102:105]
	v_mfma_f32_16x16x32_bf16 v[98:101], v[148:151], v[196:199], v[98:101]
	v_mfma_f32_16x16x32_bf16 v[126:129], v[144:147], v[176:179], v[126:129]
	v_mfma_f32_16x16x32_bf16 v[122:125], v[152:155], v[176:179], v[122:125]
	v_mfma_f32_16x16x32_bf16 v[118:121], v[144:147], v[184:187], v[118:121]
	v_mfma_f32_16x16x32_bf16 v[114:117], v[152:155], v[184:187], v[114:117]
	v_mfma_f32_16x16x32_bf16 v[110:113], v[144:147], v[192:195], v[110:113]
	v_mfma_f32_16x16x32_bf16 v[106:109], v[152:155], v[192:195], v[106:109]
	v_mfma_f32_16x16x32_bf16 v[102:105], v[144:147], v[200:203], v[102:105]
	v_mfma_f32_16x16x32_bf16 v[98:101], v[152:155], v[200:203], v[98:101]
	v_mfma_f32_16x16x32_bf16 v[94:97], v[156:159], v[172:175], v[94:97]
	v_mfma_f32_16x16x32_bf16 v[90:93], v[164:167], v[172:175], v[90:93]
	v_mfma_f32_16x16x32_bf16 v[86:89], v[156:159], v[180:183], v[86:89]
	v_mfma_f32_16x16x32_bf16 v[82:85], v[164:167], v[180:183], v[82:85]
	v_mfma_f32_16x16x32_bf16 v[78:81], v[156:159], v[188:191], v[78:81]
	v_mfma_f32_16x16x32_bf16 v[74:77], v[164:167], v[188:191], v[74:77]
	v_mfma_f32_16x16x32_bf16 v[70:73], v[156:159], v[196:199], v[70:73]
	v_mfma_f32_16x16x32_bf16 v[66:69], v[164:167], v[196:199], v[66:69]
	v_mfma_f32_16x16x32_bf16 v[94:97], v[160:163], v[176:179], v[94:97]
	v_mfma_f32_16x16x32_bf16 v[90:93], v[168:171], v[176:179], v[90:93]
	v_mfma_f32_16x16x32_bf16 v[86:89], v[160:163], v[184:187], v[86:89]
	v_mfma_f32_16x16x32_bf16 v[82:85], v[168:171], v[184:187], v[82:85]
	v_mfma_f32_16x16x32_bf16 v[78:81], v[160:163], v[192:195], v[78:81]
	v_mfma_f32_16x16x32_bf16 v[74:77], v[168:171], v[192:195], v[74:77]
	v_mfma_f32_16x16x32_bf16 v[70:73], v[160:163], v[200:203], v[70:73]
	v_mfma_f32_16x16x32_bf16 v[66:69], v[168:171], v[200:203], v[66:69]
	s_barrier
; #define PG8_STAGE(bufoff, gbase, voff) do { _Pragma("unroll") for (int _i = 0; _i < 2; ++_i) \
;         __builtin_amdgcn_global_load_lds((const unsigned*)((const char*)(gbase) + (voff)[_i]), (LAS unsigned*)(lds + (bufoff) + ldsw + _i * 8192), 16, 0, 0); } while (0)
; #define PG8_LDA(dst, b, h) do { _Pragma("unroll") for (int m = 0; m < 4; ++m) _Pragma("unroll") for (int k = 0; k < 2; ++k) dst[m][k] = *(const LAS bf16x8*)(lds + PG8_SA(b, h) + aoff + m * 2048 + k * 1024); } while (0)
; #define PG8_MMA(ai, bj, At, Bt) do { __builtin_amdgcn_s_setprio(1); _Pragma("unroll") for (int m = 0; m < 4; ++m) _Pragma("unroll") for (int n = 0; n < 2; ++n) _Pragma("unroll") for (int k = 0; k < 2; ++k) \
;         acc[ai][bj][m][n] = __builtin_amdgcn_mfma_f32_16x16x32_bf16(Bt[n][k], At[m][k], acc[ai][bj][m][n], 0, 0, 0); __builtin_amdgcn_s_setprio(0); } while (0)
; #define PG8_WAIT_V(n) asm volatile("s_waitcnt vmcnt(" #n ")" ::: "memory")
; #define PG8_WAIT_L(n) asm volatile("s_waitcnt lgkmcnt(" #n ")" ::: "memory")
; #define PG8_BAR __builtin_amdgcn_s_barrier()
; #define PG8_SCHED __builtin_amdgcn_sched_barrier(0)
; template <class Epi, class Sched, bool ALIGN_EPI, bool LAST_FUSED = false, bool PERM = false, bool CARRY = false>
; __device__ __forceinline__ void gemm_phase(LAS unsigned char* lds, const int tid, const int K, const int lda, const int ldb, const Sched& S, const Epi& E) {
;     ...
;             PG8_LDA(At, 1, 1); PG8_STAGE(PG8_SB(1, 0), b3, voffB); PG8_STAGE(PG8_SB(1, 1), b3 + hstepB, voffB); PG8_STAGE(PG8_SA(1, 0), a3, voffA);
;             PG8_WAIT_V(8); PG8_WAIT_L(0); PG8_BAR; PG8_MMA(1, 0, At, B0); PG8_MMA(1, 1, At, B1); PG8_BAR; PG8_SCHED;
;         }
;         if constexpr (ALIGN_EPI) { if (wr == 0) PG8_BAR; }
	s_setprio 0
	s_mov_b32 m0, s61
	v_lshl_add_u64 v[204:205], v[204:205], 0, s[68:69]
	ds_read_b128 v[172:175], v143 offset:49152
	ds_read_b128 v[176:179], v143 offset:50176
	ds_read_b128 v[180:183], v143 offset:51200
	ds_read_b128 v[184:187], v143 offset:52224
	ds_read_b128 v[188:191], v143 offset:53248
	ds_read_b128 v[192:195], v143 offset:54272
	ds_read_b128 v[196:199], v143 offset:55296
	ds_read_b128 v[200:203], v143 offset:56320
	global_load_lds_dwordx4 v[204:205], off
	v_lshl_add_u64 v[204:205], v[206:207], 0, s[68:69]
	s_mov_b32 m0, s24
	s_nop 0
	global_load_lds_dwordx4 v[204:205], off
	v_lshl_add_u64 v[204:205], s[38:39], 0, v[0:1]
	s_mov_b32 m0, s63
	s_nop 0
	global_load_lds_dwordx4 v[204:205], off
	v_lshl_add_u64 v[204:205], s[38:39], 0, v[134:135]
	s_mov_b32 m0, s62
	s_nop 0
	global_load_lds_dwordx4 v[204:205], off
	v_lshl_add_u64 v[204:205], v[208:209], 0, s[68:69]
	s_mov_b32 m0, s55
	s_nop 0
	global_load_lds_dwordx4 v[204:205], off
	v_lshl_add_u64 v[204:205], v[210:211], 0, s[68:69]
	s_mov_b32 m0, s56
	s_nop 0
	global_load_lds_dwordx4 v[204:205], off
	s_waitcnt vmcnt(8)
	s_waitcnt lgkmcnt(0)
	s_barrier
	s_setprio 1
	v_mfma_f32_16x16x32_bf16 v[62:65], v[136:139], v[172:175], v[62:65]
	v_mfma_f32_16x16x32_bf16 v[58:61], v[148:151], v[172:175], v[58:61]
	v_mfma_f32_16x16x32_bf16 v[54:57], v[136:139], v[180:183], v[54:57]
	v_mfma_f32_16x16x32_bf16 v[50:53], v[148:151], v[180:183], v[50:53]
	v_mfma_f32_16x16x32_bf16 v[46:49], v[136:139], v[188:191], v[46:49]
	v_mfma_f32_16x16x32_bf16 v[42:45], v[148:151], v[188:191], v[42:45]
	v_mfma_f32_16x16x32_bf16 v[38:41], v[136:139], v[196:199], v[38:41]
	v_mfma_f32_16x16x32_bf16 v[34:37], v[148:151], v[196:199], v[34:37]
	v_mfma_f32_16x16x32_bf16 v[62:65], v[144:147], v[176:179], v[62:65]
	v_mfma_f32_16x16x32_bf16 v[58:61], v[152:155], v[176:179], v[58:61]
	v_mfma_f32_16x16x32_bf16 v[54:57], v[144:147], v[184:187], v[54:57]
	v_mfma_f32_16x16x32_bf16 v[50:53], v[152:155], v[184:187], v[50:53]
	v_mfma_f32_16x16x32_bf16 v[46:49], v[144:147], v[192:195], v[46:49]
	v_mfma_f32_16x16x32_bf16 v[42:45], v[152:155], v[192:195], v[42:45]
	v_mfma_f32_16x16x32_bf16 v[38:41], v[144:147], v[200:203], v[38:41]
	v_mfma_f32_16x16x32_bf16 v[34:37], v[152:155], v[200:203], v[34:37]
	v_mfma_f32_16x16x32_bf16 v[30:33], v[156:159], v[172:175], v[30:33]
	v_mfma_f32_16x16x32_bf16 v[26:29], v[164:167], v[172:175], v[26:29]
	v_mfma_f32_16x16x32_bf16 v[22:25], v[156:159], v[180:183], v[22:25]
	v_mfma_f32_16x16x32_bf16 v[18:21], v[164:167], v[180:183], v[18:21]
	v_mfma_f32_16x16x32_bf16 v[14:17], v[156:159], v[188:191], v[14:17]
	v_mfma_f32_16x16x32_bf16 v[10:13], v[164:167], v[188:191], v[10:13]
	v_mfma_f32_16x16x32_bf16 v[6:9], v[156:159], v[196:199], v[6:9]
	v_mfma_f32_16x16x32_bf16 v[2:5], v[164:167], v[196:199], v[2:5]
	v_mfma_f32_16x16x32_bf16 v[30:33], v[160:163], v[176:179], v[30:33]
	v_mfma_f32_16x16x32_bf16 v[26:29], v[168:171], v[176:179], v[26:29]
	v_mfma_f32_16x16x32_bf16 v[22:25], v[160:163], v[184:187], v[22:25]
	v_mfma_f32_16x16x32_bf16 v[18:21], v[168:171], v[184:187], v[18:21]
	v_mfma_f32_16x16x32_bf16 v[14:17], v[160:163], v[192:195], v[14:17]
	v_mfma_f32_16x16x32_bf16 v[10:13], v[168:171], v[192:195], v[10:13]
	v_mfma_f32_16x16x32_bf16 v[6:9], v[160:163], v[200:203], v[6:9]
	v_mfma_f32_16x16x32_bf16 v[2:5], v[168:171], v[200:203], v[2:5]
	s_barrier
	s_setprio 0
	s_movk_i32 s24, 0x100
	s_andn2_b64 vcc, exec, s[36:37]
	s_mov_b64 s[38:39], -1
	s_mov_b64 s[36:37], 0
	s_cbranch_vccz .LBB0_622
	s_and_b64 vcc, exec, s[10:11]
	s_cbranch_vccz .LBB0_625
	s_barrier

; #define PG8_STAGE(bufoff, gbase, voff) do { _Pragma("unroll") for (int _i = 0; _i < 2; ++_i) \
;         __builtin_amdgcn_global_load_lds((const unsigned*)((const char*)(gbase) + (voff)[_i]), (LAS unsigned*)(lds + (bufoff) + ldsw + _i * 8192), 16, 0, 0); } while (0)
; #define PG8_LDA(dst, b, h) do { _Pragma("unroll") for (int m = 0; m < 4; ++m) _Pragma("unroll") for (int k = 0; k < 2; ++k) dst[m][k] = *(const LAS bf16x8*)(lds + PG8_SA(b, h) + aoff + m * 2048 + k * 1024); } while (0)
; #define PG8_LDB(dst, b, h) do { _Pragma("unroll") for (int n = 0; n < 2; ++n) _Pragma("unroll") for (int k = 0; k < 2; ++k) dst[n][k] = *(const LAS bf16x8*)(lds + PG8_SB(b, h) + boff + n * 2048 + k * 1024); } while (0)
; #define PG8_WAIT_V(n) asm volatile("s_waitcnt vmcnt(" #n ")" ::: "memory")
; #define PG8_WAIT_L(n) asm volatile("s_waitcnt lgkmcnt(" #n ")" ::: "memory")
; #define PG8_BAR __builtin_amdgcn_s_barrier()
; #define PG8_SCHED __builtin_amdgcn_sched_barrier(0)
; template <class Epi, class Sched, bool ALIGN_EPI, bool LAST_FUSED = false, bool PERM = false, bool CARRY = false>
; __device__ __forceinline__ void gemm_phase(LAS unsigned char* lds, const int tid, const int K, const int lda, const int ldb, const Sched& S, const Epi& E) {
;     ...
;         const bool has_next = S.next(KD_IDX(ui + 1), nxt);
;         const char* nA = has_next ? nxt.a : cA; const char* nB = has_next ? nxt.b : cB; const int nt = cur.nt;
; #pragma unroll 1
;         for (int t = 0; t < nt; t += 2) {
;             const bool last = (t == nt - 2);
;             const char* a1 = cA + (size_t)(t + 1) * kstep;
;             const char* a2 = last ? nA : cA + (size_t)(t + 2) * kstep; const char* b2 = last ? nB : cB + (size_t)(t + 2) * kstep;
;             const char* a3 = a2 + kstep; const char* b3 = b2 + kstep;
;             PG8_LDB(B0, 0, 0); PG8_LDB(B1, 0, 1); PG8_SCHED; PG8_LDA(At, 0, 0); PG8_STAGE(PG8_SA(1, 1), a1 + hstepA, voffA);
;             PG8_WAIT_V(8); PG8_WAIT_L(0); PG8_BAR; PG8_MMA(0, 0, At, B0); PG8_MMA(0, 1, At, B1); PG8_BAR; PG8_SCHED;
;             PG8_LDA(At, 0, 1); PG8_STAGE(PG8_SB(0, 0), b2, voffB); PG8_STAGE(PG8_SB(0, 1), b2 + hstepB, voffB); PG8_STAGE(PG8_SA(0, 0), a2, voffA);
;             PG8_WAIT_V(8); PG8_WAIT_L(0); PG8_BAR; PG8_MMA(1, 0, At, B0); PG8_MMA(1, 1, At, B1); PG8_BAR; PG8_SCHED;
.LBB0_705:
	s_add_u32 s30, s26, 0x100
	s_addc_u32 s31, s27, 0
	s_add_i32 s54, 0, 0x10000
	s_cmp_eq_u32 s53, 8
	s_cselect_b32 s39, s15, s31
	s_cselect_b32 s38, s14, s30
	v_add_u32_e32 v140, s54, v144
	s_cselect_b32 s37, s17, s52
	s_cselect_b32 s36, s16, s13
	s_add_i32 s55, 0, 0x14000
	ds_read_b128 v[146:149], v140
	ds_read_b128 v[150:153], v140 offset:1024
	ds_read_b128 v[154:157], v140 offset:2048
	ds_read_b128 v[158:161], v140 offset:3072
	v_add_u32_e32 v140, s55, v144
	ds_read_b128 v[162:165], v140
	ds_read_b128 v[166:169], v140 offset:1024
	ds_read_b128 v[170:173], v140 offset:2048
	ds_read_b128 v[174:177], v140 offset:3072
	v_lshl_add_u64 v[140:141], s[26:27], 0, v[136:137]
	s_add_i32 m0, s19, 0xc000
	ds_read_b128 v[178:181], v145
	ds_read_b128 v[182:185], v145 offset:1024
	ds_read_b128 v[186:189], v145 offset:2048
	ds_read_b128 v[190:193], v145 offset:3072
	ds_read_b128 v[194:197], v145 offset:4096
	ds_read_b128 v[198:201], v145 offset:5120
	ds_read_b128 v[202:205], v145 offset:6144
	ds_read_b128 v[206:209], v145 offset:7168
	global_load_lds_dwordx4 v[140:141], off
	v_lshl_add_u64 v[140:141], s[26:27], 0, v[138:139]
	s_add_i32 m0, s19, 0xe000
	s_nop 0
	global_load_lds_dwordx4 v[140:141], off
	s_waitcnt vmcnt(8)
	s_waitcnt lgkmcnt(0)
	s_barrier
	s_setprio 1
	v_mfma_f32_16x16x32_bf16 v[126:129], v[146:149], v[178:181], v[126:129]
	v_mfma_f32_16x16x32_bf16 v[122:125], v[154:157], v[178:181], v[122:125]
	v_mfma_f32_16x16x32_bf16 v[118:121], v[146:149], v[186:189], v[118:121]
	v_mfma_f32_16x16x32_bf16 v[110:113], v[154:157], v[186:189], v[110:113]
	v_mfma_f32_16x16x32_bf16 v[102:105], v[146:149], v[194:197], v[102:105]
	v_mfma_f32_16x16x32_bf16 v[94:97], v[154:157], v[194:197], v[94:97]
	v_mfma_f32_16x16x32_bf16 v[86:89], v[146:149], v[202:205], v[86:89]
	v_mfma_f32_16x16x32_bf16 v[78:81], v[154:157], v[202:205], v[78:81]
	v_mfma_f32_16x16x32_bf16 v[126:129], v[150:153], v[182:185], v[126:129]
	v_mfma_f32_16x16x32_bf16 v[122:125], v[158:161], v[182:185], v[122:125]
	v_mfma_f32_16x16x32_bf16 v[118:121], v[150:153], v[190:193], v[118:121]
	v_mfma_f32_16x16x32_bf16 v[110:113], v[158:161], v[190:193], v[110:113]
	v_mfma_f32_16x16x32_bf16 v[102:105], v[150:153], v[198:201], v[102:105]
	v_mfma_f32_16x16x32_bf16 v[94:97], v[158:161], v[198:201], v[94:97]
	v_mfma_f32_16x16x32_bf16 v[86:89], v[150:153], v[206:209], v[86:89]
	v_mfma_f32_16x16x32_bf16 v[78:81], v[158:161], v[206:209], v[78:81]
	v_mfma_f32_16x16x32_bf16 v[114:117], v[162:165], v[178:181], v[114:117]
	v_mfma_f32_16x16x32_bf16 v[106:109], v[170:173], v[178:181], v[106:109]
	v_mfma_f32_16x16x32_bf16 v[98:101], v[162:165], v[186:189], v[98:101]
	v_mfma_f32_16x16x32_bf16 v[90:93], v[170:173], v[186:189], v[90:93]
	v_mfma_f32_16x16x32_bf16 v[82:85], v[162:165], v[194:197], v[82:85]
	v_mfma_f32_16x16x32_bf16 v[74:77], v[170:173], v[194:197], v[74:77]
	v_mfma_f32_16x16x32_bf16 v[70:73], v[162:165], v[202:205], v[70:73]
	v_mfma_f32_16x16x32_bf16 v[66:69], v[170:173], v[202:205], v[66:69]
	v_mfma_f32_16x16x32_bf16 v[114:117], v[166:169], v[182:185], v[114:117]
	v_mfma_f32_16x16x32_bf16 v[106:109], v[174:177], v[182:185], v[106:109]
	v_mfma_f32_16x16x32_bf16 v[98:101], v[166:169], v[190:193], v[98:101]
	v_mfma_f32_16x16x32_bf16 v[90:93], v[174:177], v[190:193], v[90:93]
	v_mfma_f32_16x16x32_bf16 v[82:85], v[166:169], v[198:201], v[82:85]
	v_mfma_f32_16x16x32_bf16 v[74:77], v[174:177], v[198:201], v[74:77]
	v_mfma_f32_16x16x32_bf16 v[70:73], v[166:169], v[206:209], v[70:73]
	v_mfma_f32_16x16x32_bf16 v[66:69], v[174:177], v[206:209], v[66:69]
	s_barrier
	s_setprio 0
	s_add_i32 s26, s54, s40
	v_lshl_add_u64 v[140:141], s[36:37], 0, v[0:1]
	s_mov_b32 m0, s26
	ds_read_b128 v[178:181], v145 offset:16384
	ds_read_b128 v[182:185], v145 offset:17408
	ds_read_b128 v[186:189], v145 offset:18432
	ds_read_b128 v[190:193], v145 offset:19456
	ds_read_b128 v[194:197], v145 offset:20480
	ds_read_b128 v[198:201], v145 offset:21504
	ds_read_b128 v[202:205], v145 offset:22528
	ds_read_b128 v[206:209], v145 offset:23552
	global_load_lds_dwordx4 v[140:141], off
	s_add_i32 m0, s26, 0x2000
	s_add_u32 s26, s36, 0x30000
	v_lshl_add_u64 v[210:211], s[36:37], 0, v[130:131]
	s_addc_u32 s27, s37, 0
	s_add_i32 s54, s55, s40
	global_load_lds_dwordx4 v[210:211], off
	v_lshl_add_u64 v[212:213], s[26:27], 0, v[0:1]
	s_mov_b32 m0, s54
	v_lshl_add_u64 v[214:215], s[38:39], 0, v[132:133]
	global_load_lds_dwordx4 v[212:213], off
	v_lshl_add_u64 v[212:213], s[26:27], 0, v[130:131]
	s_add_i32 m0, s54, 0x2000
	s_nop 0
	global_load_lds_dwordx4 v[212:213], off
	v_lshl_add_u64 v[212:213], s[38:39], 0, v[134:135]
	s_mov_b32 m0, s19
	s_nop 0
	global_load_lds_dwordx4 v[212:213], off
	s_mov_b32 m0, s42
	s_nop 0
	global_load_lds_dwordx4 v[214:215], off
	s_waitcnt vmcnt(8)
	s_waitcnt lgkmcnt(0)
	s_barrier
; #define PG8_STAGE(bufoff, gbase, voff) do { _Pragma("unroll") for (int _i = 0; _i < 2; ++_i) \
;         __builtin_amdgcn_global_load_lds((const unsigned*)((const char*)(gbase) + (voff)[_i]), (LAS unsigned*)(lds + (bufoff) + ldsw + _i * 8192), 16, 0, 0); } while (0)
; #define PG8_LDA(dst, b, h) do { _Pragma("unroll") for (int m = 0; m < 4; ++m) _Pragma("unroll") for (int k = 0; k < 2; ++k) dst[m][k] = *(const LAS bf16x8*)(lds + PG8_SA(b, h) + aoff + m * 2048 + k * 1024); } while (0)
; #define PG8_LDB(dst, b, h) do { _Pragma("unroll") for (int n = 0; n < 2; ++n) _Pragma("unroll") for (int k = 0; k < 2; ++k) dst[n][k] = *(const LAS bf16x8*)(lds + PG8_SB(b, h) + boff + n * 2048 + k * 1024); } while (0)
; #define PG8_MMA(ai, bj, At, Bt) do { __builtin_amdgcn_s_setprio(1); _Pragma("unroll") for (int m = 0; m < 4; ++m) _Pragma("unroll") for (int n = 0; n < 2; ++n) _Pragma("unroll") for (int k = 0; k < 2; ++k) \
;         acc[ai][bj][m][n] = __builtin_amdgcn_mfma_f32_16x16x32_bf16(Bt[n][k], At[m][k], acc[ai][bj][m][n], 0, 0, 0); __builtin_amdgcn_s_setprio(0); } while (0)
; #define PG8_WAIT_V(n) asm volatile("s_waitcnt vmcnt(" #n ")" ::: "memory")
; #define PG8_WAIT_L(n) asm volatile("s_waitcnt lgkmcnt(" #n ")" ::: "memory")
; #define PG8_BAR __builtin_amdgcn_s_barrier()
; #define PG8_SCHED __builtin_amdgcn_sched_barrier(0)
; template <class Epi, class Sched, bool ALIGN_EPI, bool LAST_FUSED = false, bool PERM = false, bool CARRY = false>
; __device__ __forceinline__ void gemm_phase(LAS unsigned char* lds, const int tid, const int K, const int lda, const int ldb, const Sched& S, const Epi& E) {
;     ...
;             PG8_WAIT_V(8); PG8_WAIT_L(0); PG8_BAR; PG8_MMA(1, 0, At, B0); PG8_MMA(1, 1, At, B1); PG8_BAR; PG8_SCHED;
;             PG8_LDB(B0, 1, 0); PG8_LDB(B1, 1, 1); PG8_SCHED; PG8_LDA(At, 1, 0); PG8_STAGE(PG8_SA(0, 1), a2 + hstepA, voffA);
;             PG8_WAIT_V(8); PG8_WAIT_L(0); PG8_BAR; PG8_MMA(0, 0, At, B0); PG8_MMA(0, 1, At, B1); PG8_BAR; PG8_SCHED;
	s_setprio 1
	v_mfma_f32_16x16x32_bf16 v[62:65], v[146:149], v[178:181], v[62:65]
	v_mfma_f32_16x16x32_bf16 v[58:61], v[154:157], v[178:181], v[58:61]
	v_mfma_f32_16x16x32_bf16 v[54:57], v[146:149], v[186:189], v[54:57]
	v_mfma_f32_16x16x32_bf16 v[46:49], v[154:157], v[186:189], v[46:49]
	v_mfma_f32_16x16x32_bf16 v[38:41], v[146:149], v[194:197], v[38:41]
	v_mfma_f32_16x16x32_bf16 v[30:33], v[154:157], v[194:197], v[30:33]
	v_mfma_f32_16x16x32_bf16 v[22:25], v[146:149], v[202:205], v[22:25]
	v_mfma_f32_16x16x32_bf16 v[14:17], v[154:157], v[202:205], v[14:17]
	v_mfma_f32_16x16x32_bf16 v[62:65], v[150:153], v[182:185], v[62:65]
	v_mfma_f32_16x16x32_bf16 v[58:61], v[158:161], v[182:185], v[58:61]
	v_mfma_f32_16x16x32_bf16 v[54:57], v[150:153], v[190:193], v[54:57]
	v_mfma_f32_16x16x32_bf16 v[46:49], v[158:161], v[190:193], v[46:49]
	v_mfma_f32_16x16x32_bf16 v[38:41], v[150:153], v[198:201], v[38:41]
	v_mfma_f32_16x16x32_bf16 v[30:33], v[158:161], v[198:201], v[30:33]
	v_mfma_f32_16x16x32_bf16 v[22:25], v[150:153], v[206:209], v[22:25]
	v_mfma_f32_16x16x32_bf16 v[14:17], v[158:161], v[206:209], v[14:17]
	v_mfma_f32_16x16x32_bf16 v[50:53], v[162:165], v[178:181], v[50:53]
	v_mfma_f32_16x16x32_bf16 v[42:45], v[170:173], v[178:181], v[42:45]
	v_mfma_f32_16x16x32_bf16 v[34:37], v[162:165], v[186:189], v[34:37]
	v_mfma_f32_16x16x32_bf16 v[26:29], v[170:173], v[186:189], v[26:29]
	v_mfma_f32_16x16x32_bf16 v[18:21], v[162:165], v[194:197], v[18:21]
	v_mfma_f32_16x16x32_bf16 v[10:13], v[170:173], v[194:197], v[10:13]
	v_mfma_f32_16x16x32_bf16 v[6:9], v[162:165], v[202:205], v[6:9]
	v_mfma_f32_16x16x32_bf16 v[2:5], v[170:173], v[202:205], v[2:5]
	v_mfma_f32_16x16x32_bf16 v[50:53], v[166:169], v[182:185], v[50:53]
	v_mfma_f32_16x16x32_bf16 v[42:45], v[174:177], v[182:185], v[42:45]
	v_mfma_f32_16x16x32_bf16 v[34:37], v[166:169], v[190:193], v[34:37]
	v_mfma_f32_16x16x32_bf16 v[26:29], v[174:177], v[190:193], v[26:29]
	v_mfma_f32_16x16x32_bf16 v[18:21], v[166:169], v[198:201], v[18:21]
	v_mfma_f32_16x16x32_bf16 v[10:13], v[174:177], v[198:201], v[10:13]
	v_mfma_f32_16x16x32_bf16 v[6:9], v[166:169], v[206:209], v[6:9]
	v_mfma_f32_16x16x32_bf16 v[2:5], v[174:177], v[206:209], v[2:5]
	s_barrier
	s_setprio 0
	s_add_i32 s54, 0, 0x18000
	s_add_i32 s55, 0, 0x1c000
	v_add_u32_e32 v158, s54, v144
	v_add_u32_e32 v174, s55, v144
	ds_read_b128 v[146:149], v158
	ds_read_b128 v[150:153], v158 offset:1024
	ds_read_b128 v[154:157], v158 offset:2048
	ds_read_b128 v[158:161], v158 offset:3072
	ds_read_b128 v[162:165], v174
	ds_read_b128 v[166:169], v174 offset:1024
	ds_read_b128 v[170:173], v174 offset:2048
	ds_read_b128 v[174:177], v174 offset:3072
	s_add_u32 s26, s38, 0x180000
	s_addc_u32 s27, s39, 0
	s_mov_b32 m0, s43
	v_lshl_add_u64 v[216:217], s[26:27], 0, v[134:135]
	ds_read_b128 v[178:181], v145 offset:32768
	ds_read_b128 v[182:185], v145 offset:33792
	ds_read_b128 v[186:189], v145 offset:34816
	ds_read_b128 v[190:193], v145 offset:35840
	ds_read_b128 v[194:197], v145 offset:36864
	ds_read_b128 v[198:201], v145 offset:37888
	ds_read_b128 v[202:205], v145 offset:38912
	ds_read_b128 v[206:209], v145 offset:39936
	global_load_lds_dwordx4 v[216:217], off
	v_lshl_add_u64 v[216:217], s[26:27], 0, v[132:133]
	s_mov_b32 m0, s44
	s_nop 0
	global_load_lds_dwordx4 v[216:217], off
	s_waitcnt vmcnt(8)
	s_waitcnt lgkmcnt(0)
	s_barrier
	s_setprio 1
	v_mfma_f32_16x16x32_bf16 v[126:129], v[146:149], v[178:181], v[126:129]
	v_mfma_f32_16x16x32_bf16 v[122:125], v[154:157], v[178:181], v[122:125]
	v_mfma_f32_16x16x32_bf16 v[118:121], v[146:149], v[186:189], v[118:121]
	v_mfma_f32_16x16x32_bf16 v[110:113], v[154:157], v[186:189], v[110:113]
	v_mfma_f32_16x16x32_bf16 v[102:105], v[146:149], v[194:197], v[102:105]
	v_mfma_f32_16x16x32_bf16 v[94:97], v[154:157], v[194:197], v[94:97]
	v_mfma_f32_16x16x32_bf16 v[86:89], v[146:149], v[202:205], v[86:89]
	v_mfma_f32_16x16x32_bf16 v[78:81], v[154:157], v[202:205], v[78:81]
	v_mfma_f32_16x16x32_bf16 v[126:129], v[150:153], v[182:185], v[126:129]
	v_mfma_f32_16x16x32_bf16 v[122:125], v[158:161], v[182:185], v[122:125]
	v_mfma_f32_16x16x32_bf16 v[118:121], v[150:153], v[190:193], v[118:121]
	v_mfma_f32_16x16x32_bf16 v[110:113], v[158:161], v[190:193], v[110:113]
	v_mfma_f32_16x16x32_bf16 v[102:105], v[150:153], v[198:201], v[102:105]
	v_mfma_f32_16x16x32_bf16 v[94:97], v[158:161], v[198:201], v[94:97]
	v_mfma_f32_16x16x32_bf16 v[86:89], v[150:153], v[206:209], v[86:89]
	v_mfma_f32_16x16x32_bf16 v[78:81], v[158:161], v[206:209], v[78:81]
	v_mfma_f32_16x16x32_bf16 v[114:117], v[162:165], v[178:181], v[114:117]
	v_mfma_f32_16x16x32_bf16 v[106:109], v[170:173], v[178:181], v[106:109]
	v_mfma_f32_16x16x32_bf16 v[98:101], v[162:165], v[186:189], v[98:101]
	v_mfma_f32_16x16x32_bf16 v[90:93], v[170:173], v[186:189], v[90:93]
	v_mfma_f32_16x16x32_bf16 v[82:85], v[162:165], v[194:197], v[82:85]
	v_mfma_f32_16x16x32_bf16 v[74:77], v[170:173], v[194:197], v[74:77]
	v_mfma_f32_16x16x32_bf16 v[70:73], v[162:165], v[202:205], v[70:73]
	v_mfma_f32_16x16x32_bf16 v[66:69], v[170:173], v[202:205], v[66:69]
	v_mfma_f32_16x16x32_bf16 v[114:117], v[166:169], v[182:185], v[114:117]
	v_mfma_f32_16x16x32_bf16 v[106:109], v[174:177], v[182:185], v[106:109]
	v_mfma_f32_16x16x32_bf16 v[98:101], v[166:169], v[190:193], v[98:101]
	v_mfma_f32_16x16x32_bf16 v[90:93], v[174:177], v[190:193], v[90:93]
	v_mfma_f32_16x16x32_bf16 v[82:85], v[166:169], v[198:201], v[82:85]
	v_mfma_f32_16x16x32_bf16 v[74:77], v[174:177], v[198:201], v[74:77]
	v_mfma_f32_16x16x32_bf16 v[70:73], v[166:169], v[206:209], v[70:73]
	v_mfma_f32_16x16x32_bf16 v[66:69], v[174:177], v[206:209], v[66:69]
	s_barrier
; #define PG8_STAGE(bufoff, gbase, voff) do { _Pragma("unroll") for (int _i = 0; _i < 2; ++_i) \
;         __builtin_amdgcn_global_load_lds((const unsigned*)((const char*)(gbase) + (voff)[_i]), (LAS unsigned*)(lds + (bufoff) + ldsw + _i * 8192), 16, 0, 0); } while (0)
; #define PG8_LDA(dst, b, h) do { _Pragma("unroll") for (int m = 0; m < 4; ++m) _Pragma("unroll") for (int k = 0; k < 2; ++k) dst[m][k] = *(const LAS bf16x8*)(lds + PG8_SA(b, h) + aoff + m * 2048 + k * 1024); } while (0)
; #define PG8_MMA(ai, bj, At, Bt) do { __builtin_amdgcn_s_setprio(1); _Pragma("unroll") for (int m = 0; m < 4; ++m) _Pragma("unroll") for (int n = 0; n < 2; ++n) _Pragma("unroll") for (int k = 0; k < 2; ++k) \
;         acc[ai][bj][m][n] = __builtin_amdgcn_mfma_f32_16x16x32_bf16(Bt[n][k], At[m][k], acc[ai][bj][m][n], 0, 0, 0); __builtin_amdgcn_s_setprio(0); } while (0)
; #define PG8_WAIT_V(n) asm volatile("s_waitcnt vmcnt(" #n ")" ::: "memory")
; #define PG8_WAIT_L(n) asm volatile("s_waitcnt lgkmcnt(" #n ")" ::: "memory")
; #define PG8_BAR __builtin_amdgcn_s_barrier()
; #define PG8_SCHED __builtin_amdgcn_sched_barrier(0)
; template <class Epi, class Sched, bool ALIGN_EPI, bool LAST_FUSED = false, bool PERM = false, bool CARRY = false>
; __device__ __forceinline__ void gemm_phase(LAS unsigned char* lds, const int tid, const int K, const int lda, const int ldb, const Sched& S, const Epi& E) {
;     ...
;             PG8_LDA(At, 1, 1); PG8_STAGE(PG8_SB(1, 0), b3, voffB); PG8_STAGE(PG8_SB(1, 1), b3 + hstepB, voffB); PG8_STAGE(PG8_SA(1, 0), a3, voffA);
;             PG8_WAIT_V(8); PG8_WAIT_L(0); PG8_BAR; PG8_MMA(1, 0, At, B0); PG8_MMA(1, 1, At, B1); PG8_BAR; PG8_SCHED;
;         }
;         if constexpr (ALIGN_EPI) { if (wr == 0) PG8_BAR; }
	s_setprio 0
	s_add_i32 s26, s54, s40
	v_lshl_add_u64 v[140:141], v[140:141], 0, s[68:69]
	s_mov_b32 m0, s26
	ds_read_b128 v[178:181], v145 offset:49152
	ds_read_b128 v[182:185], v145 offset:50176
	ds_read_b128 v[186:189], v145 offset:51200
	ds_read_b128 v[190:193], v145 offset:52224
	ds_read_b128 v[194:197], v145 offset:53248
	ds_read_b128 v[198:201], v145 offset:54272
	ds_read_b128 v[202:205], v145 offset:55296
	ds_read_b128 v[206:209], v145 offset:56320
	global_load_lds_dwordx4 v[140:141], off
	s_add_i32 m0, s26, 0x2000
	s_add_u32 s26, s36, 0x30080
	v_lshl_add_u64 v[140:141], v[210:211], 0, s[68:69]
	s_addc_u32 s27, s37, 0
	s_add_i32 s36, s55, s40
	global_load_lds_dwordx4 v[140:141], off
	v_lshl_add_u64 v[140:141], s[26:27], 0, v[0:1]
	s_mov_b32 m0, s36
	s_nop 0
	global_load_lds_dwordx4 v[140:141], off
	v_lshl_add_u64 v[140:141], s[26:27], 0, v[130:131]
	s_add_i32 m0, s36, 0x2000
	s_nop 0
	global_load_lds_dwordx4 v[140:141], off
	v_lshl_add_u64 v[140:141], v[212:213], 0, s[68:69]
	s_mov_b32 m0, s46
	s_nop 0
	global_load_lds_dwordx4 v[140:141], off
	v_lshl_add_u64 v[140:141], v[214:215], 0, s[68:69]
	s_mov_b32 m0, s47
	s_nop 0
	global_load_lds_dwordx4 v[140:141], off
	s_waitcnt vmcnt(8)
	s_waitcnt lgkmcnt(0)
	s_barrier
	s_setprio 1
	v_mfma_f32_16x16x32_bf16 v[62:65], v[146:149], v[178:181], v[62:65]
	v_mfma_f32_16x16x32_bf16 v[58:61], v[154:157], v[178:181], v[58:61]
	v_mfma_f32_16x16x32_bf16 v[54:57], v[146:149], v[186:189], v[54:57]
	v_mfma_f32_16x16x32_bf16 v[46:49], v[154:157], v[186:189], v[46:49]
	v_mfma_f32_16x16x32_bf16 v[38:41], v[146:149], v[194:197], v[38:41]
	v_mfma_f32_16x16x32_bf16 v[30:33], v[154:157], v[194:197], v[30:33]
	v_mfma_f32_16x16x32_bf16 v[22:25], v[146:149], v[202:205], v[22:25]
	v_mfma_f32_16x16x32_bf16 v[14:17], v[154:157], v[202:205], v[14:17]
	v_mfma_f32_16x16x32_bf16 v[62:65], v[150:153], v[182:185], v[62:65]
	v_mfma_f32_16x16x32_bf16 v[58:61], v[158:161], v[182:185], v[58:61]
	v_mfma_f32_16x16x32_bf16 v[54:57], v[150:153], v[190:193], v[54:57]
	v_mfma_f32_16x16x32_bf16 v[46:49], v[158:161], v[190:193], v[46:49]
	v_mfma_f32_16x16x32_bf16 v[38:41], v[150:153], v[198:201], v[38:41]
	v_mfma_f32_16x16x32_bf16 v[30:33], v[158:161], v[198:201], v[30:33]
	v_mfma_f32_16x16x32_bf16 v[22:25], v[150:153], v[206:209], v[22:25]
	v_mfma_f32_16x16x32_bf16 v[14:17], v[158:161], v[206:209], v[14:17]
	v_mfma_f32_16x16x32_bf16 v[50:53], v[162:165], v[178:181], v[50:53]
	v_mfma_f32_16x16x32_bf16 v[42:45], v[170:173], v[178:181], v[42:45]
	v_mfma_f32_16x16x32_bf16 v[34:37], v[162:165], v[186:189], v[34:37]
	v_mfma_f32_16x16x32_bf16 v[26:29], v[170:173], v[186:189], v[26:29]
	v_mfma_f32_16x16x32_bf16 v[18:21], v[162:165], v[194:197], v[18:21]
	v_mfma_f32_16x16x32_bf16 v[10:13], v[170:173], v[194:197], v[10:13]
	v_mfma_f32_16x16x32_bf16 v[6:9], v[162:165], v[202:205], v[6:9]
	v_mfma_f32_16x16x32_bf16 v[2:5], v[170:173], v[202:205], v[2:5]
	v_mfma_f32_16x16x32_bf16 v[50:53], v[166:169], v[182:185], v[50:53]
	v_mfma_f32_16x16x32_bf16 v[42:45], v[174:177], v[182:185], v[42:45]
	v_mfma_f32_16x16x32_bf16 v[34:37], v[166:169], v[190:193], v[34:37]
	v_mfma_f32_16x16x32_bf16 v[26:29], v[174:177], v[190:193], v[26:29]
	v_mfma_f32_16x16x32_bf16 v[18:21], v[166:169], v[198:201], v[18:21]
	v_mfma_f32_16x16x32_bf16 v[10:13], v[174:177], v[198:201], v[10:13]
	v_mfma_f32_16x16x32_bf16 v[6:9], v[166:169], v[206:209], v[6:9]
	v_mfma_f32_16x16x32_bf16 v[2:5], v[174:177], v[206:209], v[2:5]
	s_barrier
	s_setprio 0
	s_add_i32 s53, s53, 2
	s_add_u32 s13, s13, 0x100
	s_addc_u32 s52, s52, 0
	s_cmp_gt_u32 s53, 9
	s_mov_b64 s[26:27], s[30:31]
	s_cbranch_scc0 .LBB0_705
	s_and_b64 vcc, exec, s[10:11]
	s_cbranch_vccz .LBB0_708
	s_barrier

; #define PG8_STAGE(bufoff, gbase, voff) do { _Pragma("unroll") for (int _i = 0; _i < 2; ++_i) \
;         __builtin_amdgcn_global_load_lds((const unsigned*)((const char*)(gbase) + (voff)[_i]), (LAS unsigned*)(lds + (bufoff) + ldsw + _i * 8192), 16, 0, 0); } while (0)
; #define PG8_LDA(dst, b, h) do { _Pragma("unroll") for (int m = 0; m < 4; ++m) _Pragma("unroll") for (int k = 0; k < 2; ++k) dst[m][k] = *(const LAS bf16x8*)(lds + PG8_SA(b, h) + aoff + m * 2048 + k * 1024); } while (0)
; #define PG8_LDB(dst, b, h) do { _Pragma("unroll") for (int n = 0; n < 2; ++n) _Pragma("unroll") for (int k = 0; k < 2; ++k) dst[n][k] = *(const LAS bf16x8*)(lds + PG8_SB(b, h) + boff + n * 2048 + k * 1024); } while (0)
; #define PG8_WAIT_V(n) asm volatile("s_waitcnt vmcnt(" #n ")" ::: "memory")
; #define PG8_WAIT_L(n) asm volatile("s_waitcnt lgkmcnt(" #n ")" ::: "memory")
; #define PG8_BAR __builtin_amdgcn_s_barrier()
; #define PG8_SCHED __builtin_amdgcn_sched_barrier(0)
; template <class Epi, class Sched, bool ALIGN_EPI, bool LAST_FUSED = false, bool PERM = false, bool CARRY = false>
; __device__ __forceinline__ void gemm_phase(LAS unsigned char* lds, const int tid, const int K, const int lda, const int ldb, const Sched& S, const Epi& E) {
;     ...
;         const bool has_next = S.next(KD_IDX(ui + 1), nxt);
;         const char* nA = has_next ? nxt.a : cA; const char* nB = has_next ? nxt.b : cB; const int nt = cur.nt;
; #pragma unroll 1
;         for (int t = 0; t < nt; t += 2) {
;             const bool last = (t == nt - 2);
;             const char* a1 = cA + (size_t)(t + 1) * kstep;
;             const char* a2 = last ? nA : cA + (size_t)(t + 2) * kstep; const char* b2 = last ? nB : cB + (size_t)(t + 2) * kstep;
;             const char* a3 = a2 + kstep; const char* b3 = b2 + kstep;
;             PG8_LDB(B0, 0, 0); PG8_LDB(B1, 0, 1); PG8_SCHED; PG8_LDA(At, 0, 0); PG8_STAGE(PG8_SA(1, 1), a1 + hstepA, voffA);
;             PG8_WAIT_V(8); PG8_WAIT_L(0); PG8_BAR; PG8_MMA(0, 0, At, B0); PG8_MMA(0, 1, At, B1); PG8_BAR; PG8_SCHED;
;             PG8_LDA(At, 0, 1); PG8_STAGE(PG8_SB(0, 0), b2, voffB); PG8_STAGE(PG8_SB(0, 1), b2 + hstepB, voffB); PG8_STAGE(PG8_SA(0, 0), a2, voffA);
;             PG8_WAIT_V(8); PG8_WAIT_L(0); PG8_BAR; PG8_MMA(1, 0, At, B0); PG8_MMA(1, 1, At, B1); PG8_BAR; PG8_SCHED;
.LBB0_838:
	s_add_u32 s6, s4, 0xfff80080
	s_addc_u32 s7, s5, -1
	s_add_i32 s29, 0, 0x10000
	s_cmp_eq_u32 s28, 28
	s_cselect_b32 s37, s43, s7
	s_cselect_b32 s36, s42, s6
	v_add_u32_e32 v140, s29, v146
	s_cselect_b32 s7, s71, s23
	s_cselect_b32 s6, s70, s22
	s_add_i32 s31, 0, 0x14000
	ds_read_b128 v[136:139], v140
	ds_read_b128 v[148:151], v140 offset:1024
	ds_read_b128 v[152:155], v140 offset:2048
	ds_read_b128 v[156:159], v140 offset:3072
	v_add_u32_e32 v140, s31, v146
	ds_read_b128 v[160:163], v140
	ds_read_b128 v[164:167], v140 offset:1024
	ds_read_b128 v[168:171], v140 offset:2048
	ds_read_b128 v[172:175], v140 offset:3072
	v_lshl_add_u64 v[140:141], s[4:5], 0, v[132:133]
	s_add_i32 m0, s50, 0xc000
	ds_read_b128 v[176:179], v147
	ds_read_b128 v[180:183], v147 offset:1024
	ds_read_b128 v[184:187], v147 offset:2048
	ds_read_b128 v[188:191], v147 offset:3072
	ds_read_b128 v[192:195], v147 offset:4096
	ds_read_b128 v[196:199], v147 offset:5120
	ds_read_b128 v[200:203], v147 offset:6144
	ds_read_b128 v[204:207], v147 offset:7168
	global_load_lds_dwordx4 v[140:141], off
	v_lshl_add_u64 v[140:141], s[4:5], 0, v[134:135]
	s_add_i32 m0, s50, 0xe000
	s_nop 0
	global_load_lds_dwordx4 v[140:141], off
	s_waitcnt vmcnt(8)
	s_waitcnt lgkmcnt(0)
	s_barrier
	s_setprio 1
	v_mfma_f32_16x16x32_bf16 v[126:129], v[136:139], v[176:179], v[126:129]
	v_mfma_f32_16x16x32_bf16 v[122:125], v[152:155], v[176:179], v[122:125]
	v_mfma_f32_16x16x32_bf16 v[110:113], v[136:139], v[184:187], v[110:113]
	v_mfma_f32_16x16x32_bf16 v[106:109], v[152:155], v[184:187], v[106:109]
	v_mfma_f32_16x16x32_bf16 v[94:97], v[136:139], v[192:195], v[94:97]
	v_mfma_f32_16x16x32_bf16 v[90:93], v[152:155], v[192:195], v[90:93]
	v_mfma_f32_16x16x32_bf16 v[78:81], v[136:139], v[200:203], v[78:81]
	v_mfma_f32_16x16x32_bf16 v[74:77], v[152:155], v[200:203], v[74:77]
	v_mfma_f32_16x16x32_bf16 v[126:129], v[148:151], v[180:183], v[126:129]
	v_mfma_f32_16x16x32_bf16 v[122:125], v[156:159], v[180:183], v[122:125]
	v_mfma_f32_16x16x32_bf16 v[110:113], v[148:151], v[188:191], v[110:113]
	v_mfma_f32_16x16x32_bf16 v[106:109], v[156:159], v[188:191], v[106:109]
	v_mfma_f32_16x16x32_bf16 v[94:97], v[148:151], v[196:199], v[94:97]
	v_mfma_f32_16x16x32_bf16 v[90:93], v[156:159], v[196:199], v[90:93]
	v_mfma_f32_16x16x32_bf16 v[78:81], v[148:151], v[204:207], v[78:81]
	v_mfma_f32_16x16x32_bf16 v[74:77], v[156:159], v[204:207], v[74:77]
	v_mfma_f32_16x16x32_bf16 v[118:121], v[160:163], v[176:179], v[118:121]
	v_mfma_f32_16x16x32_bf16 v[114:117], v[168:171], v[176:179], v[114:117]
	v_mfma_f32_16x16x32_bf16 v[102:105], v[160:163], v[184:187], v[102:105]
	v_mfma_f32_16x16x32_bf16 v[98:101], v[168:171], v[184:187], v[98:101]
	v_mfma_f32_16x16x32_bf16 v[86:89], v[160:163], v[192:195], v[86:89]
	v_mfma_f32_16x16x32_bf16 v[82:85], v[168:171], v[192:195], v[82:85]
	v_mfma_f32_16x16x32_bf16 v[70:73], v[160:163], v[200:203], v[70:73]
	v_mfma_f32_16x16x32_bf16 v[66:69], v[168:171], v[200:203], v[66:69]
	v_mfma_f32_16x16x32_bf16 v[118:121], v[164:167], v[180:183], v[118:121]
	v_mfma_f32_16x16x32_bf16 v[114:117], v[172:175], v[180:183], v[114:117]
	v_mfma_f32_16x16x32_bf16 v[102:105], v[164:167], v[188:191], v[102:105]
	v_mfma_f32_16x16x32_bf16 v[98:101], v[172:175], v[188:191], v[98:101]
	v_mfma_f32_16x16x32_bf16 v[86:89], v[164:167], v[196:199], v[86:89]
	v_mfma_f32_16x16x32_bf16 v[82:85], v[172:175], v[196:199], v[82:85]
	v_mfma_f32_16x16x32_bf16 v[70:73], v[164:167], v[204:207], v[70:73]
	v_mfma_f32_16x16x32_bf16 v[66:69], v[172:175], v[204:207], v[66:69]
	s_barrier
	s_setprio 0
	s_add_i32 s29, s29, s49
	v_lshl_add_u64 v[140:141], s[6:7], 0, v[0:1]
	s_mov_b32 m0, s29
	ds_read_b128 v[176:179], v147 offset:16384
	ds_read_b128 v[180:183], v147 offset:17408
	ds_read_b128 v[184:187], v147 offset:18432
	ds_read_b128 v[188:191], v147 offset:19456
	ds_read_b128 v[192:195], v147 offset:20480
	ds_read_b128 v[196:199], v147 offset:21504
	ds_read_b128 v[200:203], v147 offset:22528
	ds_read_b128 v[204:207], v147 offset:23552
	global_load_lds_dwordx4 v[140:141], off
	s_add_i32 m0, s29, 0x2000
	s_add_u32 s44, s6, 0x80000
	v_lshl_add_u64 v[208:209], s[6:7], 0, v[130:131]
	s_addc_u32 s45, s7, 0
	s_add_i32 s29, s31, s49
	global_load_lds_dwordx4 v[208:209], off
	v_lshl_add_u64 v[210:211], s[44:45], 0, v[0:1]
	s_mov_b32 m0, s29
	v_lshl_add_u64 v[212:213], s[36:37], 0, v[130:131]
	global_load_lds_dwordx4 v[210:211], off
	v_lshl_add_u64 v[210:211], s[44:45], 0, v[130:131]
	s_add_i32 m0, s29, 0x2000
	s_nop 0
	global_load_lds_dwordx4 v[210:211], off
	v_lshl_add_u64 v[210:211], s[36:37], 0, v[0:1]
	s_mov_b32 m0, s50
	s_nop 0
	global_load_lds_dwordx4 v[210:211], off
	s_mov_b32 m0, s51
	s_nop 0
	global_load_lds_dwordx4 v[212:213], off
	s_waitcnt vmcnt(8)
	s_waitcnt lgkmcnt(0)
	s_barrier
; #define PG8_STAGE(bufoff, gbase, voff) do { _Pragma("unroll") for (int _i = 0; _i < 2; ++_i) \
;         __builtin_amdgcn_global_load_lds((const unsigned*)((const char*)(gbase) + (voff)[_i]), (LAS unsigned*)(lds + (bufoff) + ldsw + _i * 8192), 16, 0, 0); } while (0)
; #define PG8_LDA(dst, b, h) do { _Pragma("unroll") for (int m = 0; m < 4; ++m) _Pragma("unroll") for (int k = 0; k < 2; ++k) dst[m][k] = *(const LAS bf16x8*)(lds + PG8_SA(b, h) + aoff + m * 2048 + k * 1024); } while (0)
; #define PG8_LDB(dst, b, h) do { _Pragma("unroll") for (int n = 0; n < 2; ++n) _Pragma("unroll") for (int k = 0; k < 2; ++k) dst[n][k] = *(const LAS bf16x8*)(lds + PG8_SB(b, h) + boff + n * 2048 + k * 1024); } while (0)
; #define PG8_MMA(ai, bj, At, Bt) do { __builtin_amdgcn_s_setprio(1); _Pragma("unroll") for (int m = 0; m < 4; ++m) _Pragma("unroll") for (int n = 0; n < 2; ++n) _Pragma("unroll") for (int k = 0; k < 2; ++k) \
;         acc[ai][bj][m][n] = __builtin_amdgcn_mfma_f32_16x16x32_bf16(Bt[n][k], At[m][k], acc[ai][bj][m][n], 0, 0, 0); __builtin_amdgcn_s_setprio(0); } while (0)
; #define PG8_WAIT_V(n) asm volatile("s_waitcnt vmcnt(" #n ")" ::: "memory")
; #define PG8_WAIT_L(n) asm volatile("s_waitcnt lgkmcnt(" #n ")" ::: "memory")
; #define PG8_BAR __builtin_amdgcn_s_barrier()
; #define PG8_SCHED __builtin_amdgcn_sched_barrier(0)
; template <class Epi, class Sched, bool ALIGN_EPI, bool LAST_FUSED = false, bool PERM = false, bool CARRY = false>
; __device__ __forceinline__ void gemm_phase(LAS unsigned char* lds, const int tid, const int K, const int lda, const int ldb, const Sched& S, const Epi& E) {
;     ...
;             PG8_WAIT_V(8); PG8_WAIT_L(0); PG8_BAR; PG8_MMA(1, 0, At, B0); PG8_MMA(1, 1, At, B1); PG8_BAR; PG8_SCHED;
;             PG8_LDB(B0, 1, 0); PG8_LDB(B1, 1, 1); PG8_SCHED; PG8_LDA(At, 1, 0); PG8_STAGE(PG8_SA(0, 1), a2 + hstepA, voffA);
;             PG8_WAIT_V(8); PG8_WAIT_L(0); PG8_BAR; PG8_MMA(0, 0, At, B0); PG8_MMA(0, 1, At, B1); PG8_BAR; PG8_SCHED;
	s_setprio 1
	v_mfma_f32_16x16x32_bf16 v[62:65], v[136:139], v[176:179], v[62:65]
	v_mfma_f32_16x16x32_bf16 v[58:61], v[152:155], v[176:179], v[58:61]
	v_mfma_f32_16x16x32_bf16 v[46:49], v[136:139], v[184:187], v[46:49]
	v_mfma_f32_16x16x32_bf16 v[42:45], v[152:155], v[184:187], v[42:45]
	v_mfma_f32_16x16x32_bf16 v[30:33], v[136:139], v[192:195], v[30:33]
	v_mfma_f32_16x16x32_bf16 v[26:29], v[152:155], v[192:195], v[26:29]
	v_mfma_f32_16x16x32_bf16 v[14:17], v[136:139], v[200:203], v[14:17]
	v_mfma_f32_16x16x32_bf16 v[10:13], v[152:155], v[200:203], v[10:13]
	v_mfma_f32_16x16x32_bf16 v[62:65], v[148:151], v[180:183], v[62:65]
	v_mfma_f32_16x16x32_bf16 v[58:61], v[156:159], v[180:183], v[58:61]
	v_mfma_f32_16x16x32_bf16 v[46:49], v[148:151], v[188:191], v[46:49]
	v_mfma_f32_16x16x32_bf16 v[42:45], v[156:159], v[188:191], v[42:45]
	v_mfma_f32_16x16x32_bf16 v[30:33], v[148:151], v[196:199], v[30:33]
	v_mfma_f32_16x16x32_bf16 v[26:29], v[156:159], v[196:199], v[26:29]
	v_mfma_f32_16x16x32_bf16 v[14:17], v[148:151], v[204:207], v[14:17]
	v_mfma_f32_16x16x32_bf16 v[10:13], v[156:159], v[204:207], v[10:13]
	v_mfma_f32_16x16x32_bf16 v[54:57], v[160:163], v[176:179], v[54:57]
	v_mfma_f32_16x16x32_bf16 v[50:53], v[168:171], v[176:179], v[50:53]
	v_mfma_f32_16x16x32_bf16 v[38:41], v[160:163], v[184:187], v[38:41]
	v_mfma_f32_16x16x32_bf16 v[34:37], v[168:171], v[184:187], v[34:37]
	v_mfma_f32_16x16x32_bf16 v[22:25], v[160:163], v[192:195], v[22:25]
	v_mfma_f32_16x16x32_bf16 v[18:21], v[168:171], v[192:195], v[18:21]
	v_mfma_f32_16x16x32_bf16 v[6:9], v[160:163], v[200:203], v[6:9]
	v_mfma_f32_16x16x32_bf16 v[2:5], v[168:171], v[200:203], v[2:5]
	v_mfma_f32_16x16x32_bf16 v[54:57], v[164:167], v[180:183], v[54:57]
	v_mfma_f32_16x16x32_bf16 v[50:53], v[172:175], v[180:183], v[50:53]
	v_mfma_f32_16x16x32_bf16 v[38:41], v[164:167], v[188:191], v[38:41]
	v_mfma_f32_16x16x32_bf16 v[34:37], v[172:175], v[188:191], v[34:37]
	v_mfma_f32_16x16x32_bf16 v[22:25], v[164:167], v[196:199], v[22:25]
	v_mfma_f32_16x16x32_bf16 v[18:21], v[172:175], v[196:199], v[18:21]
	v_mfma_f32_16x16x32_bf16 v[6:9], v[164:167], v[204:207], v[6:9]
	v_mfma_f32_16x16x32_bf16 v[2:5], v[172:175], v[204:207], v[2:5]
	s_barrier
	s_setprio 0
	s_add_i32 s29, 0, 0x18000
	s_add_i32 s31, 0, 0x1c000
	v_add_u32_e32 v156, s29, v146
	v_add_u32_e32 v172, s31, v146
	ds_read_b128 v[136:139], v156
	ds_read_b128 v[148:151], v156 offset:1024
	ds_read_b128 v[152:155], v156 offset:2048
	ds_read_b128 v[156:159], v156 offset:3072
	ds_read_b128 v[160:163], v172
	ds_read_b128 v[164:167], v172 offset:1024
	ds_read_b128 v[168:171], v172 offset:2048
	ds_read_b128 v[172:175], v172 offset:3072
	s_add_u32 s36, s36, 0x80000
	s_addc_u32 s37, s37, 0
	s_mov_b32 m0, s52
	v_lshl_add_u64 v[214:215], s[36:37], 0, v[0:1]
	ds_read_b128 v[176:179], v147 offset:32768
	ds_read_b128 v[180:183], v147 offset:33792
	ds_read_b128 v[184:187], v147 offset:34816
	ds_read_b128 v[188:191], v147 offset:35840
	ds_read_b128 v[192:195], v147 offset:36864
	ds_read_b128 v[196:199], v147 offset:37888
	ds_read_b128 v[200:203], v147 offset:38912
	ds_read_b128 v[204:207], v147 offset:39936
	global_load_lds_dwordx4 v[214:215], off
	v_lshl_add_u64 v[214:215], s[36:37], 0, v[130:131]
	s_mov_b32 m0, s53
	s_nop 0
	global_load_lds_dwordx4 v[214:215], off
	s_waitcnt vmcnt(8)
	s_waitcnt lgkmcnt(0)
	s_barrier
	s_setprio 1
	v_mfma_f32_16x16x32_bf16 v[126:129], v[136:139], v[176:179], v[126:129]
	v_mfma_f32_16x16x32_bf16 v[122:125], v[152:155], v[176:179], v[122:125]
	v_mfma_f32_16x16x32_bf16 v[110:113], v[136:139], v[184:187], v[110:113]
	v_mfma_f32_16x16x32_bf16 v[106:109], v[152:155], v[184:187], v[106:109]
	v_mfma_f32_16x16x32_bf16 v[94:97], v[136:139], v[192:195], v[94:97]
	v_mfma_f32_16x16x32_bf16 v[90:93], v[152:155], v[192:195], v[90:93]
	v_mfma_f32_16x16x32_bf16 v[78:81], v[136:139], v[200:203], v[78:81]
	v_mfma_f32_16x16x32_bf16 v[74:77], v[152:155], v[200:203], v[74:77]
	v_mfma_f32_16x16x32_bf16 v[126:129], v[148:151], v[180:183], v[126:129]
	v_mfma_f32_16x16x32_bf16 v[122:125], v[156:159], v[180:183], v[122:125]
	v_mfma_f32_16x16x32_bf16 v[110:113], v[148:151], v[188:191], v[110:113]
	v_mfma_f32_16x16x32_bf16 v[106:109], v[156:159], v[188:191], v[106:109]
	v_mfma_f32_16x16x32_bf16 v[94:97], v[148:151], v[196:199], v[94:97]
	v_mfma_f32_16x16x32_bf16 v[90:93], v[156:159], v[196:199], v[90:93]
	v_mfma_f32_16x16x32_bf16 v[78:81], v[148:151], v[204:207], v[78:81]
	v_mfma_f32_16x16x32_bf16 v[74:77], v[156:159], v[204:207], v[74:77]
	v_mfma_f32_16x16x32_bf16 v[118:121], v[160:163], v[176:179], v[118:121]
	v_mfma_f32_16x16x32_bf16 v[114:117], v[168:171], v[176:179], v[114:117]
	v_mfma_f32_16x16x32_bf16 v[102:105], v[160:163], v[184:187], v[102:105]
	v_mfma_f32_16x16x32_bf16 v[98:101], v[168:171], v[184:187], v[98:101]
	v_mfma_f32_16x16x32_bf16 v[86:89], v[160:163], v[192:195], v[86:89]
	v_mfma_f32_16x16x32_bf16 v[82:85], v[168:171], v[192:195], v[82:85]
	v_mfma_f32_16x16x32_bf16 v[70:73], v[160:163], v[200:203], v[70:73]
	v_mfma_f32_16x16x32_bf16 v[66:69], v[168:171], v[200:203], v[66:69]
	v_mfma_f32_16x16x32_bf16 v[118:121], v[164:167], v[180:183], v[118:121]
	v_mfma_f32_16x16x32_bf16 v[114:117], v[172:175], v[180:183], v[114:117]
	v_mfma_f32_16x16x32_bf16 v[102:105], v[164:167], v[188:191], v[102:105]
	v_mfma_f32_16x16x32_bf16 v[98:101], v[172:175], v[188:191], v[98:101]
	v_mfma_f32_16x16x32_bf16 v[86:89], v[164:167], v[196:199], v[86:89]
	v_mfma_f32_16x16x32_bf16 v[82:85], v[172:175], v[196:199], v[82:85]
	v_mfma_f32_16x16x32_bf16 v[70:73], v[164:167], v[204:207], v[70:73]
	v_mfma_f32_16x16x32_bf16 v[66:69], v[172:175], v[204:207], v[66:69]
	s_barrier
; #define PG8_STAGE(bufoff, gbase, voff) do { _Pragma("unroll") for (int _i = 0; _i < 2; ++_i) \
;         __builtin_amdgcn_global_load_lds((const unsigned*)((const char*)(gbase) + (voff)[_i]), (LAS unsigned*)(lds + (bufoff) + ldsw + _i * 8192), 16, 0, 0); } while (0)
; #define PG8_LDA(dst, b, h) do { _Pragma("unroll") for (int m = 0; m < 4; ++m) _Pragma("unroll") for (int k = 0; k < 2; ++k) dst[m][k] = *(const LAS bf16x8*)(lds + PG8_SA(b, h) + aoff + m * 2048 + k * 1024); } while (0)
; #define PG8_MMA(ai, bj, At, Bt) do { __builtin_amdgcn_s_setprio(1); _Pragma("unroll") for (int m = 0; m < 4; ++m) _Pragma("unroll") for (int n = 0; n < 2; ++n) _Pragma("unroll") for (int k = 0; k < 2; ++k) \
;         acc[ai][bj][m][n] = __builtin_amdgcn_mfma_f32_16x16x32_bf16(Bt[n][k], At[m][k], acc[ai][bj][m][n], 0, 0, 0); __builtin_amdgcn_s_setprio(0); } while (0)
; #define PG8_WAIT_V(n) asm volatile("s_waitcnt vmcnt(" #n ")" ::: "memory")
; #define PG8_WAIT_L(n) asm volatile("s_waitcnt lgkmcnt(" #n ")" ::: "memory")
; #define PG8_BAR __builtin_amdgcn_s_barrier()
; #define PG8_SCHED __builtin_amdgcn_sched_barrier(0)
; template <class Epi, class Sched, bool ALIGN_EPI, bool LAST_FUSED = false, bool PERM = false, bool CARRY = false>
; __device__ __forceinline__ void gemm_phase(LAS unsigned char* lds, const int tid, const int K, const int lda, const int ldb, const Sched& S, const Epi& E) {
;     ...
;             PG8_LDA(At, 1, 1); PG8_STAGE(PG8_SB(1, 0), b3, voffB); PG8_STAGE(PG8_SB(1, 1), b3 + hstepB, voffB); PG8_STAGE(PG8_SA(1, 0), a3, voffA);
;             PG8_WAIT_V(8); PG8_WAIT_L(0); PG8_BAR; PG8_MMA(1, 0, At, B0); PG8_MMA(1, 1, At, B1); PG8_BAR; PG8_SCHED;
;         }
;         if constexpr (ALIGN_EPI) { if (wr == 0) PG8_BAR; }
	s_setprio 0
	s_add_i32 s29, s29, s49
	v_lshl_add_u64 v[140:141], v[140:141], 0, s[68:69]
	s_mov_b32 m0, s29
	ds_read_b128 v[176:179], v147 offset:49152
	ds_read_b128 v[180:183], v147 offset:50176
	ds_read_b128 v[184:187], v147 offset:51200
	ds_read_b128 v[188:191], v147 offset:52224
	ds_read_b128 v[192:195], v147 offset:53248
	ds_read_b128 v[196:199], v147 offset:54272
	ds_read_b128 v[200:203], v147 offset:55296
	ds_read_b128 v[204:207], v147 offset:56320
	global_load_lds_dwordx4 v[140:141], off
	s_add_i32 m0, s29, 0x2000
	s_add_u32 s6, s6, 0x80080
	v_lshl_add_u64 v[140:141], v[208:209], 0, s[68:69]
	s_addc_u32 s7, s7, 0
	s_add_i32 s29, s31, s49
	global_load_lds_dwordx4 v[140:141], off
	v_lshl_add_u64 v[140:141], s[6:7], 0, v[0:1]
	s_mov_b32 m0, s29
	s_nop 0
	global_load_lds_dwordx4 v[140:141], off
	v_lshl_add_u64 v[140:141], s[6:7], 0, v[130:131]
	s_add_i32 m0, s29, 0x2000
	s_nop 0
	global_load_lds_dwordx4 v[140:141], off
	v_lshl_add_u64 v[140:141], v[210:211], 0, s[68:69]
	s_mov_b32 m0, s55
	s_nop 0
	global_load_lds_dwordx4 v[140:141], off
	v_lshl_add_u64 v[140:141], v[212:213], 0, s[68:69]
	s_mov_b32 m0, s56
	s_nop 0
	global_load_lds_dwordx4 v[140:141], off
	s_waitcnt vmcnt(8)
	s_waitcnt lgkmcnt(0)
	s_barrier
	s_setprio 1
	v_mfma_f32_16x16x32_bf16 v[62:65], v[136:139], v[176:179], v[62:65]
	v_mfma_f32_16x16x32_bf16 v[58:61], v[152:155], v[176:179], v[58:61]
	v_mfma_f32_16x16x32_bf16 v[46:49], v[136:139], v[184:187], v[46:49]
	v_mfma_f32_16x16x32_bf16 v[42:45], v[152:155], v[184:187], v[42:45]
	v_mfma_f32_16x16x32_bf16 v[30:33], v[136:139], v[192:195], v[30:33]
	v_mfma_f32_16x16x32_bf16 v[26:29], v[152:155], v[192:195], v[26:29]
	v_mfma_f32_16x16x32_bf16 v[14:17], v[136:139], v[200:203], v[14:17]
	v_mfma_f32_16x16x32_bf16 v[10:13], v[152:155], v[200:203], v[10:13]
	v_mfma_f32_16x16x32_bf16 v[62:65], v[148:151], v[180:183], v[62:65]
	v_mfma_f32_16x16x32_bf16 v[58:61], v[156:159], v[180:183], v[58:61]
	v_mfma_f32_16x16x32_bf16 v[46:49], v[148:151], v[188:191], v[46:49]
	v_mfma_f32_16x16x32_bf16 v[42:45], v[156:159], v[188:191], v[42:45]
	v_mfma_f32_16x16x32_bf16 v[30:33], v[148:151], v[196:199], v[30:33]
	v_mfma_f32_16x16x32_bf16 v[26:29], v[156:159], v[196:199], v[26:29]
	v_mfma_f32_16x16x32_bf16 v[14:17], v[148:151], v[204:207], v[14:17]
	v_mfma_f32_16x16x32_bf16 v[10:13], v[156:159], v[204:207], v[10:13]
	v_mfma_f32_16x16x32_bf16 v[54:57], v[160:163], v[176:179], v[54:57]
	v_mfma_f32_16x16x32_bf16 v[50:53], v[168:171], v[176:179], v[50:53]
	v_mfma_f32_16x16x32_bf16 v[38:41], v[160:163], v[184:187], v[38:41]
	v_mfma_f32_16x16x32_bf16 v[34:37], v[168:171], v[184:187], v[34:37]
	v_mfma_f32_16x16x32_bf16 v[22:25], v[160:163], v[192:195], v[22:25]
	v_mfma_f32_16x16x32_bf16 v[18:21], v[168:171], v[192:195], v[18:21]
	v_mfma_f32_16x16x32_bf16 v[6:9], v[160:163], v[200:203], v[6:9]
	v_mfma_f32_16x16x32_bf16 v[2:5], v[168:171], v[200:203], v[2:5]
	v_mfma_f32_16x16x32_bf16 v[54:57], v[164:167], v[180:183], v[54:57]
	v_mfma_f32_16x16x32_bf16 v[50:53], v[172:175], v[180:183], v[50:53]
	v_mfma_f32_16x16x32_bf16 v[38:41], v[164:167], v[188:191], v[38:41]
	v_mfma_f32_16x16x32_bf16 v[34:37], v[172:175], v[188:191], v[34:37]
	v_mfma_f32_16x16x32_bf16 v[22:25], v[164:167], v[196:199], v[22:25]
	v_mfma_f32_16x16x32_bf16 v[18:21], v[172:175], v[196:199], v[18:21]
	v_mfma_f32_16x16x32_bf16 v[6:9], v[164:167], v[204:207], v[6:9]
	v_mfma_f32_16x16x32_bf16 v[2:5], v[172:175], v[204:207], v[2:5]
	s_barrier
	s_setprio 0
	s_add_i32 s28, s28, 2
	s_add_u32 s4, s4, 0x100
	s_addc_u32 s5, s5, 0
	s_add_u32 s22, s22, 0x100
	s_addc_u32 s23, s23, 0
	s_cmp_gt_u32 s28, 29
	s_cbranch_scc0 .LBB0_838
	s_and_b64 vcc, exec, s[26:27]
	s_cbranch_vccz .LBB0_841
	s_barrier

; #define PG8_STAGE(bufoff, gbase, voff) do { _Pragma("unroll") for (int _i = 0; _i < 2; ++_i) \
;         __builtin_amdgcn_global_load_lds((const unsigned*)((const char*)(gbase) + (voff)[_i]), (LAS unsigned*)(lds + (bufoff) + ldsw + _i * 8192), 16, 0, 0); } while (0)
; #define PG8_LDA(dst, b, h) do { _Pragma("unroll") for (int m = 0; m < 4; ++m) _Pragma("unroll") for (int k = 0; k < 2; ++k) dst[m][k] = *(const LAS bf16x8*)(lds + PG8_SA(b, h) + aoff + m * 2048 + k * 1024); } while (0)
; #define PG8_LDB(dst, b, h) do { _Pragma("unroll") for (int n = 0; n < 2; ++n) _Pragma("unroll") for (int k = 0; k < 2; ++k) dst[n][k] = *(const LAS bf16x8*)(lds + PG8_SB(b, h) + boff + n * 2048 + k * 1024); } while (0)
; #define PG8_WAIT_V(n) asm volatile("s_waitcnt vmcnt(" #n ")" ::: "memory")
; #define PG8_WAIT_L(n) asm volatile("s_waitcnt lgkmcnt(" #n ")" ::: "memory")
; #define PG8_BAR __builtin_amdgcn_s_barrier()
; #define PG8_SCHED __builtin_amdgcn_sched_barrier(0)
; template <class Epi, class Sched, bool ALIGN_EPI, bool LAST_FUSED = false, bool PERM = false, bool CARRY = false>
; __device__ __forceinline__ void gemm_phase(LAS unsigned char* lds, const int tid, const int K, const int lda, const int ldb, const Sched& S, const Epi& E) {
;     ...
;         const bool has_next = S.next(KD_IDX(ui + 1), nxt);
;         const char* nA = has_next ? nxt.a : cA; const char* nB = has_next ? nxt.b : cB; const int nt = cur.nt;
; #pragma unroll 1
;         for (int t = 0; t < nt; t += 2) {
;             const bool last = (t == nt - 2);
;             const char* a1 = cA + (size_t)(t + 1) * kstep;
;             const char* a2 = last ? nA : cA + (size_t)(t + 2) * kstep; const char* b2 = last ? nB : cB + (size_t)(t + 2) * kstep;
;             const char* a3 = a2 + kstep; const char* b3 = b2 + kstep;
;             PG8_LDB(B0, 0, 0); PG8_LDB(B1, 0, 1); PG8_SCHED; PG8_LDA(At, 0, 0); PG8_STAGE(PG8_SA(1, 1), a1 + hstepA, voffA);
;             PG8_WAIT_V(8); PG8_WAIT_L(0); PG8_BAR; PG8_MMA(0, 0, At, B0); PG8_MMA(0, 1, At, B1); PG8_BAR; PG8_SCHED;
;             PG8_LDA(At, 0, 1); PG8_STAGE(PG8_SB(0, 0), b2, voffB); PG8_STAGE(PG8_SB(0, 1), b2 + hstepB, voffB); PG8_STAGE(PG8_SA(0, 0), a2, voffA);
;             PG8_WAIT_V(8); PG8_WAIT_L(0); PG8_BAR; PG8_MMA(1, 0, At, B0); PG8_MMA(1, 1, At, B1); PG8_BAR; PG8_SCHED;
.LBB0_1077:
	s_add_u32 s23, s26, 0xfff80080
	s_addc_u32 s28, s27, -1
	s_add_i32 s29, 0, 0x10000
	s_cmp_eq_u32 s15, 28
	s_cselect_b32 s37, s17, s28
	s_cselect_b32 s36, s16, s23
	s_cselect_b32 s31, s19, s13
	s_cselect_b32 s30, s18, s5
	s_add_i32 s23, 0, 0x14000
	v_add_u32_e32 v152, s29, v142
	v_add_u32_e32 v168, s23, v142
	ds_read_b128 v[136:139], v152
	ds_read_b128 v[144:147], v152 offset:1024
	ds_read_b128 v[148:151], v152 offset:2048
	ds_read_b128 v[152:155], v152 offset:3072
	ds_read_b128 v[156:159], v168
	ds_read_b128 v[160:163], v168 offset:1024
	ds_read_b128 v[164:167], v168 offset:2048
	ds_read_b128 v[168:171], v168 offset:3072
	v_lshl_add_u64 v[204:205], s[26:27], 0, v[132:133]
	s_add_i32 m0, s46, 0xc000
	ds_read_b128 v[172:175], v143
	ds_read_b128 v[176:179], v143 offset:1024
	ds_read_b128 v[180:183], v143 offset:2048
	ds_read_b128 v[184:187], v143 offset:3072
	ds_read_b128 v[188:191], v143 offset:4096
	ds_read_b128 v[192:195], v143 offset:5120
	ds_read_b128 v[196:199], v143 offset:6144
	ds_read_b128 v[200:203], v143 offset:7168
	global_load_lds_dwordx4 v[204:205], off
	v_lshl_add_u64 v[204:205], s[26:27], 0, v[134:135]
	s_add_i32 m0, s46, 0xe000
	s_nop 0
	global_load_lds_dwordx4 v[204:205], off
	s_waitcnt vmcnt(8)
	s_waitcnt lgkmcnt(0)
	s_barrier
	s_setprio 1
	v_mfma_f32_16x16x32_bf16 v[126:129], v[136:139], v[172:175], v[126:129]
	v_mfma_f32_16x16x32_bf16 v[122:125], v[148:151], v[172:175], v[122:125]
	v_mfma_f32_16x16x32_bf16 v[110:113], v[136:139], v[180:183], v[110:113]
	v_mfma_f32_16x16x32_bf16 v[106:109], v[148:151], v[180:183], v[106:109]
	v_mfma_f32_16x16x32_bf16 v[94:97], v[136:139], v[188:191], v[94:97]
	v_mfma_f32_16x16x32_bf16 v[90:93], v[148:151], v[188:191], v[90:93]
	v_mfma_f32_16x16x32_bf16 v[78:81], v[136:139], v[196:199], v[78:81]
	v_mfma_f32_16x16x32_bf16 v[74:77], v[148:151], v[196:199], v[74:77]
	v_mfma_f32_16x16x32_bf16 v[126:129], v[144:147], v[176:179], v[126:129]
	v_mfma_f32_16x16x32_bf16 v[122:125], v[152:155], v[176:179], v[122:125]
	v_mfma_f32_16x16x32_bf16 v[110:113], v[144:147], v[184:187], v[110:113]
	v_mfma_f32_16x16x32_bf16 v[106:109], v[152:155], v[184:187], v[106:109]
	v_mfma_f32_16x16x32_bf16 v[94:97], v[144:147], v[192:195], v[94:97]
	v_mfma_f32_16x16x32_bf16 v[90:93], v[152:155], v[192:195], v[90:93]
	v_mfma_f32_16x16x32_bf16 v[78:81], v[144:147], v[200:203], v[78:81]
	v_mfma_f32_16x16x32_bf16 v[74:77], v[152:155], v[200:203], v[74:77]
	v_mfma_f32_16x16x32_bf16 v[118:121], v[156:159], v[172:175], v[118:121]
	v_mfma_f32_16x16x32_bf16 v[114:117], v[164:167], v[172:175], v[114:117]
	v_mfma_f32_16x16x32_bf16 v[102:105], v[156:159], v[180:183], v[102:105]
	v_mfma_f32_16x16x32_bf16 v[98:101], v[164:167], v[180:183], v[98:101]
	v_mfma_f32_16x16x32_bf16 v[86:89], v[156:159], v[188:191], v[86:89]
	v_mfma_f32_16x16x32_bf16 v[82:85], v[164:167], v[188:191], v[82:85]
	v_mfma_f32_16x16x32_bf16 v[70:73], v[156:159], v[196:199], v[70:73]
	v_mfma_f32_16x16x32_bf16 v[66:69], v[164:167], v[196:199], v[66:69]
	v_mfma_f32_16x16x32_bf16 v[118:121], v[160:163], v[176:179], v[118:121]
	v_mfma_f32_16x16x32_bf16 v[114:117], v[168:171], v[176:179], v[114:117]
	v_mfma_f32_16x16x32_bf16 v[102:105], v[160:163], v[184:187], v[102:105]
	v_mfma_f32_16x16x32_bf16 v[98:101], v[168:171], v[184:187], v[98:101]
	v_mfma_f32_16x16x32_bf16 v[86:89], v[160:163], v[192:195], v[86:89]
	v_mfma_f32_16x16x32_bf16 v[82:85], v[168:171], v[192:195], v[82:85]
	v_mfma_f32_16x16x32_bf16 v[70:73], v[160:163], v[200:203], v[70:73]
	v_mfma_f32_16x16x32_bf16 v[66:69], v[168:171], v[200:203], v[66:69]
	s_barrier
	s_setprio 0
	s_add_i32 s28, s29, s43
	v_lshl_add_u64 v[204:205], s[30:31], 0, v[0:1]
	s_mov_b32 m0, s28
	ds_read_b128 v[172:175], v143 offset:16384
	ds_read_b128 v[176:179], v143 offset:17408
	ds_read_b128 v[180:183], v143 offset:18432
	ds_read_b128 v[184:187], v143 offset:19456
	ds_read_b128 v[188:191], v143 offset:20480
	ds_read_b128 v[192:195], v143 offset:21504
	ds_read_b128 v[196:199], v143 offset:22528
	ds_read_b128 v[200:203], v143 offset:23552
	global_load_lds_dwordx4 v[204:205], off
	s_add_i32 m0, s28, 0x2000
	s_add_u32 s28, s30, 0x80000
	v_lshl_add_u64 v[206:207], s[30:31], 0, v[130:131]
	s_addc_u32 s29, s31, 0
	s_add_i32 s23, s23, s43
	global_load_lds_dwordx4 v[206:207], off
	v_lshl_add_u64 v[208:209], s[28:29], 0, v[0:1]
	s_mov_b32 m0, s23
	v_lshl_add_u64 v[210:211], s[36:37], 0, v[130:131]
	global_load_lds_dwordx4 v[208:209], off
	v_lshl_add_u64 v[208:209], s[28:29], 0, v[130:131]
	s_add_i32 m0, s23, 0x2000
	s_nop 0
	global_load_lds_dwordx4 v[208:209], off
	v_lshl_add_u64 v[208:209], s[36:37], 0, v[0:1]
	s_mov_b32 m0, s46
	s_nop 0
	global_load_lds_dwordx4 v[208:209], off
	s_mov_b32 m0, s47
	s_nop 0
	global_load_lds_dwordx4 v[210:211], off
	s_waitcnt vmcnt(8)
	s_waitcnt lgkmcnt(0)
	s_barrier
; #define PG8_STAGE(bufoff, gbase, voff) do { _Pragma("unroll") for (int _i = 0; _i < 2; ++_i) \
;         __builtin_amdgcn_global_load_lds((const unsigned*)((const char*)(gbase) + (voff)[_i]), (LAS unsigned*)(lds + (bufoff) + ldsw + _i * 8192), 16, 0, 0); } while (0)
; #define PG8_LDA(dst, b, h) do { _Pragma("unroll") for (int m = 0; m < 4; ++m) _Pragma("unroll") for (int k = 0; k < 2; ++k) dst[m][k] = *(const LAS bf16x8*)(lds + PG8_SA(b, h) + aoff + m * 2048 + k * 1024); } while (0)
; #define PG8_LDB(dst, b, h) do { _Pragma("unroll") for (int n = 0; n < 2; ++n) _Pragma("unroll") for (int k = 0; k < 2; ++k) dst[n][k] = *(const LAS bf16x8*)(lds + PG8_SB(b, h) + boff + n * 2048 + k * 1024); } while (0)
; #define PG8_MMA(ai, bj, At, Bt) do { __builtin_amdgcn_s_setprio(1); _Pragma("unroll") for (int m = 0; m < 4; ++m) _Pragma("unroll") for (int n = 0; n < 2; ++n) _Pragma("unroll") for (int k = 0; k < 2; ++k) \
;         acc[ai][bj][m][n] = __builtin_amdgcn_mfma_f32_16x16x32_bf16(Bt[n][k], At[m][k], acc[ai][bj][m][n], 0, 0, 0); __builtin_amdgcn_s_setprio(0); } while (0)
; #define PG8_WAIT_V(n) asm volatile("s_waitcnt vmcnt(" #n ")" ::: "memory")
; #define PG8_WAIT_L(n) asm volatile("s_waitcnt lgkmcnt(" #n ")" ::: "memory")
; #define PG8_BAR __builtin_amdgcn_s_barrier()
; #define PG8_SCHED __builtin_amdgcn_sched_barrier(0)
; template <class Epi, class Sched, bool ALIGN_EPI, bool LAST_FUSED = false, bool PERM = false, bool CARRY = false>
; __device__ __forceinline__ void gemm_phase(LAS unsigned char* lds, const int tid, const int K, const int lda, const int ldb, const Sched& S, const Epi& E) {
;     ...
;             PG8_WAIT_V(8); PG8_WAIT_L(0); PG8_BAR; PG8_MMA(1, 0, At, B0); PG8_MMA(1, 1, At, B1); PG8_BAR; PG8_SCHED;
;             PG8_LDB(B0, 1, 0); PG8_LDB(B1, 1, 1); PG8_SCHED; PG8_LDA(At, 1, 0); PG8_STAGE(PG8_SA(0, 1), a2 + hstepA, voffA);
;             PG8_WAIT_V(8); PG8_WAIT_L(0); PG8_BAR; PG8_MMA(0, 0, At, B0); PG8_MMA(0, 1, At, B1); PG8_BAR; PG8_SCHED;
	s_setprio 1
	v_mfma_f32_16x16x32_bf16 v[62:65], v[136:139], v[172:175], v[62:65]
	v_mfma_f32_16x16x32_bf16 v[58:61], v[148:151], v[172:175], v[58:61]
	v_mfma_f32_16x16x32_bf16 v[46:49], v[136:139], v[180:183], v[46:49]
	v_mfma_f32_16x16x32_bf16 v[42:45], v[148:151], v[180:183], v[42:45]
	v_mfma_f32_16x16x32_bf16 v[30:33], v[136:139], v[188:191], v[30:33]
	v_mfma_f32_16x16x32_bf16 v[26:29], v[148:151], v[188:191], v[26:29]
	v_mfma_f32_16x16x32_bf16 v[14:17], v[136:139], v[196:199], v[14:17]
	v_mfma_f32_16x16x32_bf16 v[10:13], v[148:151], v[196:199], v[10:13]
	v_mfma_f32_16x16x32_bf16 v[62:65], v[144:147], v[176:179], v[62:65]
	v_mfma_f32_16x16x32_bf16 v[58:61], v[152:155], v[176:179], v[58:61]
	v_mfma_f32_16x16x32_bf16 v[46:49], v[144:147], v[184:187], v[46:49]
	v_mfma_f32_16x16x32_bf16 v[42:45], v[152:155], v[184:187], v[42:45]
	v_mfma_f32_16x16x32_bf16 v[30:33], v[144:147], v[192:195], v[30:33]
	v_mfma_f32_16x16x32_bf16 v[26:29], v[152:155], v[192:195], v[26:29]
	v_mfma_f32_16x16x32_bf16 v[14:17], v[144:147], v[200:203], v[14:17]
	v_mfma_f32_16x16x32_bf16 v[10:13], v[152:155], v[200:203], v[10:13]
	v_mfma_f32_16x16x32_bf16 v[54:57], v[156:159], v[172:175], v[54:57]
	v_mfma_f32_16x16x32_bf16 v[50:53], v[164:167], v[172:175], v[50:53]
	v_mfma_f32_16x16x32_bf16 v[38:41], v[156:159], v[180:183], v[38:41]
	v_mfma_f32_16x16x32_bf16 v[34:37], v[164:167], v[180:183], v[34:37]
	v_mfma_f32_16x16x32_bf16 v[22:25], v[156:159], v[188:191], v[22:25]
	v_mfma_f32_16x16x32_bf16 v[18:21], v[164:167], v[188:191], v[18:21]
	v_mfma_f32_16x16x32_bf16 v[6:9], v[156:159], v[196:199], v[6:9]
	v_mfma_f32_16x16x32_bf16 v[2:5], v[164:167], v[196:199], v[2:5]
	v_mfma_f32_16x16x32_bf16 v[54:57], v[160:163], v[176:179], v[54:57]
	v_mfma_f32_16x16x32_bf16 v[50:53], v[168:171], v[176:179], v[50:53]
	v_mfma_f32_16x16x32_bf16 v[38:41], v[160:163], v[184:187], v[38:41]
	v_mfma_f32_16x16x32_bf16 v[34:37], v[168:171], v[184:187], v[34:37]
	v_mfma_f32_16x16x32_bf16 v[22:25], v[160:163], v[192:195], v[22:25]
	v_mfma_f32_16x16x32_bf16 v[18:21], v[168:171], v[192:195], v[18:21]
	v_mfma_f32_16x16x32_bf16 v[6:9], v[160:163], v[200:203], v[6:9]
	v_mfma_f32_16x16x32_bf16 v[2:5], v[168:171], v[200:203], v[2:5]
	s_barrier
	s_setprio 0
	s_add_i32 s23, 0, 0x18000
	s_add_i32 s35, 0, 0x1c000
	v_add_u32_e32 v152, s23, v142
	v_add_u32_e32 v168, s35, v142
	ds_read_b128 v[136:139], v152
	ds_read_b128 v[144:147], v152 offset:1024
	ds_read_b128 v[148:151], v152 offset:2048
	ds_read_b128 v[152:155], v152 offset:3072
	ds_read_b128 v[156:159], v168
	ds_read_b128 v[160:163], v168 offset:1024
	ds_read_b128 v[164:167], v168 offset:2048
	ds_read_b128 v[168:171], v168 offset:3072
	s_add_u32 s28, s36, 0x80000
	s_addc_u32 s29, s37, 0
	s_mov_b32 m0, s48
	v_lshl_add_u64 v[212:213], s[28:29], 0, v[0:1]
	ds_read_b128 v[172:175], v143 offset:32768
	ds_read_b128 v[176:179], v143 offset:33792
	ds_read_b128 v[180:183], v143 offset:34816
	ds_read_b128 v[184:187], v143 offset:35840
	ds_read_b128 v[188:191], v143 offset:36864
	ds_read_b128 v[192:195], v143 offset:37888
	ds_read_b128 v[196:199], v143 offset:38912
	ds_read_b128 v[200:203], v143 offset:39936
	global_load_lds_dwordx4 v[212:213], off
	v_lshl_add_u64 v[212:213], s[28:29], 0, v[130:131]
	s_mov_b32 m0, s49
	s_nop 0
	global_load_lds_dwordx4 v[212:213], off
	s_waitcnt vmcnt(8)
	s_waitcnt lgkmcnt(0)
	s_barrier
	s_setprio 1
	v_mfma_f32_16x16x32_bf16 v[126:129], v[136:139], v[172:175], v[126:129]
	v_mfma_f32_16x16x32_bf16 v[122:125], v[148:151], v[172:175], v[122:125]
	v_mfma_f32_16x16x32_bf16 v[110:113], v[136:139], v[180:183], v[110:113]
	v_mfma_f32_16x16x32_bf16 v[106:109], v[148:151], v[180:183], v[106:109]
	v_mfma_f32_16x16x32_bf16 v[94:97], v[136:139], v[188:191], v[94:97]
	v_mfma_f32_16x16x32_bf16 v[90:93], v[148:151], v[188:191], v[90:93]
	v_mfma_f32_16x16x32_bf16 v[78:81], v[136:139], v[196:199], v[78:81]
	v_mfma_f32_16x16x32_bf16 v[74:77], v[148:151], v[196:199], v[74:77]
	v_mfma_f32_16x16x32_bf16 v[126:129], v[144:147], v[176:179], v[126:129]
	v_mfma_f32_16x16x32_bf16 v[122:125], v[152:155], v[176:179], v[122:125]
	v_mfma_f32_16x16x32_bf16 v[110:113], v[144:147], v[184:187], v[110:113]
	v_mfma_f32_16x16x32_bf16 v[106:109], v[152:155], v[184:187], v[106:109]
	v_mfma_f32_16x16x32_bf16 v[94:97], v[144:147], v[192:195], v[94:97]
	v_mfma_f32_16x16x32_bf16 v[90:93], v[152:155], v[192:195], v[90:93]
	v_mfma_f32_16x16x32_bf16 v[78:81], v[144:147], v[200:203], v[78:81]
	v_mfma_f32_16x16x32_bf16 v[74:77], v[152:155], v[200:203], v[74:77]
	v_mfma_f32_16x16x32_bf16 v[118:121], v[156:159], v[172:175], v[118:121]
	v_mfma_f32_16x16x32_bf16 v[114:117], v[164:167], v[172:175], v[114:117]
	v_mfma_f32_16x16x32_bf16 v[102:105], v[156:159], v[180:183], v[102:105]
	v_mfma_f32_16x16x32_bf16 v[98:101], v[164:167], v[180:183], v[98:101]
	v_mfma_f32_16x16x32_bf16 v[86:89], v[156:159], v[188:191], v[86:89]
	v_mfma_f32_16x16x32_bf16 v[82:85], v[164:167], v[188:191], v[82:85]
	v_mfma_f32_16x16x32_bf16 v[70:73], v[156:159], v[196:199], v[70:73]
	v_mfma_f32_16x16x32_bf16 v[66:69], v[164:167], v[196:199], v[66:69]
	v_mfma_f32_16x16x32_bf16 v[118:121], v[160:163], v[176:179], v[118:121]
	v_mfma_f32_16x16x32_bf16 v[114:117], v[168:171], v[176:179], v[114:117]
	v_mfma_f32_16x16x32_bf16 v[102:105], v[160:163], v[184:187], v[102:105]
	v_mfma_f32_16x16x32_bf16 v[98:101], v[168:171], v[184:187], v[98:101]
	v_mfma_f32_16x16x32_bf16 v[86:89], v[160:163], v[192:195], v[86:89]
	v_mfma_f32_16x16x32_bf16 v[82:85], v[168:171], v[192:195], v[82:85]
	v_mfma_f32_16x16x32_bf16 v[70:73], v[160:163], v[200:203], v[70:73]
	v_mfma_f32_16x16x32_bf16 v[66:69], v[168:171], v[200:203], v[66:69]
	s_barrier
; #define PG8_STAGE(bufoff, gbase, voff) do { _Pragma("unroll") for (int _i = 0; _i < 2; ++_i) \
;         __builtin_amdgcn_global_load_lds((const unsigned*)((const char*)(gbase) + (voff)[_i]), (LAS unsigned*)(lds + (bufoff) + ldsw + _i * 8192), 16, 0, 0); } while (0)
; #define PG8_LDA(dst, b, h) do { _Pragma("unroll") for (int m = 0; m < 4; ++m) _Pragma("unroll") for (int k = 0; k < 2; ++k) dst[m][k] = *(const LAS bf16x8*)(lds + PG8_SA(b, h) + aoff + m * 2048 + k * 1024); } while (0)
; #define PG8_MMA(ai, bj, At, Bt) do { __builtin_amdgcn_s_setprio(1); _Pragma("unroll") for (int m = 0; m < 4; ++m) _Pragma("unroll") for (int n = 0; n < 2; ++n) _Pragma("unroll") for (int k = 0; k < 2; ++k) \
;         acc[ai][bj][m][n] = __builtin_amdgcn_mfma_f32_16x16x32_bf16(Bt[n][k], At[m][k], acc[ai][bj][m][n], 0, 0, 0); __builtin_amdgcn_s_setprio(0); } while (0)
; #define PG8_WAIT_V(n) asm volatile("s_waitcnt vmcnt(" #n ")" ::: "memory")
; #define PG8_WAIT_L(n) asm volatile("s_waitcnt lgkmcnt(" #n ")" ::: "memory")
; #define PG8_BAR __builtin_amdgcn_s_barrier()
; #define PG8_SCHED __builtin_amdgcn_sched_barrier(0)
; template <class Epi, class Sched, bool ALIGN_EPI, bool LAST_FUSED = false, bool PERM = false, bool CARRY = false>
; __device__ __forceinline__ void gemm_phase(LAS unsigned char* lds, const int tid, const int K, const int lda, const int ldb, const Sched& S, const Epi& E) {
;     ...
;             PG8_LDA(At, 1, 1); PG8_STAGE(PG8_SB(1, 0), b3, voffB); PG8_STAGE(PG8_SB(1, 1), b3 + hstepB, voffB); PG8_STAGE(PG8_SA(1, 0), a3, voffA);
;             PG8_WAIT_V(8); PG8_WAIT_L(0); PG8_BAR; PG8_MMA(1, 0, At, B0); PG8_MMA(1, 1, At, B1); PG8_BAR; PG8_SCHED;
;         }
;         if constexpr (ALIGN_EPI) { if (wr == 0) PG8_BAR; }
	s_setprio 0
	s_add_i32 s23, s23, s43
	v_lshl_add_u64 v[204:205], v[204:205], 0, s[68:69]
	s_mov_b32 m0, s23
	ds_read_b128 v[172:175], v143 offset:49152
	ds_read_b128 v[176:179], v143 offset:50176
	ds_read_b128 v[180:183], v143 offset:51200
	ds_read_b128 v[184:187], v143 offset:52224
	ds_read_b128 v[188:191], v143 offset:53248
	ds_read_b128 v[192:195], v143 offset:54272
	ds_read_b128 v[196:199], v143 offset:55296
	ds_read_b128 v[200:203], v143 offset:56320
	global_load_lds_dwordx4 v[204:205], off
	s_add_i32 m0, s23, 0x2000
	s_add_u32 s28, s30, 0x80080
	v_lshl_add_u64 v[204:205], v[206:207], 0, s[68:69]
	s_addc_u32 s29, s31, 0
	s_add_i32 s23, s35, s43
	global_load_lds_dwordx4 v[204:205], off
	v_lshl_add_u64 v[204:205], s[28:29], 0, v[0:1]
	s_mov_b32 m0, s23
	s_nop 0
	global_load_lds_dwordx4 v[204:205], off
	v_lshl_add_u64 v[204:205], s[28:29], 0, v[130:131]
	s_add_i32 m0, s23, 0x2000
	s_nop 0
	global_load_lds_dwordx4 v[204:205], off
	v_lshl_add_u64 v[204:205], v[208:209], 0, s[68:69]
	s_mov_b32 m0, s51
	s_nop 0
	global_load_lds_dwordx4 v[204:205], off
	v_lshl_add_u64 v[204:205], v[210:211], 0, s[68:69]
	s_mov_b32 m0, s52
	s_nop 0
	global_load_lds_dwordx4 v[204:205], off
	s_waitcnt vmcnt(8)
	s_waitcnt lgkmcnt(0)
	s_barrier
	s_setprio 1
	v_mfma_f32_16x16x32_bf16 v[62:65], v[136:139], v[172:175], v[62:65]
	v_mfma_f32_16x16x32_bf16 v[58:61], v[148:151], v[172:175], v[58:61]
	v_mfma_f32_16x16x32_bf16 v[46:49], v[136:139], v[180:183], v[46:49]
	v_mfma_f32_16x16x32_bf16 v[42:45], v[148:151], v[180:183], v[42:45]
	v_mfma_f32_16x16x32_bf16 v[30:33], v[136:139], v[188:191], v[30:33]
	v_mfma_f32_16x16x32_bf16 v[26:29], v[148:151], v[188:191], v[26:29]
	v_mfma_f32_16x16x32_bf16 v[14:17], v[136:139], v[196:199], v[14:17]
	v_mfma_f32_16x16x32_bf16 v[10:13], v[148:151], v[196:199], v[10:13]
	v_mfma_f32_16x16x32_bf16 v[62:65], v[144:147], v[176:179], v[62:65]
	v_mfma_f32_16x16x32_bf16 v[58:61], v[152:155], v[176:179], v[58:61]
	v_mfma_f32_16x16x32_bf16 v[46:49], v[144:147], v[184:187], v[46:49]
	v_mfma_f32_16x16x32_bf16 v[42:45], v[152:155], v[184:187], v[42:45]
	v_mfma_f32_16x16x32_bf16 v[30:33], v[144:147], v[192:195], v[30:33]
	v_mfma_f32_16x16x32_bf16 v[26:29], v[152:155], v[192:195], v[26:29]
	v_mfma_f32_16x16x32_bf16 v[14:17], v[144:147], v[200:203], v[14:17]
	v_mfma_f32_16x16x32_bf16 v[10:13], v[152:155], v[200:203], v[10:13]
	v_mfma_f32_16x16x32_bf16 v[54:57], v[156:159], v[172:175], v[54:57]
	v_mfma_f32_16x16x32_bf16 v[50:53], v[164:167], v[172:175], v[50:53]
	v_mfma_f32_16x16x32_bf16 v[38:41], v[156:159], v[180:183], v[38:41]
	v_mfma_f32_16x16x32_bf16 v[34:37], v[164:167], v[180:183], v[34:37]
	v_mfma_f32_16x16x32_bf16 v[22:25], v[156:159], v[188:191], v[22:25]
	v_mfma_f32_16x16x32_bf16 v[18:21], v[164:167], v[188:191], v[18:21]
	v_mfma_f32_16x16x32_bf16 v[6:9], v[156:159], v[196:199], v[6:9]
	v_mfma_f32_16x16x32_bf16 v[2:5], v[164:167], v[196:199], v[2:5]
	v_mfma_f32_16x16x32_bf16 v[54:57], v[160:163], v[176:179], v[54:57]
	v_mfma_f32_16x16x32_bf16 v[50:53], v[168:171], v[176:179], v[50:53]
	v_mfma_f32_16x16x32_bf16 v[38:41], v[160:163], v[184:187], v[38:41]
	v_mfma_f32_16x16x32_bf16 v[34:37], v[168:171], v[184:187], v[34:37]
	v_mfma_f32_16x16x32_bf16 v[22:25], v[160:163], v[192:195], v[22:25]
	v_mfma_f32_16x16x32_bf16 v[18:21], v[168:171], v[192:195], v[18:21]
	v_mfma_f32_16x16x32_bf16 v[6:9], v[160:163], v[200:203], v[6:9]
	v_mfma_f32_16x16x32_bf16 v[2:5], v[168:171], v[200:203], v[2:5]
	s_barrier
	s_setprio 0
	s_add_i32 s15, s15, 2
	s_add_u32 s26, s26, 0x100
	s_addc_u32 s27, s27, 0
	s_add_u32 s5, s5, 0x100
	s_addc_u32 s13, s13, 0
	s_cmp_gt_u32 s15, 29
	s_cbranch_scc0 .LBB0_1077
	s_and_b64 vcc, exec, s[10:11]
	s_cbranch_vccz .LBB0_1080
	s_barrier

; #define PG8_STAGE(bufoff, gbase, voff) do { _Pragma("unroll") for (int _i = 0; _i < 2; ++_i) \
;         __builtin_amdgcn_global_load_lds((const unsigned*)((const char*)(gbase) + (voff)[_i]), (LAS unsigned*)(lds + (bufoff) + ldsw + _i * 8192), 16, 0, 0); } while (0)
; #define PG8_LDA(dst, b, h) do { _Pragma("unroll") for (int m = 0; m < 4; ++m) _Pragma("unroll") for (int k = 0; k < 2; ++k) dst[m][k] = *(const LAS bf16x8*)(lds + PG8_SA(b, h) + aoff + m * 2048 + k * 1024); } while (0)
; #define PG8_LDB(dst, b, h) do { _Pragma("unroll") for (int n = 0; n < 2; ++n) _Pragma("unroll") for (int k = 0; k < 2; ++k) dst[n][k] = *(const LAS bf16x8*)(lds + PG8_SB(b, h) + boff + n * 2048 + k * 1024); } while (0)
; #define PG8_WAIT_V(n) asm volatile("s_waitcnt vmcnt(" #n ")" ::: "memory")
; #define PG8_WAIT_L(n) asm volatile("s_waitcnt lgkmcnt(" #n ")" ::: "memory")
; #define PG8_BAR __builtin_amdgcn_s_barrier()
; #define PG8_SCHED __builtin_amdgcn_sched_barrier(0)
; template <class Epi, class Sched, bool ALIGN_EPI, bool LAST_FUSED = false, bool PERM = false, bool CARRY = false>
; __device__ __forceinline__ void gemm_phase(LAS unsigned char* lds, const int tid, const int K, const int lda, const int ldb, const Sched& S, const Epi& E) {
;     ...
;         const bool has_next = S.next(KD_IDX(ui + 1), nxt);
;         const char* nA = has_next ? nxt.a : cA; const char* nB = has_next ? nxt.b : cB; const int nt = cur.nt;
; #pragma unroll 1
;         for (int t = 0; t < nt; t += 2) {
;             const bool last = (t == nt - 2);
;             const char* a1 = cA + (size_t)(t + 1) * kstep;
;             const char* a2 = last ? nA : cA + (size_t)(t + 2) * kstep; const char* b2 = last ? nB : cB + (size_t)(t + 2) * kstep;
;             const char* a3 = a2 + kstep; const char* b3 = b2 + kstep;
;             PG8_LDB(B0, 0, 0); PG8_LDB(B1, 0, 1); PG8_SCHED; PG8_LDA(At, 0, 0); PG8_STAGE(PG8_SA(1, 1), a1 + hstepA, voffA);
;             PG8_WAIT_V(8); PG8_WAIT_L(0); PG8_BAR; PG8_MMA(0, 0, At, B0); PG8_MMA(0, 1, At, B1); PG8_BAR; PG8_SCHED;
;             PG8_LDA(At, 0, 1); PG8_STAGE(PG8_SB(0, 0), b2, voffB); PG8_STAGE(PG8_SB(0, 1), b2 + hstepB, voffB); PG8_STAGE(PG8_SA(0, 0), a2, voffA);
;             PG8_WAIT_V(8); PG8_WAIT_L(0); PG8_BAR; PG8_MMA(1, 0, At, B0); PG8_MMA(1, 1, At, B1); PG8_BAR; PG8_SCHED;
.LBB0_1367:
	s_add_u32 s19, s38, s17
	s_addc_u32 s23, s39, 0
	s_add_u32 s35, s19, 0x100
	s_addc_u32 s37, s23, 0
	s_and_b64 s[28:29], s[46:47], exec
	s_cselect_b32 s51, s27, s37
	s_cselect_b32 s50, s26, s35
	s_add_u32 s17, s40, s17
	s_addc_u32 s28, s41, 0
	s_add_u32 s17, s17, 0x100
	s_addc_u32 s35, s28, 0
	s_add_i32 s45, 0, 0x10000
	s_and_b64 s[28:29], s[46:47], exec
	s_cselect_b32 s55, s31, s35
	s_cselect_b32 s54, s30, s17
	s_add_i32 s47, 0, 0x14000
	s_add_u32 s52, s19, 0x80080
	s_addc_u32 s53, s23, 0
	s_add_i32 s44, s45, s61
	s_add_i32 m0, s63, 0xc000
	s_add_i32 s79, s63, 0xe000
	s_add_i32 s29, s44, 0x2000
	s_add_u32 s58, s54, 0x10000
	v_add_u32_e32 v46, s45, v216
	v_add_u32_e32 v164, s47, v216
	s_addc_u32 s59, s55, 0
	s_add_i32 s37, s47, s61
	ds_read_b128 v[26:29], v46
	ds_read_b128 v[34:37], v46 offset:1024
	ds_read_b128 v[38:41], v46 offset:2048
	ds_read_b128 v[46:49], v46 offset:3072
	ds_read_b128 v[54:57], v164
	ds_read_b128 v[58:61], v164 offset:1024
	ds_read_b128 v[160:163], v164 offset:2048
	ds_read_b128 v[164:167], v164 offset:3072
	s_add_i32 s35, s37, 0x2000
	s_add_i32 s28, 0, 0x18000
	s_add_i32 s23, 0, 0x1c000
	s_add_u32 s48, s50, 0x80000
	s_addc_u32 s49, s51, 0
	s_add_i32 s19, s28, s61
	s_add_i32 s17, s19, 0x2000
	s_add_u32 s46, s54, 0x10080
	s_addc_u32 s47, s55, 0
	s_add_i32 s78, s23, s61
	s_add_i32 s45, s78, 0x2000
	v_lshl_add_u64 v[200:201], s[52:53], 0, v[158:159]
	ds_read_b128 v[168:171], v217
	ds_read_b128 v[172:175], v217 offset:1024
	ds_read_b128 v[176:179], v217 offset:2048
	ds_read_b128 v[180:183], v217 offset:3072
	ds_read_b128 v[184:187], v217 offset:4096
	ds_read_b128 v[188:191], v217 offset:5120
	ds_read_b128 v[192:195], v217 offset:6144
	ds_read_b128 v[196:199], v217 offset:7168
	global_load_lds_dwordx4 v[200:201], off
	v_lshl_add_u64 v[200:201], s[52:53], 0, v[156:157]
	s_mov_b32 m0, s79
	s_nop 0
	global_load_lds_dwordx4 v[200:201], off
	s_waitcnt vmcnt(8)
	s_waitcnt lgkmcnt(0)
	s_barrier
	s_setprio 1
	v_mfma_f32_16x16x32_bf16 v[150:153], v[26:29], v[168:171], v[150:153]
	v_mfma_f32_16x16x32_bf16 v[142:145], v[38:41], v[168:171], v[142:145]
	v_mfma_f32_16x16x32_bf16 v[134:137], v[26:29], v[176:179], v[134:137]
	v_mfma_f32_16x16x32_bf16 v[126:129], v[38:41], v[176:179], v[126:129]
	v_mfma_f32_16x16x32_bf16 v[118:121], v[26:29], v[184:187], v[118:121]
	v_mfma_f32_16x16x32_bf16 v[110:113], v[38:41], v[184:187], v[110:113]
	v_mfma_f32_16x16x32_bf16 v[102:105], v[26:29], v[192:195], v[102:105]
	v_mfma_f32_16x16x32_bf16 v[94:97], v[38:41], v[192:195], v[94:97]
	v_mfma_f32_16x16x32_bf16 v[150:153], v[34:37], v[172:175], v[150:153]
	v_mfma_f32_16x16x32_bf16 v[142:145], v[46:49], v[172:175], v[142:145]
	v_mfma_f32_16x16x32_bf16 v[134:137], v[34:37], v[180:183], v[134:137]
	v_mfma_f32_16x16x32_bf16 v[126:129], v[46:49], v[180:183], v[126:129]
	v_mfma_f32_16x16x32_bf16 v[118:121], v[34:37], v[188:191], v[118:121]
	v_mfma_f32_16x16x32_bf16 v[110:113], v[46:49], v[188:191], v[110:113]
	v_mfma_f32_16x16x32_bf16 v[102:105], v[34:37], v[196:199], v[102:105]
	v_mfma_f32_16x16x32_bf16 v[94:97], v[46:49], v[196:199], v[94:97]
	v_mfma_f32_16x16x32_bf16 v[146:149], v[54:57], v[168:171], v[146:149]
	v_mfma_f32_16x16x32_bf16 v[138:141], v[160:163], v[168:171], v[138:141]
	v_mfma_f32_16x16x32_bf16 v[130:133], v[54:57], v[176:179], v[130:133]
	v_mfma_f32_16x16x32_bf16 v[122:125], v[160:163], v[176:179], v[122:125]
	v_mfma_f32_16x16x32_bf16 v[114:117], v[54:57], v[184:187], v[114:117]
	v_mfma_f32_16x16x32_bf16 v[106:109], v[160:163], v[184:187], v[106:109]
	v_mfma_f32_16x16x32_bf16 v[98:101], v[54:57], v[192:195], v[98:101]
	v_mfma_f32_16x16x32_bf16 v[90:93], v[160:163], v[192:195], v[90:93]
	v_mfma_f32_16x16x32_bf16 v[146:149], v[58:61], v[172:175], v[146:149]
	v_mfma_f32_16x16x32_bf16 v[138:141], v[164:167], v[172:175], v[138:141]
	v_mfma_f32_16x16x32_bf16 v[130:133], v[58:61], v[180:183], v[130:133]
	v_mfma_f32_16x16x32_bf16 v[122:125], v[164:167], v[180:183], v[122:125]
	v_mfma_f32_16x16x32_bf16 v[114:117], v[58:61], v[188:191], v[114:117]
	v_mfma_f32_16x16x32_bf16 v[106:109], v[164:167], v[188:191], v[106:109]
	v_mfma_f32_16x16x32_bf16 v[98:101], v[58:61], v[196:199], v[98:101]
	v_mfma_f32_16x16x32_bf16 v[90:93], v[164:167], v[196:199], v[90:93]
	s_barrier
	s_setprio 0
	s_mov_b32 m0, s44
	v_lshl_add_u64 v[204:205], s[54:55], 0, v[0:1]
	ds_read_b128 v[168:171], v217 offset:16384
	ds_read_b128 v[172:175], v217 offset:17408
	ds_read_b128 v[176:179], v217 offset:18432
	ds_read_b128 v[180:183], v217 offset:19456
	ds_read_b128 v[184:187], v217 offset:20480
	ds_read_b128 v[188:191], v217 offset:21504
	ds_read_b128 v[192:195], v217 offset:22528
	ds_read_b128 v[196:199], v217 offset:23552
	global_load_lds_dwordx4 v[204:205], off
	v_lshl_add_u64 v[206:207], s[54:55], 0, v[154:155]
	s_mov_b32 m0, s29
	v_lshl_add_u64 v[200:201], s[58:59], 0, v[0:1]
	global_load_lds_dwordx4 v[206:207], off
	s_mov_b32 m0, s37
	v_lshl_add_u64 v[208:209], s[50:51], 0, v[158:159]
	global_load_lds_dwordx4 v[200:201], off
	v_lshl_add_u64 v[200:201], s[58:59], 0, v[154:155]
	s_mov_b32 m0, s35
	v_lshl_add_u64 v[210:211], s[50:51], 0, v[156:157]
	global_load_lds_dwordx4 v[200:201], off
	s_mov_b32 m0, s63
	s_nop 0
	global_load_lds_dwordx4 v[208:209], off
	s_mov_b32 m0, s64
	s_nop 0
	global_load_lds_dwordx4 v[210:211], off
	s_waitcnt vmcnt(8)
	s_waitcnt lgkmcnt(0)
	s_barrier
; #define PG8_STAGE(bufoff, gbase, voff) do { _Pragma("unroll") for (int _i = 0; _i < 2; ++_i) \
;         __builtin_amdgcn_global_load_lds((const unsigned*)((const char*)(gbase) + (voff)[_i]), (LAS unsigned*)(lds + (bufoff) + ldsw + _i * 8192), 16, 0, 0); } while (0)
; #define PG8_LDA(dst, b, h) do { _Pragma("unroll") for (int m = 0; m < 4; ++m) _Pragma("unroll") for (int k = 0; k < 2; ++k) dst[m][k] = *(const LAS bf16x8*)(lds + PG8_SA(b, h) + aoff + m * 2048 + k * 1024); } while (0)
; #define PG8_LDB(dst, b, h) do { _Pragma("unroll") for (int n = 0; n < 2; ++n) _Pragma("unroll") for (int k = 0; k < 2; ++k) dst[n][k] = *(const LAS bf16x8*)(lds + PG8_SB(b, h) + boff + n * 2048 + k * 1024); } while (0)
; #define PG8_MMA(ai, bj, At, Bt) do { __builtin_amdgcn_s_setprio(1); _Pragma("unroll") for (int m = 0; m < 4; ++m) _Pragma("unroll") for (int n = 0; n < 2; ++n) _Pragma("unroll") for (int k = 0; k < 2; ++k) \
;         acc[ai][bj][m][n] = __builtin_amdgcn_mfma_f32_16x16x32_bf16(Bt[n][k], At[m][k], acc[ai][bj][m][n], 0, 0, 0); __builtin_amdgcn_s_setprio(0); } while (0)
; #define PG8_WAIT_V(n) asm volatile("s_waitcnt vmcnt(" #n ")" ::: "memory")
; #define PG8_WAIT_L(n) asm volatile("s_waitcnt lgkmcnt(" #n ")" ::: "memory")
; #define PG8_BAR __builtin_amdgcn_s_barrier()
; #define PG8_SCHED __builtin_amdgcn_sched_barrier(0)
; template <class Epi, class Sched, bool ALIGN_EPI, bool LAST_FUSED = false, bool PERM = false, bool CARRY = false>
; __device__ __forceinline__ void gemm_phase(LAS unsigned char* lds, const int tid, const int K, const int lda, const int ldb, const Sched& S, const Epi& E) {
;     ...
;             PG8_WAIT_V(8); PG8_WAIT_L(0); PG8_BAR; PG8_MMA(1, 0, At, B0); PG8_MMA(1, 1, At, B1); PG8_BAR; PG8_SCHED;
;             PG8_LDB(B0, 1, 0); PG8_LDB(B1, 1, 1); PG8_SCHED; PG8_LDA(At, 1, 0); PG8_STAGE(PG8_SA(0, 1), a2 + hstepA, voffA);
;             PG8_WAIT_V(8); PG8_WAIT_L(0); PG8_BAR; PG8_MMA(0, 0, At, B0); PG8_MMA(0, 1, At, B1); PG8_BAR; PG8_SCHED;
	s_setprio 1
	v_mfma_f32_16x16x32_bf16 v[86:89], v[26:29], v[168:171], v[86:89]
	v_mfma_f32_16x16x32_bf16 v[78:81], v[38:41], v[168:171], v[78:81]
	v_mfma_f32_16x16x32_bf16 v[70:73], v[26:29], v[176:179], v[70:73]
	v_mfma_f32_16x16x32_bf16 v[62:65], v[38:41], v[176:179], v[62:65]
	v_mfma_f32_16x16x32_bf16 v[42:45], v[26:29], v[184:187], v[42:45]
	v_mfma_f32_16x16x32_bf16 v[22:25], v[38:41], v[184:187], v[22:25]
	v_mfma_f32_16x16x32_bf16 v[14:17], v[26:29], v[192:195], v[14:17]
	v_mfma_f32_16x16x32_bf16 v[6:9], v[38:41], v[192:195], v[6:9]
	v_mfma_f32_16x16x32_bf16 v[86:89], v[34:37], v[172:175], v[86:89]
	v_mfma_f32_16x16x32_bf16 v[78:81], v[46:49], v[172:175], v[78:81]
	v_mfma_f32_16x16x32_bf16 v[70:73], v[34:37], v[180:183], v[70:73]
	v_mfma_f32_16x16x32_bf16 v[62:65], v[46:49], v[180:183], v[62:65]
	v_mfma_f32_16x16x32_bf16 v[42:45], v[34:37], v[188:191], v[42:45]
	v_mfma_f32_16x16x32_bf16 v[22:25], v[46:49], v[188:191], v[22:25]
	v_mfma_f32_16x16x32_bf16 v[14:17], v[34:37], v[196:199], v[14:17]
	v_mfma_f32_16x16x32_bf16 v[6:9], v[46:49], v[196:199], v[6:9]
	v_mfma_f32_16x16x32_bf16 v[30:33], v[54:57], v[184:187], v[30:33]
	v_mfma_f32_16x16x32_bf16 v[18:21], v[160:163], v[184:187], v[18:21]
	v_mfma_f32_16x16x32_bf16 v[10:13], v[54:57], v[192:195], v[10:13]
	v_mfma_f32_16x16x32_bf16 v[2:5], v[160:163], v[192:195], v[2:5]
	v_mfma_f32_16x16x32_bf16 v[26:29], v[54:57], v[168:171], v[82:85]
	v_mfma_f32_16x16x32_bf16 v[34:37], v[160:163], v[168:171], v[74:77]
	v_mfma_f32_16x16x32_bf16 v[38:41], v[54:57], v[176:179], v[66:69]
	v_mfma_f32_16x16x32_bf16 v[46:49], v[160:163], v[176:179], v[50:53]
	v_mfma_f32_16x16x32_bf16 v[30:33], v[58:61], v[188:191], v[30:33]
	v_mfma_f32_16x16x32_bf16 v[18:21], v[164:167], v[188:191], v[18:21]
	v_mfma_f32_16x16x32_bf16 v[10:13], v[58:61], v[196:199], v[10:13]
	v_mfma_f32_16x16x32_bf16 v[2:5], v[164:167], v[196:199], v[2:5]
	v_mfma_f32_16x16x32_bf16 v[26:29], v[58:61], v[172:175], v[26:29]
	v_mfma_f32_16x16x32_bf16 v[34:37], v[164:167], v[172:175], v[34:37]
	v_mfma_f32_16x16x32_bf16 v[38:41], v[58:61], v[180:183], v[38:41]
	v_mfma_f32_16x16x32_bf16 v[46:49], v[164:167], v[180:183], v[46:49]
	s_barrier
	s_setprio 0
	v_add_u32_e32 v66, s28, v216
	v_add_u32_e32 v74, s23, v216
	ds_read_b128 v[50:53], v66
	ds_read_b128 v[54:57], v66 offset:1024
	ds_read_b128 v[58:61], v66 offset:2048
	ds_read_b128 v[66:69], v66 offset:3072
	ds_read_b128 v[160:163], v74
	ds_read_b128 v[164:167], v74 offset:1024
	ds_read_b128 v[168:171], v74 offset:2048
	ds_read_b128 v[172:175], v74 offset:3072
	s_mov_b32 m0, s65
	v_lshl_add_u64 v[200:201], s[48:49], 0, v[158:159]
	ds_read_b128 v[74:77], v217 offset:32768
	ds_read_b128 v[82:85], v217 offset:33792
	ds_read_b128 v[176:179], v217 offset:34816
	ds_read_b128 v[180:183], v217 offset:35840
	ds_read_b128 v[184:187], v217 offset:36864
	ds_read_b128 v[188:191], v217 offset:37888
	ds_read_b128 v[192:195], v217 offset:38912
	ds_read_b128 v[196:199], v217 offset:39936
	global_load_lds_dwordx4 v[200:201], off
	v_lshl_add_u64 v[200:201], s[48:49], 0, v[156:157]
	s_mov_b32 m0, s66
	s_nop 0
	global_load_lds_dwordx4 v[200:201], off
	s_waitcnt vmcnt(8)
	s_waitcnt lgkmcnt(0)
	s_barrier
	s_setprio 1
	v_mfma_f32_16x16x32_bf16 v[150:153], v[50:53], v[74:77], v[150:153]
	v_mfma_f32_16x16x32_bf16 v[142:145], v[58:61], v[74:77], v[142:145]
	v_mfma_f32_16x16x32_bf16 v[134:137], v[50:53], v[176:179], v[134:137]
	v_mfma_f32_16x16x32_bf16 v[126:129], v[58:61], v[176:179], v[126:129]
	v_mfma_f32_16x16x32_bf16 v[118:121], v[50:53], v[184:187], v[118:121]
	v_mfma_f32_16x16x32_bf16 v[110:113], v[58:61], v[184:187], v[110:113]
	v_mfma_f32_16x16x32_bf16 v[102:105], v[50:53], v[192:195], v[102:105]
	v_mfma_f32_16x16x32_bf16 v[94:97], v[58:61], v[192:195], v[94:97]
	v_mfma_f32_16x16x32_bf16 v[150:153], v[54:57], v[82:85], v[150:153]
	v_mfma_f32_16x16x32_bf16 v[142:145], v[66:69], v[82:85], v[142:145]
	v_mfma_f32_16x16x32_bf16 v[134:137], v[54:57], v[180:183], v[134:137]
	v_mfma_f32_16x16x32_bf16 v[126:129], v[66:69], v[180:183], v[126:129]
	v_mfma_f32_16x16x32_bf16 v[118:121], v[54:57], v[188:191], v[118:121]
	v_mfma_f32_16x16x32_bf16 v[110:113], v[66:69], v[188:191], v[110:113]
	v_mfma_f32_16x16x32_bf16 v[102:105], v[54:57], v[196:199], v[102:105]
	v_mfma_f32_16x16x32_bf16 v[94:97], v[66:69], v[196:199], v[94:97]
	v_mfma_f32_16x16x32_bf16 v[146:149], v[160:163], v[74:77], v[146:149]
	v_mfma_f32_16x16x32_bf16 v[74:77], v[168:171], v[74:77], v[138:141]
	v_mfma_f32_16x16x32_bf16 v[138:141], v[172:175], v[82:85], v[74:77]
	v_mfma_f32_16x16x32_bf16 v[74:77], v[160:163], v[176:179], v[130:133]
	v_mfma_f32_16x16x32_bf16 v[130:133], v[164:167], v[180:183], v[74:77]
	v_mfma_f32_16x16x32_bf16 v[74:77], v[168:171], v[176:179], v[122:125]
	v_mfma_f32_16x16x32_bf16 v[122:125], v[172:175], v[180:183], v[74:77]
	v_mfma_f32_16x16x32_bf16 v[74:77], v[160:163], v[184:187], v[114:117]
	v_mfma_f32_16x16x32_bf16 v[114:117], v[164:167], v[188:191], v[74:77]
	v_mfma_f32_16x16x32_bf16 v[74:77], v[168:171], v[184:187], v[106:109]
	v_mfma_f32_16x16x32_bf16 v[106:109], v[172:175], v[188:191], v[74:77]
	v_mfma_f32_16x16x32_bf16 v[74:77], v[160:163], v[192:195], v[98:101]
	v_mfma_f32_16x16x32_bf16 v[98:101], v[164:167], v[196:199], v[74:77]
	v_mfma_f32_16x16x32_bf16 v[74:77], v[168:171], v[192:195], v[90:93]
	v_mfma_f32_16x16x32_bf16 v[146:149], v[164:167], v[82:85], v[146:149]
	v_mfma_f32_16x16x32_bf16 v[90:93], v[172:175], v[196:199], v[74:77]
	s_barrier
; #define PG8_STAGE(bufoff, gbase, voff) do { _Pragma("unroll") for (int _i = 0; _i < 2; ++_i) \
;         __builtin_amdgcn_global_load_lds((const unsigned*)((const char*)(gbase) + (voff)[_i]), (LAS unsigned*)(lds + (bufoff) + ldsw + _i * 8192), 16, 0, 0); } while (0)
; #define PG8_LDA(dst, b, h) do { _Pragma("unroll") for (int m = 0; m < 4; ++m) _Pragma("unroll") for (int k = 0; k < 2; ++k) dst[m][k] = *(const LAS bf16x8*)(lds + PG8_SA(b, h) + aoff + m * 2048 + k * 1024); } while (0)
; #define PG8_MMA(ai, bj, At, Bt) do { __builtin_amdgcn_s_setprio(1); _Pragma("unroll") for (int m = 0; m < 4; ++m) _Pragma("unroll") for (int n = 0; n < 2; ++n) _Pragma("unroll") for (int k = 0; k < 2; ++k) \
;         acc[ai][bj][m][n] = __builtin_amdgcn_mfma_f32_16x16x32_bf16(Bt[n][k], At[m][k], acc[ai][bj][m][n], 0, 0, 0); __builtin_amdgcn_s_setprio(0); } while (0)
; #define PG8_WAIT_V(n) asm volatile("s_waitcnt vmcnt(" #n ")" ::: "memory")
; #define PG8_WAIT_L(n) asm volatile("s_waitcnt lgkmcnt(" #n ")" ::: "memory")
; #define PG8_BAR __builtin_amdgcn_s_barrier()
; #define PG8_SCHED __builtin_amdgcn_sched_barrier(0)
; template <class Epi, class Sched, bool ALIGN_EPI, bool LAST_FUSED = false, bool PERM = false, bool CARRY = false>
; __device__ __forceinline__ void gemm_phase(LAS unsigned char* lds, const int tid, const int K, const int lda, const int ldb, const Sched& S, const Epi& E) {
;     ...
;             PG8_LDA(At, 1, 1); PG8_STAGE(PG8_SB(1, 0), b3, voffB); PG8_STAGE(PG8_SB(1, 1), b3 + hstepB, voffB); PG8_STAGE(PG8_SA(1, 0), a3, voffA);
;             PG8_WAIT_V(8); PG8_WAIT_L(0); PG8_BAR; PG8_MMA(1, 0, At, B0); PG8_MMA(1, 1, At, B1); PG8_BAR; PG8_SCHED;
;         }
;         if constexpr (ALIGN_EPI) { if (wr == 0) PG8_BAR; }
	s_setprio 0
	s_mov_b32 m0, s19
	v_lshl_add_u64 v[82:83], v[204:205], 0, s[68:69]
	s_nop 1
	ds_read_b128 v[74:77], v217 offset:49152
	ds_read_b128 v[176:179], v217 offset:50176
	ds_read_b128 v[180:183], v217 offset:51200
	ds_read_b128 v[184:187], v217 offset:52224
	ds_read_b128 v[188:191], v217 offset:53248
	ds_read_b128 v[192:195], v217 offset:54272
	ds_read_b128 v[196:199], v217 offset:55296
	ds_read_b128 v[200:203], v217 offset:56320
	global_load_lds_dwordx4 v[82:83], off
	v_lshl_add_u64 v[82:83], v[206:207], 0, s[68:69]
	s_mov_b32 m0, s17
	s_nop 0
	global_load_lds_dwordx4 v[82:83], off
	v_lshl_add_u64 v[82:83], s[46:47], 0, v[0:1]
	s_mov_b32 m0, s78
	s_nop 0
	global_load_lds_dwordx4 v[82:83], off
	v_lshl_add_u64 v[82:83], s[46:47], 0, v[154:155]
	s_mov_b32 m0, s45
	s_nop 0
	global_load_lds_dwordx4 v[82:83], off
	v_lshl_add_u64 v[82:83], v[208:209], 0, s[68:69]
	s_mov_b32 m0, s74
	s_nop 0
	global_load_lds_dwordx4 v[82:83], off
	v_lshl_add_u64 v[82:83], v[210:211], 0, s[68:69]
	s_mov_b32 m0, s75
	s_nop 0
	global_load_lds_dwordx4 v[82:83], off
	s_waitcnt vmcnt(8)
	s_waitcnt lgkmcnt(0)
	s_barrier
	s_setprio 1
	v_mfma_f32_16x16x32_bf16 v[82:85], v[50:53], v[74:77], v[86:89]
	v_mfma_f32_16x16x32_bf16 v[78:81], v[58:61], v[74:77], v[78:81]
	v_mfma_f32_16x16x32_bf16 v[70:73], v[50:53], v[180:183], v[70:73]
	v_mfma_f32_16x16x32_bf16 v[62:65], v[58:61], v[180:183], v[62:65]
	v_mfma_f32_16x16x32_bf16 v[42:45], v[50:53], v[188:191], v[42:45]
	v_mfma_f32_16x16x32_bf16 v[22:25], v[58:61], v[188:191], v[22:25]
	v_mfma_f32_16x16x32_bf16 v[14:17], v[50:53], v[196:199], v[14:17]
	v_mfma_f32_16x16x32_bf16 v[6:9], v[58:61], v[196:199], v[6:9]
	v_mfma_f32_16x16x32_bf16 v[86:89], v[54:57], v[176:179], v[82:85]
	v_mfma_f32_16x16x32_bf16 v[78:81], v[66:69], v[176:179], v[78:81]
	v_mfma_f32_16x16x32_bf16 v[70:73], v[54:57], v[184:187], v[70:73]
	v_mfma_f32_16x16x32_bf16 v[62:65], v[66:69], v[184:187], v[62:65]
	v_mfma_f32_16x16x32_bf16 v[42:45], v[54:57], v[192:195], v[42:45]
	v_mfma_f32_16x16x32_bf16 v[22:25], v[66:69], v[192:195], v[22:25]
	v_mfma_f32_16x16x32_bf16 v[14:17], v[54:57], v[200:203], v[14:17]
	v_mfma_f32_16x16x32_bf16 v[6:9], v[66:69], v[200:203], v[6:9]
	v_mfma_f32_16x16x32_bf16 v[26:29], v[160:163], v[74:77], v[26:29]
	v_mfma_f32_16x16x32_bf16 v[82:85], v[164:167], v[176:179], v[26:29]
	v_mfma_f32_16x16x32_bf16 v[26:29], v[168:171], v[74:77], v[34:37]
	v_mfma_f32_16x16x32_bf16 v[74:77], v[172:175], v[176:179], v[26:29]
	v_mfma_f32_16x16x32_bf16 v[26:29], v[160:163], v[180:183], v[38:41]
	v_mfma_f32_16x16x32_bf16 v[66:69], v[164:167], v[184:187], v[26:29]
	v_mfma_f32_16x16x32_bf16 v[26:29], v[168:171], v[180:183], v[46:49]
	v_mfma_f32_16x16x32_bf16 v[50:53], v[172:175], v[184:187], v[26:29]
	v_mfma_f32_16x16x32_bf16 v[26:29], v[160:163], v[188:191], v[30:33]
	v_mfma_f32_16x16x32_bf16 v[18:21], v[168:171], v[188:191], v[18:21]
	v_mfma_f32_16x16x32_bf16 v[10:13], v[160:163], v[196:199], v[10:13]
	v_mfma_f32_16x16x32_bf16 v[2:5], v[168:171], v[196:199], v[2:5]
	v_mfma_f32_16x16x32_bf16 v[30:33], v[164:167], v[192:195], v[26:29]
	v_mfma_f32_16x16x32_bf16 v[18:21], v[172:175], v[192:195], v[18:21]
	v_mfma_f32_16x16x32_bf16 v[10:13], v[164:167], v[200:203], v[10:13]
	v_mfma_f32_16x16x32_bf16 v[2:5], v[172:175], v[200:203], v[2:5]
	s_barrier
	s_setprio 0
	s_movk_i32 s17, 0x100
	s_andn2_b64 vcc, exec, s[42:43]
	s_mov_b64 s[46:47], -1
	s_mov_b64 s[42:43], 0
	s_cbranch_vccz .LBB0_1367
	s_and_b64 vcc, exec, s[14:15]
	s_cbranch_vccz .LBB0_1370
	s_barrier

; #define PG8_STAGE(bufoff, gbase, voff) do { _Pragma("unroll") for (int _i = 0; _i < 2; ++_i) \
;         __builtin_amdgcn_global_load_lds((const unsigned*)((const char*)(gbase) + (voff)[_i]), (LAS unsigned*)(lds + (bufoff) + ldsw + _i * 8192), 16, 0, 0); } while (0)
; #define PG8_LDA(dst, b, h) do { _Pragma("unroll") for (int m = 0; m < 4; ++m) _Pragma("unroll") for (int k = 0; k < 2; ++k) dst[m][k] = *(const LAS bf16x8*)(lds + PG8_SA(b, h) + aoff + m * 2048 + k * 1024); } while (0)
; #define PG8_LDB(dst, b, h) do { _Pragma("unroll") for (int n = 0; n < 2; ++n) _Pragma("unroll") for (int k = 0; k < 2; ++k) dst[n][k] = *(const LAS bf16x8*)(lds + PG8_SB(b, h) + boff + n * 2048 + k * 1024); } while (0)
; #define PG8_WAIT_V(n) asm volatile("s_waitcnt vmcnt(" #n ")" ::: "memory")
; #define PG8_WAIT_L(n) asm volatile("s_waitcnt lgkmcnt(" #n ")" ::: "memory")
; #define PG8_BAR __builtin_amdgcn_s_barrier()
; #define PG8_SCHED __builtin_amdgcn_sched_barrier(0)
; template <class Epi, class Sched, bool ALIGN_EPI, bool LAST_FUSED = false, bool PERM = false, bool CARRY = false>
; __device__ __forceinline__ void gemm_phase(LAS unsigned char* lds, const int tid, const int K, const int lda, const int ldb, const Sched& S, const Epi& E) {
;     ...
;         const bool has_next = S.next(KD_IDX(ui + 1), nxt);
;         const char* nA = has_next ? nxt.a : cA; const char* nB = has_next ? nxt.b : cB; const int nt = cur.nt;
; #pragma unroll 1
;         for (int t = 0; t < nt; t += 2) {
;             const bool last = (t == nt - 2);
;             const char* a1 = cA + (size_t)(t + 1) * kstep;
;             const char* a2 = last ? nA : cA + (size_t)(t + 2) * kstep; const char* b2 = last ? nB : cB + (size_t)(t + 2) * kstep;
;             const char* a3 = a2 + kstep; const char* b3 = b2 + kstep;
;             PG8_LDB(B0, 0, 0); PG8_LDB(B1, 0, 1); PG8_SCHED; PG8_LDA(At, 0, 0); PG8_STAGE(PG8_SA(1, 1), a1 + hstepA, voffA);
;             PG8_WAIT_V(8); PG8_WAIT_L(0); PG8_BAR; PG8_MMA(0, 0, At, B0); PG8_MMA(0, 1, At, B1); PG8_BAR; PG8_SCHED;
;             PG8_LDA(At, 0, 1); PG8_STAGE(PG8_SB(0, 0), b2, voffB); PG8_STAGE(PG8_SB(0, 1), b2 + hstepB, voffB); PG8_STAGE(PG8_SA(0, 0), a2, voffA);
;             PG8_WAIT_V(8); PG8_WAIT_L(0); PG8_BAR; PG8_MMA(1, 0, At, B0); PG8_MMA(1, 1, At, B1); PG8_BAR; PG8_SCHED;
.LBB0_1585:
	s_add_u32 s52, s42, s48
	s_addc_u32 s53, s43, s49
	s_add_u32 s76, s40, s48
	s_addc_u32 s77, s41, s49
	s_add_i32 s96, 0, 0x10000
	s_cmp_eq_u32 s3, s95
	s_cselect_b32 s53, s24, s53
	s_cselect_b32 s52, s55, s52
	s_cselect_b32 s77, s93, s77
	s_cselect_b32 s76, s94, s76
	s_add_i32 vcc_lo, 0, 0x14000
	v_add_u32_e32 v156, s96, v140
	v_add_u32_e32 v172, vcc_lo, v140
	ds_read_b128 v[142:145], v156
	ds_read_b128 v[146:149], v156 offset:1024
	ds_read_b128 v[150:153], v156 offset:2048
	ds_read_b128 v[156:159], v156 offset:3072
	ds_read_b128 v[160:163], v172
	ds_read_b128 v[164:167], v172 offset:1024
	ds_read_b128 v[168:171], v172 offset:2048
	ds_read_b128 v[172:175], v172 offset:3072
	v_lshl_add_u64 v[208:209], s[42:43], 0, v[138:139]
	s_add_i32 m0, s35, 0xc000
	ds_read_b128 v[176:179], v141
	ds_read_b128 v[180:183], v141 offset:1024
	ds_read_b128 v[184:187], v141 offset:2048
	ds_read_b128 v[188:191], v141 offset:3072
	ds_read_b128 v[192:195], v141 offset:4096
	ds_read_b128 v[196:199], v141 offset:5120
	ds_read_b128 v[200:203], v141 offset:6144
	ds_read_b128 v[204:207], v141 offset:7168
	global_load_lds_dwordx4 v[208:209], off
	v_lshl_add_u64 v[208:209], s[42:43], 0, v[128:129]
	s_add_i32 m0, s35, 0xe000
	s_nop 0
	global_load_lds_dwordx4 v[208:209], off
	s_waitcnt vmcnt(8)
	s_waitcnt lgkmcnt(0)
	s_barrier
	s_setprio 1
	v_mfma_f32_16x16x32_bf16 v[62:65], v[142:145], v[176:179], v[62:65]
	v_mfma_f32_16x16x32_bf16 v[42:45], v[150:153], v[176:179], v[42:45]
	v_mfma_f32_16x16x32_bf16 v[18:21], v[142:145], v[184:187], v[18:21]
	v_mfma_f32_16x16x32_bf16 v[14:17], v[150:153], v[184:187], v[14:17]
	v_mfma_f32_16x16x32_bf16 v[38:41], v[142:145], v[192:195], v[38:41]
	v_mfma_f32_16x16x32_bf16 v[30:33], v[150:153], v[192:195], v[30:33]
	v_mfma_f32_16x16x32_bf16 v[58:61], v[142:145], v[200:203], v[58:61]
	v_mfma_f32_16x16x32_bf16 v[54:57], v[150:153], v[200:203], v[54:57]
	v_mfma_f32_16x16x32_bf16 v[62:65], v[146:149], v[180:183], v[62:65]
	v_mfma_f32_16x16x32_bf16 v[42:45], v[156:159], v[180:183], v[42:45]
	v_mfma_f32_16x16x32_bf16 v[18:21], v[146:149], v[188:191], v[18:21]
	v_mfma_f32_16x16x32_bf16 v[14:17], v[156:159], v[188:191], v[14:17]
	v_mfma_f32_16x16x32_bf16 v[38:41], v[146:149], v[196:199], v[38:41]
	v_mfma_f32_16x16x32_bf16 v[30:33], v[156:159], v[196:199], v[30:33]
	v_mfma_f32_16x16x32_bf16 v[58:61], v[146:149], v[204:207], v[58:61]
	v_mfma_f32_16x16x32_bf16 v[54:57], v[156:159], v[204:207], v[54:57]
	v_mfma_f32_16x16x32_bf16 v[34:37], v[160:163], v[176:179], v[34:37]
	v_mfma_f32_16x16x32_bf16 v[2:5], v[168:171], v[176:179], v[2:5]
	v_mfma_f32_16x16x32_bf16 v[10:13], v[160:163], v[184:187], v[10:13]
	v_mfma_f32_16x16x32_bf16 v[6:9], v[168:171], v[184:187], v[6:9]
	v_mfma_f32_16x16x32_bf16 v[26:29], v[160:163], v[192:195], v[26:29]
	v_mfma_f32_16x16x32_bf16 v[22:25], v[168:171], v[192:195], v[22:25]
	v_mfma_f32_16x16x32_bf16 v[50:53], v[160:163], v[200:203], v[50:53]
	v_mfma_f32_16x16x32_bf16 v[46:49], v[168:171], v[200:203], v[46:49]
	v_mfma_f32_16x16x32_bf16 v[34:37], v[164:167], v[180:183], v[34:37]
	v_mfma_f32_16x16x32_bf16 v[2:5], v[172:175], v[180:183], v[2:5]
	v_mfma_f32_16x16x32_bf16 v[10:13], v[164:167], v[188:191], v[10:13]
	v_mfma_f32_16x16x32_bf16 v[6:9], v[172:175], v[188:191], v[6:9]
	v_mfma_f32_16x16x32_bf16 v[26:29], v[164:167], v[196:199], v[26:29]
	v_mfma_f32_16x16x32_bf16 v[22:25], v[172:175], v[196:199], v[22:25]
	v_mfma_f32_16x16x32_bf16 v[50:53], v[164:167], v[204:207], v[50:53]
	v_mfma_f32_16x16x32_bf16 v[46:49], v[172:175], v[204:207], v[46:49]
	s_barrier
	s_setprio 0
	s_add_i32 s96, s96, s87
	v_lshl_add_u64 v[208:209], s[76:77], 0, v[0:1]
	s_mov_b32 m0, s96
	ds_read_b128 v[176:179], v141 offset:16384
	ds_read_b128 v[180:183], v141 offset:17408
	ds_read_b128 v[184:187], v141 offset:18432
	ds_read_b128 v[188:191], v141 offset:19456
	ds_read_b128 v[192:195], v141 offset:20480
	ds_read_b128 v[196:199], v141 offset:21504
	ds_read_b128 v[200:203], v141 offset:22528
	ds_read_b128 v[204:207], v141 offset:23552
	global_load_lds_dwordx4 v[208:209], off
	s_add_i32 m0, s96, 0x2000
	s_add_u32 s96, s76, 0x80000
	v_lshl_add_u64 v[210:211], s[76:77], 0, v[122:123]
	s_addc_u32 s97, s77, 0
	s_add_i32 vcc_lo, vcc_lo, s87
	global_load_lds_dwordx4 v[210:211], off
	v_lshl_add_u64 v[212:213], s[96:97], 0, v[0:1]
	s_mov_b32 m0, vcc_lo
	v_lshl_add_u64 v[214:215], s[52:53], 0, v[122:123]
	global_load_lds_dwordx4 v[212:213], off
	v_lshl_add_u64 v[212:213], s[96:97], 0, v[122:123]
	s_add_i32 m0, vcc_lo, 0x2000
	s_nop 0
	global_load_lds_dwordx4 v[212:213], off
	v_lshl_add_u64 v[212:213], s[52:53], 0, v[0:1]
	s_mov_b32 m0, s35
	s_nop 0
	global_load_lds_dwordx4 v[212:213], off
	s_mov_b32 m0, s28
	s_nop 0
	global_load_lds_dwordx4 v[214:215], off
	s_waitcnt vmcnt(8)
	s_waitcnt lgkmcnt(0)
	s_barrier
; #define PG8_STAGE(bufoff, gbase, voff) do { _Pragma("unroll") for (int _i = 0; _i < 2; ++_i) \
;         __builtin_amdgcn_global_load_lds((const unsigned*)((const char*)(gbase) + (voff)[_i]), (LAS unsigned*)(lds + (bufoff) + ldsw + _i * 8192), 16, 0, 0); } while (0)
; #define PG8_LDA(dst, b, h) do { _Pragma("unroll") for (int m = 0; m < 4; ++m) _Pragma("unroll") for (int k = 0; k < 2; ++k) dst[m][k] = *(const LAS bf16x8*)(lds + PG8_SA(b, h) + aoff + m * 2048 + k * 1024); } while (0)
; #define PG8_LDB(dst, b, h) do { _Pragma("unroll") for (int n = 0; n < 2; ++n) _Pragma("unroll") for (int k = 0; k < 2; ++k) dst[n][k] = *(const LAS bf16x8*)(lds + PG8_SB(b, h) + boff + n * 2048 + k * 1024); } while (0)
; #define PG8_MMA(ai, bj, At, Bt) do { __builtin_amdgcn_s_setprio(1); _Pragma("unroll") for (int m = 0; m < 4; ++m) _Pragma("unroll") for (int n = 0; n < 2; ++n) _Pragma("unroll") for (int k = 0; k < 2; ++k) \
;         acc[ai][bj][m][n] = __builtin_amdgcn_mfma_f32_16x16x32_bf16(Bt[n][k], At[m][k], acc[ai][bj][m][n], 0, 0, 0); __builtin_amdgcn_s_setprio(0); } while (0)
; #define PG8_WAIT_V(n) asm volatile("s_waitcnt vmcnt(" #n ")" ::: "memory")
; #define PG8_WAIT_L(n) asm volatile("s_waitcnt lgkmcnt(" #n ")" ::: "memory")
; #define PG8_BAR __builtin_amdgcn_s_barrier()
; #define PG8_SCHED __builtin_amdgcn_sched_barrier(0)
; template <class Epi, class Sched, bool ALIGN_EPI, bool LAST_FUSED = false, bool PERM = false, bool CARRY = false>
; __device__ __forceinline__ void gemm_phase(LAS unsigned char* lds, const int tid, const int K, const int lda, const int ldb, const Sched& S, const Epi& E) {
;     ...
;             PG8_WAIT_V(8); PG8_WAIT_L(0); PG8_BAR; PG8_MMA(1, 0, At, B0); PG8_MMA(1, 1, At, B1); PG8_BAR; PG8_SCHED;
;             PG8_LDB(B0, 1, 0); PG8_LDB(B1, 1, 1); PG8_SCHED; PG8_LDA(At, 1, 0); PG8_STAGE(PG8_SA(0, 1), a2 + hstepA, voffA);
;             PG8_WAIT_V(8); PG8_WAIT_L(0); PG8_BAR; PG8_MMA(0, 0, At, B0); PG8_MMA(0, 1, At, B1); PG8_BAR; PG8_SCHED;
	s_setprio 1
	v_mfma_f32_16x16x32_bf16 v[78:81], v[142:145], v[176:179], v[78:81]
	v_mfma_f32_16x16x32_bf16 v[74:77], v[150:153], v[176:179], v[74:77]
	v_mfma_f32_16x16x32_bf16 v[98:101], v[142:145], v[184:187], v[98:101]
	v_mfma_f32_16x16x32_bf16 v[94:97], v[150:153], v[184:187], v[94:97]
	v_mfma_f32_16x16x32_bf16 v[118:121], v[142:145], v[192:195], v[118:121]
	v_mfma_f32_16x16x32_bf16 v[114:117], v[150:153], v[192:195], v[114:117]
	v_mfma_f32_16x16x32_bf16 v[134:137], v[142:145], v[200:203], v[134:137]
	v_mfma_f32_16x16x32_bf16 v[130:133], v[150:153], v[200:203], v[130:133]
	v_mfma_f32_16x16x32_bf16 v[78:81], v[146:149], v[180:183], v[78:81]
	v_mfma_f32_16x16x32_bf16 v[74:77], v[156:159], v[180:183], v[74:77]
	v_mfma_f32_16x16x32_bf16 v[98:101], v[146:149], v[188:191], v[98:101]
	v_mfma_f32_16x16x32_bf16 v[94:97], v[156:159], v[188:191], v[94:97]
	v_mfma_f32_16x16x32_bf16 v[118:121], v[146:149], v[196:199], v[118:121]
	v_mfma_f32_16x16x32_bf16 v[114:117], v[156:159], v[196:199], v[114:117]
	v_mfma_f32_16x16x32_bf16 v[134:137], v[146:149], v[204:207], v[134:137]
	v_mfma_f32_16x16x32_bf16 v[130:133], v[156:159], v[204:207], v[130:133]
	v_mfma_f32_16x16x32_bf16 v[70:73], v[160:163], v[176:179], v[70:73]
	v_mfma_f32_16x16x32_bf16 v[66:69], v[168:171], v[176:179], v[66:69]
	v_mfma_f32_16x16x32_bf16 v[90:93], v[160:163], v[184:187], v[90:93]
	v_mfma_f32_16x16x32_bf16 v[86:89], v[168:171], v[184:187], v[86:89]
	v_mfma_f32_16x16x32_bf16 v[110:113], v[160:163], v[192:195], v[110:113]
	v_mfma_f32_16x16x32_bf16 v[106:109], v[168:171], v[192:195], v[106:109]
	v_mfma_f32_16x16x32_bf16 v[102:105], v[160:163], v[200:203], v[102:105]
	v_mfma_f32_16x16x32_bf16 v[82:85], v[168:171], v[200:203], v[82:85]
	v_mfma_f32_16x16x32_bf16 v[70:73], v[164:167], v[180:183], v[70:73]
	v_mfma_f32_16x16x32_bf16 v[66:69], v[172:175], v[180:183], v[66:69]
	v_mfma_f32_16x16x32_bf16 v[90:93], v[164:167], v[188:191], v[90:93]
	v_mfma_f32_16x16x32_bf16 v[86:89], v[172:175], v[188:191], v[86:89]
	v_mfma_f32_16x16x32_bf16 v[110:113], v[164:167], v[196:199], v[110:113]
	v_mfma_f32_16x16x32_bf16 v[106:109], v[172:175], v[196:199], v[106:109]
	v_mfma_f32_16x16x32_bf16 v[102:105], v[164:167], v[204:207], v[102:105]
	v_mfma_f32_16x16x32_bf16 v[82:85], v[172:175], v[204:207], v[82:85]
	s_barrier
	s_setprio 0
	s_add_i32 s96, 0, 0x18000
	s_add_i32 s97, 0, 0x1c000
	v_add_u32_e32 v156, s96, v140
	v_add_u32_e32 v172, s97, v140
	ds_read_b128 v[142:145], v156
	ds_read_b128 v[146:149], v156 offset:1024
	ds_read_b128 v[150:153], v156 offset:2048
	ds_read_b128 v[156:159], v156 offset:3072
	ds_read_b128 v[160:163], v172
	ds_read_b128 v[164:167], v172 offset:1024
	ds_read_b128 v[168:171], v172 offset:2048
	ds_read_b128 v[172:175], v172 offset:3072
	s_add_u32 s52, s52, 0x80000
	s_addc_u32 s53, s53, 0
	s_mov_b32 m0, s29
	v_lshl_add_u64 v[216:217], s[52:53], 0, v[0:1]
	ds_read_b128 v[176:179], v141 offset:32768
	ds_read_b128 v[180:183], v141 offset:33792
	ds_read_b128 v[184:187], v141 offset:34816
	ds_read_b128 v[188:191], v141 offset:35840
	ds_read_b128 v[192:195], v141 offset:36864
	ds_read_b128 v[196:199], v141 offset:37888
	ds_read_b128 v[200:203], v141 offset:38912
	ds_read_b128 v[204:207], v141 offset:39936
	global_load_lds_dwordx4 v[216:217], off
	v_lshl_add_u64 v[216:217], s[52:53], 0, v[122:123]
	s_mov_b32 m0, s14
	s_nop 0
	global_load_lds_dwordx4 v[216:217], off
	s_waitcnt vmcnt(8)
	s_waitcnt lgkmcnt(0)
	s_barrier
	s_setprio 1
	v_mfma_f32_16x16x32_bf16 v[62:65], v[142:145], v[176:179], v[62:65]
	v_mfma_f32_16x16x32_bf16 v[42:45], v[150:153], v[176:179], v[42:45]
	v_mfma_f32_16x16x32_bf16 v[18:21], v[142:145], v[184:187], v[18:21]
	v_mfma_f32_16x16x32_bf16 v[14:17], v[150:153], v[184:187], v[14:17]
	v_mfma_f32_16x16x32_bf16 v[38:41], v[142:145], v[192:195], v[38:41]
	v_mfma_f32_16x16x32_bf16 v[30:33], v[150:153], v[192:195], v[30:33]
	v_mfma_f32_16x16x32_bf16 v[58:61], v[142:145], v[200:203], v[58:61]
	v_mfma_f32_16x16x32_bf16 v[54:57], v[150:153], v[200:203], v[54:57]
	v_mfma_f32_16x16x32_bf16 v[62:65], v[146:149], v[180:183], v[62:65]
	v_mfma_f32_16x16x32_bf16 v[42:45], v[156:159], v[180:183], v[42:45]
	v_mfma_f32_16x16x32_bf16 v[18:21], v[146:149], v[188:191], v[18:21]
	v_mfma_f32_16x16x32_bf16 v[14:17], v[156:159], v[188:191], v[14:17]
	v_mfma_f32_16x16x32_bf16 v[38:41], v[146:149], v[196:199], v[38:41]
	v_mfma_f32_16x16x32_bf16 v[30:33], v[156:159], v[196:199], v[30:33]
	v_mfma_f32_16x16x32_bf16 v[58:61], v[146:149], v[204:207], v[58:61]
	v_mfma_f32_16x16x32_bf16 v[54:57], v[156:159], v[204:207], v[54:57]
	v_mfma_f32_16x16x32_bf16 v[34:37], v[160:163], v[176:179], v[34:37]
	v_mfma_f32_16x16x32_bf16 v[2:5], v[168:171], v[176:179], v[2:5]
	v_mfma_f32_16x16x32_bf16 v[10:13], v[160:163], v[184:187], v[10:13]
	v_mfma_f32_16x16x32_bf16 v[6:9], v[168:171], v[184:187], v[6:9]
	v_mfma_f32_16x16x32_bf16 v[26:29], v[160:163], v[192:195], v[26:29]
	v_mfma_f32_16x16x32_bf16 v[22:25], v[168:171], v[192:195], v[22:25]
	v_mfma_f32_16x16x32_bf16 v[50:53], v[160:163], v[200:203], v[50:53]
	v_mfma_f32_16x16x32_bf16 v[46:49], v[168:171], v[200:203], v[46:49]
	v_mfma_f32_16x16x32_bf16 v[34:37], v[164:167], v[180:183], v[34:37]
	v_mfma_f32_16x16x32_bf16 v[2:5], v[172:175], v[180:183], v[2:5]
	v_mfma_f32_16x16x32_bf16 v[10:13], v[164:167], v[188:191], v[10:13]
	v_mfma_f32_16x16x32_bf16 v[6:9], v[172:175], v[188:191], v[6:9]
	v_mfma_f32_16x16x32_bf16 v[26:29], v[164:167], v[196:199], v[26:29]
	v_mfma_f32_16x16x32_bf16 v[22:25], v[172:175], v[196:199], v[22:25]
	v_mfma_f32_16x16x32_bf16 v[50:53], v[164:167], v[204:207], v[50:53]
	v_mfma_f32_16x16x32_bf16 v[46:49], v[172:175], v[204:207], v[46:49]
	s_barrier
; #define PG8_STAGE(bufoff, gbase, voff) do { _Pragma("unroll") for (int _i = 0; _i < 2; ++_i) \
;         __builtin_amdgcn_global_load_lds((const unsigned*)((const char*)(gbase) + (voff)[_i]), (LAS unsigned*)(lds + (bufoff) + ldsw + _i * 8192), 16, 0, 0); } while (0)
; #define PG8_LDA(dst, b, h) do { _Pragma("unroll") for (int m = 0; m < 4; ++m) _Pragma("unroll") for (int k = 0; k < 2; ++k) dst[m][k] = *(const LAS bf16x8*)(lds + PG8_SA(b, h) + aoff + m * 2048 + k * 1024); } while (0)
; #define PG8_MMA(ai, bj, At, Bt) do { __builtin_amdgcn_s_setprio(1); _Pragma("unroll") for (int m = 0; m < 4; ++m) _Pragma("unroll") for (int n = 0; n < 2; ++n) _Pragma("unroll") for (int k = 0; k < 2; ++k) \
;         acc[ai][bj][m][n] = __builtin_amdgcn_mfma_f32_16x16x32_bf16(Bt[n][k], At[m][k], acc[ai][bj][m][n], 0, 0, 0); __builtin_amdgcn_s_setprio(0); } while (0)
; #define PG8_WAIT_V(n) asm volatile("s_waitcnt vmcnt(" #n ")" ::: "memory")
; #define PG8_WAIT_L(n) asm volatile("s_waitcnt lgkmcnt(" #n ")" ::: "memory")
; #define PG8_BAR __builtin_amdgcn_s_barrier()
; #define PG8_SCHED __builtin_amdgcn_sched_barrier(0)
; template <class Epi, class Sched, bool ALIGN_EPI, bool LAST_FUSED = false, bool PERM = false, bool CARRY = false>
; __device__ __forceinline__ void gemm_phase(LAS unsigned char* lds, const int tid, const int K, const int lda, const int ldb, const Sched& S, const Epi& E) {
;     ...
;             PG8_LDA(At, 1, 1); PG8_STAGE(PG8_SB(1, 0), b3, voffB); PG8_STAGE(PG8_SB(1, 1), b3 + hstepB, voffB); PG8_STAGE(PG8_SA(1, 0), a3, voffA);
;             PG8_WAIT_V(8); PG8_WAIT_L(0); PG8_BAR; PG8_MMA(1, 0, At, B0); PG8_MMA(1, 1, At, B1); PG8_BAR; PG8_SCHED;
;         }
;         if constexpr (ALIGN_EPI) { if (wr == 0) PG8_BAR; }
	s_setprio 0
	s_add_i32 s52, s96, s87
	v_lshl_add_u64 v[208:209], v[208:209], 0, s[68:69]
	s_mov_b32 m0, s52
	ds_read_b128 v[176:179], v141 offset:49152
	ds_read_b128 v[180:183], v141 offset:50176
	ds_read_b128 v[184:187], v141 offset:51200
	ds_read_b128 v[188:191], v141 offset:52224
	ds_read_b128 v[192:195], v141 offset:53248
	ds_read_b128 v[196:199], v141 offset:54272
	ds_read_b128 v[200:203], v141 offset:55296
	ds_read_b128 v[204:207], v141 offset:56320
	global_load_lds_dwordx4 v[208:209], off
	s_add_i32 m0, s52, 0x2000
	s_add_u32 s52, s76, 0x80080
	v_lshl_add_u64 v[208:209], v[210:211], 0, s[68:69]
	s_addc_u32 s53, s77, 0
	s_add_i32 s76, s97, s87
	global_load_lds_dwordx4 v[208:209], off
	v_lshl_add_u64 v[208:209], s[52:53], 0, v[0:1]
	s_mov_b32 m0, s76
	s_nop 0
	global_load_lds_dwordx4 v[208:209], off
	v_lshl_add_u64 v[208:209], s[52:53], 0, v[122:123]
	s_add_i32 m0, s76, 0x2000
	s_nop 0
	global_load_lds_dwordx4 v[208:209], off
	v_lshl_add_u64 v[208:209], v[212:213], 0, s[68:69]
	s_mov_b32 m0, s85
	s_nop 0
	global_load_lds_dwordx4 v[208:209], off
	v_lshl_add_u64 v[208:209], v[214:215], 0, s[68:69]
	s_mov_b32 m0, s89
	s_nop 0
	global_load_lds_dwordx4 v[208:209], off
	s_waitcnt vmcnt(8)
	s_waitcnt lgkmcnt(0)
	s_barrier
	s_setprio 1
	v_mfma_f32_16x16x32_bf16 v[78:81], v[142:145], v[176:179], v[78:81]
	v_mfma_f32_16x16x32_bf16 v[74:77], v[150:153], v[176:179], v[74:77]
	v_mfma_f32_16x16x32_bf16 v[98:101], v[142:145], v[184:187], v[98:101]
	v_mfma_f32_16x16x32_bf16 v[94:97], v[150:153], v[184:187], v[94:97]
	v_mfma_f32_16x16x32_bf16 v[118:121], v[142:145], v[192:195], v[118:121]
	v_mfma_f32_16x16x32_bf16 v[114:117], v[150:153], v[192:195], v[114:117]
	v_mfma_f32_16x16x32_bf16 v[134:137], v[142:145], v[200:203], v[134:137]
	v_mfma_f32_16x16x32_bf16 v[130:133], v[150:153], v[200:203], v[130:133]
	v_mfma_f32_16x16x32_bf16 v[78:81], v[146:149], v[180:183], v[78:81]
	v_mfma_f32_16x16x32_bf16 v[74:77], v[156:159], v[180:183], v[74:77]
	v_mfma_f32_16x16x32_bf16 v[98:101], v[146:149], v[188:191], v[98:101]
	v_mfma_f32_16x16x32_bf16 v[94:97], v[156:159], v[188:191], v[94:97]
	v_mfma_f32_16x16x32_bf16 v[118:121], v[146:149], v[196:199], v[118:121]
	v_mfma_f32_16x16x32_bf16 v[114:117], v[156:159], v[196:199], v[114:117]
	v_mfma_f32_16x16x32_bf16 v[134:137], v[146:149], v[204:207], v[134:137]
	v_mfma_f32_16x16x32_bf16 v[130:133], v[156:159], v[204:207], v[130:133]
	v_mfma_f32_16x16x32_bf16 v[70:73], v[160:163], v[176:179], v[70:73]
	v_mfma_f32_16x16x32_bf16 v[66:69], v[168:171], v[176:179], v[66:69]
	v_mfma_f32_16x16x32_bf16 v[90:93], v[160:163], v[184:187], v[90:93]
	v_mfma_f32_16x16x32_bf16 v[86:89], v[168:171], v[184:187], v[86:89]
	v_mfma_f32_16x16x32_bf16 v[110:113], v[160:163], v[192:195], v[110:113]
	v_mfma_f32_16x16x32_bf16 v[106:109], v[168:171], v[192:195], v[106:109]
	v_mfma_f32_16x16x32_bf16 v[102:105], v[160:163], v[200:203], v[102:105]
	v_mfma_f32_16x16x32_bf16 v[82:85], v[168:171], v[200:203], v[82:85]
	v_mfma_f32_16x16x32_bf16 v[70:73], v[164:167], v[180:183], v[70:73]
	v_mfma_f32_16x16x32_bf16 v[66:69], v[172:175], v[180:183], v[66:69]
	v_mfma_f32_16x16x32_bf16 v[90:93], v[164:167], v[188:191], v[90:93]
	v_mfma_f32_16x16x32_bf16 v[86:89], v[172:175], v[188:191], v[86:89]
	v_mfma_f32_16x16x32_bf16 v[110:113], v[164:167], v[196:199], v[110:113]
	v_mfma_f32_16x16x32_bf16 v[106:109], v[172:175], v[196:199], v[106:109]
	v_mfma_f32_16x16x32_bf16 v[102:105], v[164:167], v[204:207], v[102:105]
	v_mfma_f32_16x16x32_bf16 v[82:85], v[172:175], v[204:207], v[82:85]
	s_barrier
	s_setprio 0
	s_add_i32 s52, s95, 2
	s_add_u32 s48, s48, 0x100
	s_addc_u32 s49, s49, 0
	v_lshl_add_u64 v[138:139], v[138:139], 0, s[72:73]
	v_lshl_add_u64 v[128:129], v[128:129], 0, s[72:73]
	s_cmp_ge_i32 s95, s3
	s_mov_b32 s95, s52
	s_cbranch_scc0 .LBB0_1585
	s_and_b64 vcc, exec, s[36:37]
	s_cbranch_vccz .LBB0_1588
	s_barrier

; #define PG8_STAGE(bufoff, gbase, voff) do { _Pragma("unroll") for (int _i = 0; _i < 2; ++_i) \
;         __builtin_amdgcn_global_load_lds((const unsigned*)((const char*)(gbase) + (voff)[_i]), (LAS unsigned*)(lds + (bufoff) + ldsw + _i * 8192), 16, 0, 0); } while (0)
; #define PG8_LDA(dst, b, h) do { _Pragma("unroll") for (int m = 0; m < 4; ++m) _Pragma("unroll") for (int k = 0; k < 2; ++k) dst[m][k] = *(const LAS bf16x8*)(lds + PG8_SA(b, h) + aoff + m * 2048 + k * 1024); } while (0)
; #define PG8_LDB(dst, b, h) do { _Pragma("unroll") for (int n = 0; n < 2; ++n) _Pragma("unroll") for (int k = 0; k < 2; ++k) dst[n][k] = *(const LAS bf16x8*)(lds + PG8_SB(b, h) + boff + n * 2048 + k * 1024); } while (0)
; #define PG8_WAIT_V(n) asm volatile("s_waitcnt vmcnt(" #n ")" ::: "memory")
; #define PG8_WAIT_L(n) asm volatile("s_waitcnt lgkmcnt(" #n ")" ::: "memory")
; #define PG8_BAR __builtin_amdgcn_s_barrier()
; #define PG8_SCHED __builtin_amdgcn_sched_barrier(0)
; template <class Epi, class Sched, bool ALIGN_EPI, bool LAST_FUSED = false, bool PERM = false, bool CARRY = false>
; __device__ __forceinline__ void gemm_phase(LAS unsigned char* lds, const int tid, const int K, const int lda, const int ldb, const Sched& S, const Epi& E) {
;     ...
;         const bool has_next = S.next(KD_IDX(ui + 1), nxt);
;         const char* nA = has_next ? nxt.a : cA; const char* nB = has_next ? nxt.b : cB; const int nt = cur.nt;
; #pragma unroll 1
;         for (int t = 0; t < nt; t += 2) {
;             const bool last = (t == nt - 2);
;             const char* a1 = cA + (size_t)(t + 1) * kstep;
;             const char* a2 = last ? nA : cA + (size_t)(t + 2) * kstep; const char* b2 = last ? nB : cB + (size_t)(t + 2) * kstep;
;             const char* a3 = a2 + kstep; const char* b3 = b2 + kstep;
;             PG8_LDB(B0, 0, 0); PG8_LDB(B1, 0, 1); PG8_SCHED; PG8_LDA(At, 0, 0); PG8_STAGE(PG8_SA(1, 1), a1 + hstepA, voffA);
;             PG8_WAIT_V(8); PG8_WAIT_L(0); PG8_BAR; PG8_MMA(0, 0, At, B0); PG8_MMA(0, 1, At, B1); PG8_BAR; PG8_SCHED;
;             PG8_LDA(At, 0, 1); PG8_STAGE(PG8_SB(0, 0), b2, voffB); PG8_STAGE(PG8_SB(0, 1), b2 + hstepB, voffB); PG8_STAGE(PG8_SA(0, 0), a2, voffA);
;             PG8_WAIT_V(8); PG8_WAIT_L(0); PG8_BAR; PG8_MMA(1, 0, At, B0); PG8_MMA(1, 1, At, B1); PG8_BAR; PG8_SCHED;
.LBB0_1662:
	s_add_u32 s52, s38, s48
	s_addc_u32 s53, s39, s49
	s_add_u32 s66, s40, s48
	s_addc_u32 s67, s41, s49
	s_waitcnt lgkmcnt(0)
	s_add_i32 s90, 0, 0x10000
	s_cmp_eq_u32 s3, s89
	s_cselect_b32 s53, s24, s53
	s_cselect_b32 s52, s85, s52
	s_cselect_b32 s67, s86, s67
	s_cselect_b32 s66, s87, s66
	s_add_i32 s92, 0, 0x14000
	v_add_u32_e32 v156, s90, v140
	v_add_u32_e32 v172, s92, v140
	ds_read_b128 v[142:145], v156
	ds_read_b128 v[146:149], v156 offset:1024
	ds_read_b128 v[150:153], v156 offset:2048
	ds_read_b128 v[156:159], v156 offset:3072
	ds_read_b128 v[160:163], v172
	ds_read_b128 v[164:167], v172 offset:1024
	ds_read_b128 v[168:171], v172 offset:2048
	ds_read_b128 v[172:175], v172 offset:3072
	v_lshl_add_u64 v[208:209], s[38:39], 0, v[138:139]
	s_add_i32 m0, s35, 0xc000
	ds_read_b128 v[176:179], v141
	ds_read_b128 v[180:183], v141 offset:1024
	ds_read_b128 v[184:187], v141 offset:2048
	ds_read_b128 v[188:191], v141 offset:3072
	ds_read_b128 v[192:195], v141 offset:4096
	ds_read_b128 v[196:199], v141 offset:5120
	ds_read_b128 v[200:203], v141 offset:6144
	ds_read_b128 v[204:207], v141 offset:7168
	global_load_lds_dwordx4 v[208:209], off
	v_lshl_add_u64 v[208:209], s[38:39], 0, v[128:129]
	s_add_i32 m0, s35, 0xe000
	s_nop 0
	global_load_lds_dwordx4 v[208:209], off
	s_waitcnt vmcnt(8)
	s_waitcnt lgkmcnt(0)
	s_barrier
	s_setprio 1
	v_mfma_f32_16x16x32_bf16 v[62:65], v[142:145], v[176:179], v[62:65]
	v_mfma_f32_16x16x32_bf16 v[42:45], v[150:153], v[176:179], v[42:45]
	v_mfma_f32_16x16x32_bf16 v[18:21], v[142:145], v[184:187], v[18:21]
	v_mfma_f32_16x16x32_bf16 v[14:17], v[150:153], v[184:187], v[14:17]
	v_mfma_f32_16x16x32_bf16 v[38:41], v[142:145], v[192:195], v[38:41]
	v_mfma_f32_16x16x32_bf16 v[30:33], v[150:153], v[192:195], v[30:33]
	v_mfma_f32_16x16x32_bf16 v[58:61], v[142:145], v[200:203], v[58:61]
	v_mfma_f32_16x16x32_bf16 v[54:57], v[150:153], v[200:203], v[54:57]
	v_mfma_f32_16x16x32_bf16 v[62:65], v[146:149], v[180:183], v[62:65]
	v_mfma_f32_16x16x32_bf16 v[42:45], v[156:159], v[180:183], v[42:45]
	v_mfma_f32_16x16x32_bf16 v[18:21], v[146:149], v[188:191], v[18:21]
	v_mfma_f32_16x16x32_bf16 v[14:17], v[156:159], v[188:191], v[14:17]
	v_mfma_f32_16x16x32_bf16 v[38:41], v[146:149], v[196:199], v[38:41]
	v_mfma_f32_16x16x32_bf16 v[30:33], v[156:159], v[196:199], v[30:33]
	v_mfma_f32_16x16x32_bf16 v[58:61], v[146:149], v[204:207], v[58:61]
	v_mfma_f32_16x16x32_bf16 v[54:57], v[156:159], v[204:207], v[54:57]
	v_mfma_f32_16x16x32_bf16 v[34:37], v[160:163], v[176:179], v[34:37]
	v_mfma_f32_16x16x32_bf16 v[2:5], v[168:171], v[176:179], v[2:5]
	v_mfma_f32_16x16x32_bf16 v[10:13], v[160:163], v[184:187], v[10:13]
	v_mfma_f32_16x16x32_bf16 v[6:9], v[168:171], v[184:187], v[6:9]
	v_mfma_f32_16x16x32_bf16 v[26:29], v[160:163], v[192:195], v[26:29]
	v_mfma_f32_16x16x32_bf16 v[22:25], v[168:171], v[192:195], v[22:25]
	v_mfma_f32_16x16x32_bf16 v[50:53], v[160:163], v[200:203], v[50:53]
	v_mfma_f32_16x16x32_bf16 v[46:49], v[168:171], v[200:203], v[46:49]
	v_mfma_f32_16x16x32_bf16 v[34:37], v[164:167], v[180:183], v[34:37]
	v_mfma_f32_16x16x32_bf16 v[2:5], v[172:175], v[180:183], v[2:5]
	v_mfma_f32_16x16x32_bf16 v[10:13], v[164:167], v[188:191], v[10:13]
	v_mfma_f32_16x16x32_bf16 v[6:9], v[172:175], v[188:191], v[6:9]
	v_mfma_f32_16x16x32_bf16 v[26:29], v[164:167], v[196:199], v[26:29]
	v_mfma_f32_16x16x32_bf16 v[22:25], v[172:175], v[196:199], v[22:25]
	v_mfma_f32_16x16x32_bf16 v[50:53], v[164:167], v[204:207], v[50:53]
	v_mfma_f32_16x16x32_bf16 v[46:49], v[172:175], v[204:207], v[46:49]
	s_barrier
	s_setprio 0
	s_add_i32 s90, s90, s76
	v_lshl_add_u64 v[208:209], s[66:67], 0, v[0:1]
	s_mov_b32 m0, s90
	ds_read_b128 v[176:179], v141 offset:16384
	ds_read_b128 v[180:183], v141 offset:17408
	ds_read_b128 v[184:187], v141 offset:18432
	ds_read_b128 v[188:191], v141 offset:19456
	ds_read_b128 v[192:195], v141 offset:20480
	ds_read_b128 v[196:199], v141 offset:21504
	ds_read_b128 v[200:203], v141 offset:22528
	ds_read_b128 v[204:207], v141 offset:23552
	global_load_lds_dwordx4 v[208:209], off
	s_add_i32 m0, s90, 0x2000
	s_add_u32 s90, s66, 0x100000
	v_lshl_add_u64 v[210:211], s[66:67], 0, v[122:123]
	s_addc_u32 s91, s67, 0
	s_add_i32 s92, s92, s76
	global_load_lds_dwordx4 v[210:211], off
	v_lshl_add_u64 v[212:213], s[90:91], 0, v[0:1]
	s_mov_b32 m0, s92
	v_lshl_add_u64 v[214:215], s[52:53], 0, v[122:123]
	global_load_lds_dwordx4 v[212:213], off
	v_lshl_add_u64 v[212:213], s[90:91], 0, v[122:123]
	s_add_i32 m0, s92, 0x2000
	s_nop 0
	global_load_lds_dwordx4 v[212:213], off
	v_lshl_add_u64 v[212:213], s[52:53], 0, v[0:1]
	s_mov_b32 m0, s35
	s_nop 0
	global_load_lds_dwordx4 v[212:213], off
	s_mov_b32 m0, s28
	s_nop 0
	global_load_lds_dwordx4 v[214:215], off
	s_waitcnt vmcnt(8)
	s_waitcnt lgkmcnt(0)
	s_barrier
; #define PG8_STAGE(bufoff, gbase, voff) do { _Pragma("unroll") for (int _i = 0; _i < 2; ++_i) \
;         __builtin_amdgcn_global_load_lds((const unsigned*)((const char*)(gbase) + (voff)[_i]), (LAS unsigned*)(lds + (bufoff) + ldsw + _i * 8192), 16, 0, 0); } while (0)
; #define PG8_LDA(dst, b, h) do { _Pragma("unroll") for (int m = 0; m < 4; ++m) _Pragma("unroll") for (int k = 0; k < 2; ++k) dst[m][k] = *(const LAS bf16x8*)(lds + PG8_SA(b, h) + aoff + m * 2048 + k * 1024); } while (0)
; #define PG8_LDB(dst, b, h) do { _Pragma("unroll") for (int n = 0; n < 2; ++n) _Pragma("unroll") for (int k = 0; k < 2; ++k) dst[n][k] = *(const LAS bf16x8*)(lds + PG8_SB(b, h) + boff + n * 2048 + k * 1024); } while (0)
; #define PG8_MMA(ai, bj, At, Bt) do { __builtin_amdgcn_s_setprio(1); _Pragma("unroll") for (int m = 0; m < 4; ++m) _Pragma("unroll") for (int n = 0; n < 2; ++n) _Pragma("unroll") for (int k = 0; k < 2; ++k) \
;         acc[ai][bj][m][n] = __builtin_amdgcn_mfma_f32_16x16x32_bf16(Bt[n][k], At[m][k], acc[ai][bj][m][n], 0, 0, 0); __builtin_amdgcn_s_setprio(0); } while (0)
; #define PG8_WAIT_V(n) asm volatile("s_waitcnt vmcnt(" #n ")" ::: "memory")
; #define PG8_WAIT_L(n) asm volatile("s_waitcnt lgkmcnt(" #n ")" ::: "memory")
; #define PG8_BAR __builtin_amdgcn_s_barrier()
; #define PG8_SCHED __builtin_amdgcn_sched_barrier(0)
; template <class Epi, class Sched, bool ALIGN_EPI, bool LAST_FUSED = false, bool PERM = false, bool CARRY = false>
; __device__ __forceinline__ void gemm_phase(LAS unsigned char* lds, const int tid, const int K, const int lda, const int ldb, const Sched& S, const Epi& E) {
;     ...
;             PG8_WAIT_V(8); PG8_WAIT_L(0); PG8_BAR; PG8_MMA(1, 0, At, B0); PG8_MMA(1, 1, At, B1); PG8_BAR; PG8_SCHED;
;             PG8_LDB(B0, 1, 0); PG8_LDB(B1, 1, 1); PG8_SCHED; PG8_LDA(At, 1, 0); PG8_STAGE(PG8_SA(0, 1), a2 + hstepA, voffA);
;             PG8_WAIT_V(8); PG8_WAIT_L(0); PG8_BAR; PG8_MMA(0, 0, At, B0); PG8_MMA(0, 1, At, B1); PG8_BAR; PG8_SCHED;
	s_setprio 1
	v_mfma_f32_16x16x32_bf16 v[78:81], v[142:145], v[176:179], v[78:81]
	v_mfma_f32_16x16x32_bf16 v[74:77], v[150:153], v[176:179], v[74:77]
	v_mfma_f32_16x16x32_bf16 v[98:101], v[142:145], v[184:187], v[98:101]
	v_mfma_f32_16x16x32_bf16 v[94:97], v[150:153], v[184:187], v[94:97]
	v_mfma_f32_16x16x32_bf16 v[118:121], v[142:145], v[192:195], v[118:121]
	v_mfma_f32_16x16x32_bf16 v[114:117], v[150:153], v[192:195], v[114:117]
	v_mfma_f32_16x16x32_bf16 v[134:137], v[142:145], v[200:203], v[134:137]
	v_mfma_f32_16x16x32_bf16 v[130:133], v[150:153], v[200:203], v[130:133]
	v_mfma_f32_16x16x32_bf16 v[78:81], v[146:149], v[180:183], v[78:81]
	v_mfma_f32_16x16x32_bf16 v[74:77], v[156:159], v[180:183], v[74:77]
	v_mfma_f32_16x16x32_bf16 v[98:101], v[146:149], v[188:191], v[98:101]
	v_mfma_f32_16x16x32_bf16 v[94:97], v[156:159], v[188:191], v[94:97]
	v_mfma_f32_16x16x32_bf16 v[118:121], v[146:149], v[196:199], v[118:121]
	v_mfma_f32_16x16x32_bf16 v[114:117], v[156:159], v[196:199], v[114:117]
	v_mfma_f32_16x16x32_bf16 v[134:137], v[146:149], v[204:207], v[134:137]
	v_mfma_f32_16x16x32_bf16 v[130:133], v[156:159], v[204:207], v[130:133]
	v_mfma_f32_16x16x32_bf16 v[70:73], v[160:163], v[176:179], v[70:73]
	v_mfma_f32_16x16x32_bf16 v[66:69], v[168:171], v[176:179], v[66:69]
	v_mfma_f32_16x16x32_bf16 v[90:93], v[160:163], v[184:187], v[90:93]
	v_mfma_f32_16x16x32_bf16 v[86:89], v[168:171], v[184:187], v[86:89]
	v_mfma_f32_16x16x32_bf16 v[110:113], v[160:163], v[192:195], v[110:113]
	v_mfma_f32_16x16x32_bf16 v[106:109], v[168:171], v[192:195], v[106:109]
	v_mfma_f32_16x16x32_bf16 v[102:105], v[160:163], v[200:203], v[102:105]
	v_mfma_f32_16x16x32_bf16 v[82:85], v[168:171], v[200:203], v[82:85]
	v_mfma_f32_16x16x32_bf16 v[70:73], v[164:167], v[180:183], v[70:73]
	v_mfma_f32_16x16x32_bf16 v[66:69], v[172:175], v[180:183], v[66:69]
	v_mfma_f32_16x16x32_bf16 v[90:93], v[164:167], v[188:191], v[90:93]
	v_mfma_f32_16x16x32_bf16 v[86:89], v[172:175], v[188:191], v[86:89]
	v_mfma_f32_16x16x32_bf16 v[110:113], v[164:167], v[196:199], v[110:113]
	v_mfma_f32_16x16x32_bf16 v[106:109], v[172:175], v[196:199], v[106:109]
	v_mfma_f32_16x16x32_bf16 v[102:105], v[164:167], v[204:207], v[102:105]
	v_mfma_f32_16x16x32_bf16 v[82:85], v[172:175], v[204:207], v[82:85]
	s_barrier
	s_setprio 0
	s_add_i32 s90, 0, 0x18000
	s_add_i32 s91, 0, 0x1c000
	v_add_u32_e32 v156, s90, v140
	v_add_u32_e32 v172, s91, v140
	ds_read_b128 v[142:145], v156
	ds_read_b128 v[146:149], v156 offset:1024
	ds_read_b128 v[150:153], v156 offset:2048
	ds_read_b128 v[156:159], v156 offset:3072
	ds_read_b128 v[160:163], v172
	ds_read_b128 v[164:167], v172 offset:1024
	ds_read_b128 v[168:171], v172 offset:2048
	ds_read_b128 v[172:175], v172 offset:3072
	s_add_u32 s52, s52, 0x100000
	s_addc_u32 s53, s53, 0
	s_mov_b32 m0, s29
	v_lshl_add_u64 v[216:217], s[52:53], 0, v[0:1]
	ds_read_b128 v[176:179], v141 offset:32768
	ds_read_b128 v[180:183], v141 offset:33792
	ds_read_b128 v[184:187], v141 offset:34816
	ds_read_b128 v[188:191], v141 offset:35840
	ds_read_b128 v[192:195], v141 offset:36864
	ds_read_b128 v[196:199], v141 offset:37888
	ds_read_b128 v[200:203], v141 offset:38912
	ds_read_b128 v[204:207], v141 offset:39936
	global_load_lds_dwordx4 v[216:217], off
	v_lshl_add_u64 v[216:217], s[52:53], 0, v[122:123]
	s_mov_b32 m0, s14
	s_nop 0
	global_load_lds_dwordx4 v[216:217], off
	s_waitcnt vmcnt(8)
	s_waitcnt lgkmcnt(0)
	s_barrier
	s_setprio 1
	v_mfma_f32_16x16x32_bf16 v[62:65], v[142:145], v[176:179], v[62:65]
	v_mfma_f32_16x16x32_bf16 v[42:45], v[150:153], v[176:179], v[42:45]
	v_mfma_f32_16x16x32_bf16 v[18:21], v[142:145], v[184:187], v[18:21]
	v_mfma_f32_16x16x32_bf16 v[14:17], v[150:153], v[184:187], v[14:17]
	v_mfma_f32_16x16x32_bf16 v[38:41], v[142:145], v[192:195], v[38:41]
	v_mfma_f32_16x16x32_bf16 v[30:33], v[150:153], v[192:195], v[30:33]
	v_mfma_f32_16x16x32_bf16 v[58:61], v[142:145], v[200:203], v[58:61]
	v_mfma_f32_16x16x32_bf16 v[54:57], v[150:153], v[200:203], v[54:57]
	v_mfma_f32_16x16x32_bf16 v[62:65], v[146:149], v[180:183], v[62:65]
	v_mfma_f32_16x16x32_bf16 v[42:45], v[156:159], v[180:183], v[42:45]
	v_mfma_f32_16x16x32_bf16 v[18:21], v[146:149], v[188:191], v[18:21]
	v_mfma_f32_16x16x32_bf16 v[14:17], v[156:159], v[188:191], v[14:17]
	v_mfma_f32_16x16x32_bf16 v[38:41], v[146:149], v[196:199], v[38:41]
	v_mfma_f32_16x16x32_bf16 v[30:33], v[156:159], v[196:199], v[30:33]
	v_mfma_f32_16x16x32_bf16 v[58:61], v[146:149], v[204:207], v[58:61]
	v_mfma_f32_16x16x32_bf16 v[54:57], v[156:159], v[204:207], v[54:57]
	v_mfma_f32_16x16x32_bf16 v[34:37], v[160:163], v[176:179], v[34:37]
	v_mfma_f32_16x16x32_bf16 v[2:5], v[168:171], v[176:179], v[2:5]
	v_mfma_f32_16x16x32_bf16 v[10:13], v[160:163], v[184:187], v[10:13]
	v_mfma_f32_16x16x32_bf16 v[6:9], v[168:171], v[184:187], v[6:9]
	v_mfma_f32_16x16x32_bf16 v[26:29], v[160:163], v[192:195], v[26:29]
	v_mfma_f32_16x16x32_bf16 v[22:25], v[168:171], v[192:195], v[22:25]
	v_mfma_f32_16x16x32_bf16 v[50:53], v[160:163], v[200:203], v[50:53]
	v_mfma_f32_16x16x32_bf16 v[46:49], v[168:171], v[200:203], v[46:49]
	v_mfma_f32_16x16x32_bf16 v[34:37], v[164:167], v[180:183], v[34:37]
	v_mfma_f32_16x16x32_bf16 v[2:5], v[172:175], v[180:183], v[2:5]
	v_mfma_f32_16x16x32_bf16 v[10:13], v[164:167], v[188:191], v[10:13]
	v_mfma_f32_16x16x32_bf16 v[6:9], v[172:175], v[188:191], v[6:9]
	v_mfma_f32_16x16x32_bf16 v[26:29], v[164:167], v[196:199], v[26:29]
	v_mfma_f32_16x16x32_bf16 v[22:25], v[172:175], v[196:199], v[22:25]
	v_mfma_f32_16x16x32_bf16 v[50:53], v[164:167], v[204:207], v[50:53]
	v_mfma_f32_16x16x32_bf16 v[46:49], v[172:175], v[204:207], v[46:49]
	s_barrier
; #define PG8_STAGE(bufoff, gbase, voff) do { _Pragma("unroll") for (int _i = 0; _i < 2; ++_i) \
;         __builtin_amdgcn_global_load_lds((const unsigned*)((const char*)(gbase) + (voff)[_i]), (LAS unsigned*)(lds + (bufoff) + ldsw + _i * 8192), 16, 0, 0); } while (0)
; #define PG8_LDA(dst, b, h) do { _Pragma("unroll") for (int m = 0; m < 4; ++m) _Pragma("unroll") for (int k = 0; k < 2; ++k) dst[m][k] = *(const LAS bf16x8*)(lds + PG8_SA(b, h) + aoff + m * 2048 + k * 1024); } while (0)
; #define PG8_MMA(ai, bj, At, Bt) do { __builtin_amdgcn_s_setprio(1); _Pragma("unroll") for (int m = 0; m < 4; ++m) _Pragma("unroll") for (int n = 0; n < 2; ++n) _Pragma("unroll") for (int k = 0; k < 2; ++k) \
;         acc[ai][bj][m][n] = __builtin_amdgcn_mfma_f32_16x16x32_bf16(Bt[n][k], At[m][k], acc[ai][bj][m][n], 0, 0, 0); __builtin_amdgcn_s_setprio(0); } while (0)
; #define PG8_WAIT_V(n) asm volatile("s_waitcnt vmcnt(" #n ")" ::: "memory")
; #define PG8_WAIT_L(n) asm volatile("s_waitcnt lgkmcnt(" #n ")" ::: "memory")
; #define PG8_BAR __builtin_amdgcn_s_barrier()
; #define PG8_SCHED __builtin_amdgcn_sched_barrier(0)
; template <class Epi, class Sched, bool ALIGN_EPI, bool LAST_FUSED = false, bool PERM = false, bool CARRY = false>
; __device__ __forceinline__ void gemm_phase(LAS unsigned char* lds, const int tid, const int K, const int lda, const int ldb, const Sched& S, const Epi& E) {
;     ...
;             PG8_LDA(At, 1, 1); PG8_STAGE(PG8_SB(1, 0), b3, voffB); PG8_STAGE(PG8_SB(1, 1), b3 + hstepB, voffB); PG8_STAGE(PG8_SA(1, 0), a3, voffA);
;             PG8_WAIT_V(8); PG8_WAIT_L(0); PG8_BAR; PG8_MMA(1, 0, At, B0); PG8_MMA(1, 1, At, B1); PG8_BAR; PG8_SCHED;
;         }
;         if constexpr (ALIGN_EPI) { if (wr == 0) PG8_BAR; }
	s_setprio 0
	s_add_i32 s52, s90, s76
	v_lshl_add_u64 v[208:209], v[208:209], 0, s[68:69]
	s_mov_b32 m0, s52
	ds_read_b128 v[176:179], v141 offset:49152
	ds_read_b128 v[180:183], v141 offset:50176
	ds_read_b128 v[184:187], v141 offset:51200
	ds_read_b128 v[188:191], v141 offset:52224
	ds_read_b128 v[192:195], v141 offset:53248
	ds_read_b128 v[196:199], v141 offset:54272
	ds_read_b128 v[200:203], v141 offset:55296
	ds_read_b128 v[204:207], v141 offset:56320
	global_load_lds_dwordx4 v[208:209], off
	s_add_i32 m0, s52, 0x2000
	s_add_u32 s52, s66, 0x100080
	v_lshl_add_u64 v[208:209], v[210:211], 0, s[68:69]
	s_addc_u32 s53, s67, 0
	s_add_i32 s66, s91, s76
	global_load_lds_dwordx4 v[208:209], off
	v_lshl_add_u64 v[208:209], s[52:53], 0, v[0:1]
	s_mov_b32 m0, s66
	s_nop 0
	global_load_lds_dwordx4 v[208:209], off
	v_lshl_add_u64 v[208:209], s[52:53], 0, v[122:123]
	s_add_i32 m0, s66, 0x2000
	s_nop 0
	global_load_lds_dwordx4 v[208:209], off
	v_lshl_add_u64 v[208:209], v[212:213], 0, s[68:69]
	s_mov_b32 m0, s77
	s_nop 0
	global_load_lds_dwordx4 v[208:209], off
	v_lshl_add_u64 v[208:209], v[214:215], 0, s[68:69]
	s_mov_b32 m0, s79
	s_nop 0
	global_load_lds_dwordx4 v[208:209], off
	s_waitcnt vmcnt(8)
	s_waitcnt lgkmcnt(0)
	s_barrier
	s_setprio 1
	v_mfma_f32_16x16x32_bf16 v[78:81], v[142:145], v[176:179], v[78:81]
	v_mfma_f32_16x16x32_bf16 v[74:77], v[150:153], v[176:179], v[74:77]
	v_mfma_f32_16x16x32_bf16 v[98:101], v[142:145], v[184:187], v[98:101]
	v_mfma_f32_16x16x32_bf16 v[94:97], v[150:153], v[184:187], v[94:97]
	v_mfma_f32_16x16x32_bf16 v[118:121], v[142:145], v[192:195], v[118:121]
	v_mfma_f32_16x16x32_bf16 v[114:117], v[150:153], v[192:195], v[114:117]
	v_mfma_f32_16x16x32_bf16 v[134:137], v[142:145], v[200:203], v[134:137]
	v_mfma_f32_16x16x32_bf16 v[130:133], v[150:153], v[200:203], v[130:133]
	v_mfma_f32_16x16x32_bf16 v[78:81], v[146:149], v[180:183], v[78:81]
	v_mfma_f32_16x16x32_bf16 v[74:77], v[156:159], v[180:183], v[74:77]
	v_mfma_f32_16x16x32_bf16 v[98:101], v[146:149], v[188:191], v[98:101]
	v_mfma_f32_16x16x32_bf16 v[94:97], v[156:159], v[188:191], v[94:97]
	v_mfma_f32_16x16x32_bf16 v[118:121], v[146:149], v[196:199], v[118:121]
	v_mfma_f32_16x16x32_bf16 v[114:117], v[156:159], v[196:199], v[114:117]
	v_mfma_f32_16x16x32_bf16 v[134:137], v[146:149], v[204:207], v[134:137]
	v_mfma_f32_16x16x32_bf16 v[130:133], v[156:159], v[204:207], v[130:133]
	v_mfma_f32_16x16x32_bf16 v[70:73], v[160:163], v[176:179], v[70:73]
	v_mfma_f32_16x16x32_bf16 v[66:69], v[168:171], v[176:179], v[66:69]
	v_mfma_f32_16x16x32_bf16 v[90:93], v[160:163], v[184:187], v[90:93]
	v_mfma_f32_16x16x32_bf16 v[86:89], v[168:171], v[184:187], v[86:89]
	v_mfma_f32_16x16x32_bf16 v[110:113], v[160:163], v[192:195], v[110:113]
	v_mfma_f32_16x16x32_bf16 v[106:109], v[168:171], v[192:195], v[106:109]
	v_mfma_f32_16x16x32_bf16 v[102:105], v[160:163], v[200:203], v[102:105]
	v_mfma_f32_16x16x32_bf16 v[82:85], v[168:171], v[200:203], v[82:85]
	v_mfma_f32_16x16x32_bf16 v[70:73], v[164:167], v[180:183], v[70:73]
	v_mfma_f32_16x16x32_bf16 v[66:69], v[172:175], v[180:183], v[66:69]
	v_mfma_f32_16x16x32_bf16 v[90:93], v[164:167], v[188:191], v[90:93]
	v_mfma_f32_16x16x32_bf16 v[86:89], v[172:175], v[188:191], v[86:89]
	v_mfma_f32_16x16x32_bf16 v[110:113], v[164:167], v[196:199], v[110:113]
	v_mfma_f32_16x16x32_bf16 v[106:109], v[172:175], v[196:199], v[106:109]
	v_mfma_f32_16x16x32_bf16 v[102:105], v[164:167], v[204:207], v[102:105]
	v_mfma_f32_16x16x32_bf16 v[82:85], v[172:175], v[204:207], v[82:85]
	s_barrier
	s_setprio 0
	s_add_i32 s52, s89, 2
	s_add_u32 s48, s48, 0x100
	s_addc_u32 s49, s49, 0
	v_lshl_add_u64 v[138:139], v[138:139], 0, s[72:73]
	v_lshl_add_u64 v[128:129], v[128:129], 0, s[72:73]
	s_cmp_ge_i32 s89, s3
	s_mov_b32 s89, s52
	s_cbranch_scc0 .LBB0_1662
	s_and_b64 vcc, exec, s[36:37]
	s_cbranch_vccz .LBB0_1665
	s_barrier

; #define PG8_STAGE(bufoff, gbase, voff) do { _Pragma("unroll") for (int _i = 0; _i < 2; ++_i) \
;         __builtin_amdgcn_global_load_lds((const unsigned*)((const char*)(gbase) + (voff)[_i]), (LAS unsigned*)(lds + (bufoff) + ldsw + _i * 8192), 16, 0, 0); } while (0)
; #define PG8_LDA(dst, b, h) do { _Pragma("unroll") for (int m = 0; m < 4; ++m) _Pragma("unroll") for (int k = 0; k < 2; ++k) dst[m][k] = *(const LAS bf16x8*)(lds + PG8_SA(b, h) + aoff + m * 2048 + k * 1024); } while (0)
; #define PG8_LDB(dst, b, h) do { _Pragma("unroll") for (int n = 0; n < 2; ++n) _Pragma("unroll") for (int k = 0; k < 2; ++k) dst[n][k] = *(const LAS bf16x8*)(lds + PG8_SB(b, h) + boff + n * 2048 + k * 1024); } while (0)
; #define PG8_WAIT_V(n) asm volatile("s_waitcnt vmcnt(" #n ")" ::: "memory")
; #define PG8_WAIT_L(n) asm volatile("s_waitcnt lgkmcnt(" #n ")" ::: "memory")
; #define PG8_BAR __builtin_amdgcn_s_barrier()
; #define PG8_SCHED __builtin_amdgcn_sched_barrier(0)
; template <class Epi, class Sched, bool ALIGN_EPI, bool LAST_FUSED = false, bool PERM = false, bool CARRY = false>
; __device__ __forceinline__ void gemm_phase(LAS unsigned char* lds, const int tid, const int K, const int lda, const int ldb, const Sched& S, const Epi& E) {
;     ...
;         const bool has_next = S.next(KD_IDX(ui + 1), nxt);
;         const char* nA = has_next ? nxt.a : cA; const char* nB = has_next ? nxt.b : cB; const int nt = cur.nt;
; #pragma unroll 1
;         for (int t = 0; t < nt; t += 2) {
;             const bool last = (t == nt - 2);
;             const char* a1 = cA + (size_t)(t + 1) * kstep;
;             const char* a2 = last ? nA : cA + (size_t)(t + 2) * kstep; const char* b2 = last ? nB : cB + (size_t)(t + 2) * kstep;
;             const char* a3 = a2 + kstep; const char* b3 = b2 + kstep;
;             PG8_LDB(B0, 0, 0); PG8_LDB(B1, 0, 1); PG8_SCHED; PG8_LDA(At, 0, 0); PG8_STAGE(PG8_SA(1, 1), a1 + hstepA, voffA);
;             PG8_WAIT_V(8); PG8_WAIT_L(0); PG8_BAR; PG8_MMA(0, 0, At, B0); PG8_MMA(0, 1, At, B1); PG8_BAR; PG8_SCHED;
;             PG8_LDA(At, 0, 1); PG8_STAGE(PG8_SB(0, 0), b2, voffB); PG8_STAGE(PG8_SB(0, 1), b2 + hstepB, voffB); PG8_STAGE(PG8_SA(0, 0), a2, voffA);
;             PG8_WAIT_V(8); PG8_WAIT_L(0); PG8_BAR; PG8_MMA(1, 0, At, B0); PG8_MMA(1, 1, At, B1); PG8_BAR; PG8_SCHED;
.LBB0_1763:
	s_add_u32 s16, s48, 0xfff80080
	s_addc_u32 s17, s49, -1
	s_add_i32 s67, 0, 0x10000
	s_cmp_eq_u32 s41, 28
	s_cselect_b32 s53, s43, s17
	s_cselect_b32 s52, s42, s16
	v_add_u32_e32 v140, s67, v146
	s_cselect_b32 s55, s51, s39
	s_cselect_b32 s54, s50, s27
	s_add_i32 s16, 0, 0x14000
	ds_read_b128 v[148:151], v140
	ds_read_b128 v[152:155], v140 offset:1024
	ds_read_b128 v[156:159], v140 offset:2048
	ds_read_b128 v[160:163], v140 offset:3072
	v_add_u32_e32 v140, s16, v146
	ds_read_b128 v[164:167], v140
	ds_read_b128 v[168:171], v140 offset:1024
	ds_read_b128 v[172:175], v140 offset:2048
	ds_read_b128 v[176:179], v140 offset:3072
	v_lshl_add_u64 v[140:141], s[48:49], 0, v[136:137]
	s_add_i32 m0, s47, 0xc000
	ds_read_b128 v[180:183], v147
	ds_read_b128 v[184:187], v147 offset:1024
	ds_read_b128 v[188:191], v147 offset:2048
	ds_read_b128 v[192:195], v147 offset:3072
	ds_read_b128 v[196:199], v147 offset:4096
	ds_read_b128 v[200:203], v147 offset:5120
	ds_read_b128 v[204:207], v147 offset:6144
	ds_read_b128 v[208:211], v147 offset:7168
	global_load_lds_dwordx4 v[140:141], off
	v_lshl_add_u64 v[140:141], s[48:49], 0, v[138:139]
	s_add_i32 m0, s47, 0xe000
	s_nop 0
	global_load_lds_dwordx4 v[140:141], off
	s_waitcnt vmcnt(8)
	s_waitcnt lgkmcnt(0)
	s_barrier
	s_setprio 1
	v_mfma_f32_16x16x32_bf16 v[126:129], v[148:151], v[180:183], v[126:129]
	v_mfma_f32_16x16x32_bf16 v[122:125], v[156:159], v[180:183], v[122:125]
	v_mfma_f32_16x16x32_bf16 v[110:113], v[148:151], v[188:191], v[110:113]
	v_mfma_f32_16x16x32_bf16 v[106:109], v[156:159], v[188:191], v[106:109]
	v_mfma_f32_16x16x32_bf16 v[94:97], v[148:151], v[196:199], v[94:97]
	v_mfma_f32_16x16x32_bf16 v[90:93], v[156:159], v[196:199], v[90:93]
	v_mfma_f32_16x16x32_bf16 v[78:81], v[148:151], v[204:207], v[78:81]
	v_mfma_f32_16x16x32_bf16 v[74:77], v[156:159], v[204:207], v[74:77]
	v_mfma_f32_16x16x32_bf16 v[126:129], v[152:155], v[184:187], v[126:129]
	v_mfma_f32_16x16x32_bf16 v[122:125], v[160:163], v[184:187], v[122:125]
	v_mfma_f32_16x16x32_bf16 v[110:113], v[152:155], v[192:195], v[110:113]
	v_mfma_f32_16x16x32_bf16 v[106:109], v[160:163], v[192:195], v[106:109]
	v_mfma_f32_16x16x32_bf16 v[94:97], v[152:155], v[200:203], v[94:97]
	v_mfma_f32_16x16x32_bf16 v[90:93], v[160:163], v[200:203], v[90:93]
	v_mfma_f32_16x16x32_bf16 v[78:81], v[152:155], v[208:211], v[78:81]
	v_mfma_f32_16x16x32_bf16 v[74:77], v[160:163], v[208:211], v[74:77]
	v_mfma_f32_16x16x32_bf16 v[118:121], v[164:167], v[180:183], v[118:121]
	v_mfma_f32_16x16x32_bf16 v[114:117], v[172:175], v[180:183], v[114:117]
	v_mfma_f32_16x16x32_bf16 v[102:105], v[164:167], v[188:191], v[102:105]
	v_mfma_f32_16x16x32_bf16 v[98:101], v[172:175], v[188:191], v[98:101]
	v_mfma_f32_16x16x32_bf16 v[86:89], v[164:167], v[196:199], v[86:89]
	v_mfma_f32_16x16x32_bf16 v[82:85], v[172:175], v[196:199], v[82:85]
	v_mfma_f32_16x16x32_bf16 v[70:73], v[164:167], v[204:207], v[70:73]
	v_mfma_f32_16x16x32_bf16 v[66:69], v[172:175], v[204:207], v[66:69]
	v_mfma_f32_16x16x32_bf16 v[118:121], v[168:171], v[184:187], v[118:121]
	v_mfma_f32_16x16x32_bf16 v[114:117], v[176:179], v[184:187], v[114:117]
	v_mfma_f32_16x16x32_bf16 v[102:105], v[168:171], v[192:195], v[102:105]
	v_mfma_f32_16x16x32_bf16 v[98:101], v[176:179], v[192:195], v[98:101]
	v_mfma_f32_16x16x32_bf16 v[86:89], v[168:171], v[200:203], v[86:89]
	v_mfma_f32_16x16x32_bf16 v[82:85], v[176:179], v[200:203], v[82:85]
	v_mfma_f32_16x16x32_bf16 v[70:73], v[168:171], v[208:211], v[70:73]
	v_mfma_f32_16x16x32_bf16 v[66:69], v[176:179], v[208:211], v[66:69]
	s_barrier
	s_setprio 0
	s_add_i32 s17, s67, s45
	v_lshl_add_u64 v[140:141], s[54:55], 0, v[0:1]
	s_mov_b32 m0, s17
	ds_read_b128 v[180:183], v147 offset:16384
	ds_read_b128 v[184:187], v147 offset:17408
	ds_read_b128 v[188:191], v147 offset:18432
	ds_read_b128 v[192:195], v147 offset:19456
	ds_read_b128 v[196:199], v147 offset:20480
	ds_read_b128 v[200:203], v147 offset:21504
	ds_read_b128 v[204:207], v147 offset:22528
	ds_read_b128 v[208:211], v147 offset:23552
	global_load_lds_dwordx4 v[140:141], off
	s_add_i32 m0, s17, 0x2000
	s_add_u32 s70, s54, 0x80000
	v_lshl_add_u64 v[212:213], s[54:55], 0, v[130:131]
	s_addc_u32 s71, s55, 0
	s_add_i32 s16, s16, s45
	global_load_lds_dwordx4 v[212:213], off
	v_lshl_add_u64 v[214:215], s[70:71], 0, v[0:1]
	s_mov_b32 m0, s16
	v_lshl_add_u64 v[216:217], s[52:53], 0, v[132:133]
	global_load_lds_dwordx4 v[214:215], off
	v_lshl_add_u64 v[214:215], s[70:71], 0, v[130:131]
	s_add_i32 m0, s16, 0x2000
	s_nop 0
	global_load_lds_dwordx4 v[214:215], off
	v_lshl_add_u64 v[214:215], s[52:53], 0, v[134:135]
	s_mov_b32 m0, s47
	s_nop 0
	global_load_lds_dwordx4 v[214:215], off
	s_mov_b32 m0, s57
	s_nop 0
	global_load_lds_dwordx4 v[216:217], off
	s_waitcnt vmcnt(8)
	s_waitcnt lgkmcnt(0)
	s_barrier
; #define PG8_STAGE(bufoff, gbase, voff) do { _Pragma("unroll") for (int _i = 0; _i < 2; ++_i) \
;         __builtin_amdgcn_global_load_lds((const unsigned*)((const char*)(gbase) + (voff)[_i]), (LAS unsigned*)(lds + (bufoff) + ldsw + _i * 8192), 16, 0, 0); } while (0)
; #define PG8_LDA(dst, b, h) do { _Pragma("unroll") for (int m = 0; m < 4; ++m) _Pragma("unroll") for (int k = 0; k < 2; ++k) dst[m][k] = *(const LAS bf16x8*)(lds + PG8_SA(b, h) + aoff + m * 2048 + k * 1024); } while (0)
; #define PG8_LDB(dst, b, h) do { _Pragma("unroll") for (int n = 0; n < 2; ++n) _Pragma("unroll") for (int k = 0; k < 2; ++k) dst[n][k] = *(const LAS bf16x8*)(lds + PG8_SB(b, h) + boff + n * 2048 + k * 1024); } while (0)
; #define PG8_MMA(ai, bj, At, Bt) do { __builtin_amdgcn_s_setprio(1); _Pragma("unroll") for (int m = 0; m < 4; ++m) _Pragma("unroll") for (int n = 0; n < 2; ++n) _Pragma("unroll") for (int k = 0; k < 2; ++k) \
;         acc[ai][bj][m][n] = __builtin_amdgcn_mfma_f32_16x16x32_bf16(Bt[n][k], At[m][k], acc[ai][bj][m][n], 0, 0, 0); __builtin_amdgcn_s_setprio(0); } while (0)
; #define PG8_WAIT_V(n) asm volatile("s_waitcnt vmcnt(" #n ")" ::: "memory")
; #define PG8_BAR __builtin_amdgcn_s_barrier()
; template <class Epi, class Sched, bool ALIGN_EPI, bool LAST_FUSED = false, bool PERM = false, bool CARRY = false>
; __device__ __forceinline__ void gemm_phase(LAS unsigned char* lds, const int tid, const int K, const int lda, const int ldb, const Sched& S, const Epi& E) {
;     ...
;             PG8_WAIT_V(8); PG8_WAIT_L(0); PG8_BAR; PG8_MMA(0, 0, At, B0); PG8_MMA(0, 1, At, B1); PG8_BAR; PG8_SCHED;
;             PG8_LDA(At, 0, 1); PG8_STAGE(PG8_SB(0, 0), b2, voffB); PG8_STAGE(PG8_SB(0, 1), b2 + hstepB, voffB); PG8_STAGE(PG8_SA(0, 0), a2, voffA);
;             PG8_WAIT_V(8); PG8_WAIT_L(0); PG8_BAR; PG8_MMA(1, 0, At, B0); PG8_MMA(1, 1, At, B1); PG8_BAR; PG8_SCHED;
;             PG8_LDB(B0, 1, 0); PG8_LDB(B1, 1, 1); PG8_SCHED; PG8_LDA(At, 1, 0); PG8_STAGE(PG8_SA(0, 1), a2 + hstepA, voffA);
;             PG8_WAIT_V(8); PG8_WAIT_L(0); PG8_BAR; PG8_MMA(0, 0, At, B0); PG8_MMA(0, 1, At, B1); PG8_BAR; PG8_SCHED;
;             PG8_LDA(At, 1, 1); PG8_STAGE(PG8_SB(1, 0), b3, voffB); PG8_STAGE(PG8_SB(1, 1), b3 + hstepB, voffB); PG8_STAGE(PG8_SA(1, 0), a3, voffA);
;             PG8_WAIT_V(8); PG8_WAIT_L(0); PG8_BAR; PG8_MMA(1, 0, At, B0); PG8_MMA(1, 1, At, B1); PG8_BAR; PG8_SCHED;
	s_setprio 1
	v_mfma_f32_16x16x32_bf16 v[62:65], v[148:151], v[180:183], v[62:65]
	v_mfma_f32_16x16x32_bf16 v[58:61], v[156:159], v[180:183], v[58:61]
	v_mfma_f32_16x16x32_bf16 v[46:49], v[148:151], v[188:191], v[46:49]
	v_mfma_f32_16x16x32_bf16 v[42:45], v[156:159], v[188:191], v[42:45]
	v_mfma_f32_16x16x32_bf16 v[30:33], v[148:151], v[196:199], v[30:33]
	v_mfma_f32_16x16x32_bf16 v[26:29], v[156:159], v[196:199], v[26:29]
	v_mfma_f32_16x16x32_bf16 v[14:17], v[148:151], v[204:207], v[14:17]
	v_mfma_f32_16x16x32_bf16 v[10:13], v[156:159], v[204:207], v[10:13]
	v_mfma_f32_16x16x32_bf16 v[62:65], v[152:155], v[184:187], v[62:65]
	v_mfma_f32_16x16x32_bf16 v[58:61], v[160:163], v[184:187], v[58:61]
	v_mfma_f32_16x16x32_bf16 v[46:49], v[152:155], v[192:195], v[46:49]
	v_mfma_f32_16x16x32_bf16 v[42:45], v[160:163], v[192:195], v[42:45]
	v_mfma_f32_16x16x32_bf16 v[30:33], v[152:155], v[200:203], v[30:33]
	v_mfma_f32_16x16x32_bf16 v[26:29], v[160:163], v[200:203], v[26:29]
	v_mfma_f32_16x16x32_bf16 v[14:17], v[152:155], v[208:211], v[14:17]
	v_mfma_f32_16x16x32_bf16 v[10:13], v[160:163], v[208:211], v[10:13]
	v_mfma_f32_16x16x32_bf16 v[54:57], v[164:167], v[180:183], v[54:57]
	v_mfma_f32_16x16x32_bf16 v[50:53], v[172:175], v[180:183], v[50:53]
	v_mfma_f32_16x16x32_bf16 v[38:41], v[164:167], v[188:191], v[38:41]
	v_mfma_f32_16x16x32_bf16 v[34:37], v[172:175], v[188:191], v[34:37]
	v_mfma_f32_16x16x32_bf16 v[22:25], v[164:167], v[196:199], v[22:25]
	v_mfma_f32_16x16x32_bf16 v[18:21], v[172:175], v[196:199], v[18:21]
	v_mfma_f32_16x16x32_bf16 v[6:9], v[164:167], v[204:207], v[6:9]
	v_mfma_f32_16x16x32_bf16 v[2:5], v[172:175], v[204:207], v[2:5]
	v_mfma_f32_16x16x32_bf16 v[54:57], v[168:171], v[184:187], v[54:57]
	v_mfma_f32_16x16x32_bf16 v[50:53], v[176:179], v[184:187], v[50:53]
	v_mfma_f32_16x16x32_bf16 v[38:41], v[168:171], v[192:195], v[38:41]
	v_mfma_f32_16x16x32_bf16 v[34:37], v[176:179], v[192:195], v[34:37]
	v_mfma_f32_16x16x32_bf16 v[22:25], v[168:171], v[200:203], v[22:25]
	v_mfma_f32_16x16x32_bf16 v[18:21], v[176:179], v[200:203], v[18:21]
	v_mfma_f32_16x16x32_bf16 v[6:9], v[168:171], v[208:211], v[6:9]
	v_mfma_f32_16x16x32_bf16 v[2:5], v[176:179], v[208:211], v[2:5]
	s_barrier
	s_setprio 0
	s_add_i32 s16, 0, 0x18000
	s_add_i32 s17, 0, 0x1c000
	v_add_u32_e32 v160, s16, v146
	v_add_u32_e32 v176, s17, v146
	ds_read_b128 v[148:151], v160
	ds_read_b128 v[152:155], v160 offset:1024
	ds_read_b128 v[156:159], v160 offset:2048
	ds_read_b128 v[160:163], v160 offset:3072
	ds_read_b128 v[164:167], v176
	ds_read_b128 v[168:171], v176 offset:1024
	ds_read_b128 v[172:175], v176 offset:2048
	ds_read_b128 v[176:179], v176 offset:3072
	s_add_u32 s52, s52, 0x80000
	s_addc_u32 s53, s53, 0
	s_mov_b32 m0, s58
	v_lshl_add_u64 v[218:219], s[52:53], 0, v[134:135]
	ds_read_b128 v[180:183], v147 offset:32768
	ds_read_b128 v[184:187], v147 offset:33792
	ds_read_b128 v[188:191], v147 offset:34816
	ds_read_b128 v[192:195], v147 offset:35840
	ds_read_b128 v[196:199], v147 offset:36864
	ds_read_b128 v[200:203], v147 offset:37888
	ds_read_b128 v[204:207], v147 offset:38912
	ds_read_b128 v[208:211], v147 offset:39936
	global_load_lds_dwordx4 v[218:219], off
	v_lshl_add_u64 v[218:219], s[52:53], 0, v[132:133]
	s_mov_b32 m0, s59
	s_nop 0
	global_load_lds_dwordx4 v[218:219], off
	s_waitcnt vmcnt(8)
	s_waitcnt lgkmcnt(0)
	s_barrier
	s_setprio 1
	v_mfma_f32_16x16x32_bf16 v[126:129], v[148:151], v[180:183], v[126:129]
	v_mfma_f32_16x16x32_bf16 v[122:125], v[156:159], v[180:183], v[122:125]
	v_mfma_f32_16x16x32_bf16 v[110:113], v[148:151], v[188:191], v[110:113]
	v_mfma_f32_16x16x32_bf16 v[106:109], v[156:159], v[188:191], v[106:109]
	v_mfma_f32_16x16x32_bf16 v[94:97], v[148:151], v[196:199], v[94:97]
	v_mfma_f32_16x16x32_bf16 v[90:93], v[156:159], v[196:199], v[90:93]
	v_mfma_f32_16x16x32_bf16 v[78:81], v[148:151], v[204:207], v[78:81]
	v_mfma_f32_16x16x32_bf16 v[74:77], v[156:159], v[204:207], v[74:77]
	v_mfma_f32_16x16x32_bf16 v[126:129], v[152:155], v[184:187], v[126:129]
	v_mfma_f32_16x16x32_bf16 v[122:125], v[160:163], v[184:187], v[122:125]
	v_mfma_f32_16x16x32_bf16 v[110:113], v[152:155], v[192:195], v[110:113]
	v_mfma_f32_16x16x32_bf16 v[106:109], v[160:163], v[192:195], v[106:109]
	v_mfma_f32_16x16x32_bf16 v[94:97], v[152:155], v[200:203], v[94:97]
	v_mfma_f32_16x16x32_bf16 v[90:93], v[160:163], v[200:203], v[90:93]
	v_mfma_f32_16x16x32_bf16 v[78:81], v[152:155], v[208:211], v[78:81]
	v_mfma_f32_16x16x32_bf16 v[74:77], v[160:163], v[208:211], v[74:77]
	v_mfma_f32_16x16x32_bf16 v[118:121], v[164:167], v[180:183], v[118:121]
	v_mfma_f32_16x16x32_bf16 v[114:117], v[172:175], v[180:183], v[114:117]
	v_mfma_f32_16x16x32_bf16 v[102:105], v[164:167], v[188:191], v[102:105]
	v_mfma_f32_16x16x32_bf16 v[98:101], v[172:175], v[188:191], v[98:101]
	v_mfma_f32_16x16x32_bf16 v[86:89], v[164:167], v[196:199], v[86:89]
	v_mfma_f32_16x16x32_bf16 v[82:85], v[172:175], v[196:199], v[82:85]
	v_mfma_f32_16x16x32_bf16 v[70:73], v[164:167], v[204:207], v[70:73]
	v_mfma_f32_16x16x32_bf16 v[66:69], v[172:175], v[204:207], v[66:69]
	v_mfma_f32_16x16x32_bf16 v[118:121], v[168:171], v[184:187], v[118:121]
	v_mfma_f32_16x16x32_bf16 v[114:117], v[176:179], v[184:187], v[114:117]
	v_mfma_f32_16x16x32_bf16 v[102:105], v[168:171], v[192:195], v[102:105]
	v_mfma_f32_16x16x32_bf16 v[98:101], v[176:179], v[192:195], v[98:101]
	v_mfma_f32_16x16x32_bf16 v[86:89], v[168:171], v[200:203], v[86:89]
	v_mfma_f32_16x16x32_bf16 v[82:85], v[176:179], v[200:203], v[82:85]
	v_mfma_f32_16x16x32_bf16 v[70:73], v[168:171], v[208:211], v[70:73]
	v_mfma_f32_16x16x32_bf16 v[66:69], v[176:179], v[208:211], v[66:69]
	s_barrier
; #define PG8_STAGE(bufoff, gbase, voff) do { _Pragma("unroll") for (int _i = 0; _i < 2; ++_i) \
;         __builtin_amdgcn_global_load_lds((const unsigned*)((const char*)(gbase) + (voff)[_i]), (LAS unsigned*)(lds + (bufoff) + ldsw + _i * 8192), 16, 0, 0); } while (0)
; #define PG8_LDA(dst, b, h) do { _Pragma("unroll") for (int m = 0; m < 4; ++m) _Pragma("unroll") for (int k = 0; k < 2; ++k) dst[m][k] = *(const LAS bf16x8*)(lds + PG8_SA(b, h) + aoff + m * 2048 + k * 1024); } while (0)
; #define PG8_MMA(ai, bj, At, Bt) do { __builtin_amdgcn_s_setprio(1); _Pragma("unroll") for (int m = 0; m < 4; ++m) _Pragma("unroll") for (int n = 0; n < 2; ++n) _Pragma("unroll") for (int k = 0; k < 2; ++k) \
;         acc[ai][bj][m][n] = __builtin_amdgcn_mfma_f32_16x16x32_bf16(Bt[n][k], At[m][k], acc[ai][bj][m][n], 0, 0, 0); __builtin_amdgcn_s_setprio(0); } while (0)
; #define PG8_WAIT_V(n) asm volatile("s_waitcnt vmcnt(" #n ")" ::: "memory")
; #define PG8_WAIT_L(n) asm volatile("s_waitcnt lgkmcnt(" #n ")" ::: "memory")
; #define PG8_BAR __builtin_amdgcn_s_barrier()
; #define PG8_SCHED __builtin_amdgcn_sched_barrier(0)
; template <class Epi, class Sched, bool ALIGN_EPI, bool LAST_FUSED = false, bool PERM = false, bool CARRY = false>
; __device__ __forceinline__ void gemm_phase(LAS unsigned char* lds, const int tid, const int K, const int lda, const int ldb, const Sched& S, const Epi& E) {
;     ...
;             PG8_LDA(At, 1, 1); PG8_STAGE(PG8_SB(1, 0), b3, voffB); PG8_STAGE(PG8_SB(1, 1), b3 + hstepB, voffB); PG8_STAGE(PG8_SA(1, 0), a3, voffA);
;             PG8_WAIT_V(8); PG8_WAIT_L(0); PG8_BAR; PG8_MMA(1, 0, At, B0); PG8_MMA(1, 1, At, B1); PG8_BAR; PG8_SCHED;
;         }
;         if constexpr (ALIGN_EPI) { if (wr == 0) PG8_BAR; }
	s_setprio 0
	s_add_i32 s16, s16, s45
	v_lshl_add_u64 v[140:141], v[140:141], 0, s[68:69]
	s_mov_b32 m0, s16
	ds_read_b128 v[180:183], v147 offset:49152
	ds_read_b128 v[184:187], v147 offset:50176
	ds_read_b128 v[188:191], v147 offset:51200
	ds_read_b128 v[192:195], v147 offset:52224
	ds_read_b128 v[196:199], v147 offset:53248
	ds_read_b128 v[200:203], v147 offset:54272
	ds_read_b128 v[204:207], v147 offset:55296
	ds_read_b128 v[208:211], v147 offset:56320
	global_load_lds_dwordx4 v[140:141], off
	s_add_i32 m0, s16, 0x2000
	s_add_u32 s52, s54, 0x80080
	v_lshl_add_u64 v[140:141], v[212:213], 0, s[68:69]
	s_addc_u32 s53, s55, 0
	s_add_i32 s16, s17, s45
	global_load_lds_dwordx4 v[140:141], off
	v_lshl_add_u64 v[140:141], s[52:53], 0, v[0:1]
	s_mov_b32 m0, s16
	s_nop 0
	global_load_lds_dwordx4 v[140:141], off
	v_lshl_add_u64 v[140:141], s[52:53], 0, v[130:131]
	s_add_i32 m0, s16, 0x2000
	s_nop 0
	global_load_lds_dwordx4 v[140:141], off
	v_lshl_add_u64 v[140:141], v[214:215], 0, s[68:69]
	s_mov_b32 m0, s61
	s_nop 0
	global_load_lds_dwordx4 v[140:141], off
	v_lshl_add_u64 v[140:141], v[216:217], 0, s[68:69]
	s_mov_b32 m0, s62
	s_nop 0
	global_load_lds_dwordx4 v[140:141], off
	s_waitcnt vmcnt(8)
	s_waitcnt lgkmcnt(0)
	s_barrier
	s_setprio 1
	v_mfma_f32_16x16x32_bf16 v[62:65], v[148:151], v[180:183], v[62:65]
	v_mfma_f32_16x16x32_bf16 v[58:61], v[156:159], v[180:183], v[58:61]
	v_mfma_f32_16x16x32_bf16 v[46:49], v[148:151], v[188:191], v[46:49]
	v_mfma_f32_16x16x32_bf16 v[42:45], v[156:159], v[188:191], v[42:45]
	v_mfma_f32_16x16x32_bf16 v[30:33], v[148:151], v[196:199], v[30:33]
	v_mfma_f32_16x16x32_bf16 v[26:29], v[156:159], v[196:199], v[26:29]
	v_mfma_f32_16x16x32_bf16 v[14:17], v[148:151], v[204:207], v[14:17]
	v_mfma_f32_16x16x32_bf16 v[10:13], v[156:159], v[204:207], v[10:13]
	v_mfma_f32_16x16x32_bf16 v[62:65], v[152:155], v[184:187], v[62:65]
	v_mfma_f32_16x16x32_bf16 v[58:61], v[160:163], v[184:187], v[58:61]
	v_mfma_f32_16x16x32_bf16 v[46:49], v[152:155], v[192:195], v[46:49]
	v_mfma_f32_16x16x32_bf16 v[42:45], v[160:163], v[192:195], v[42:45]
	v_mfma_f32_16x16x32_bf16 v[30:33], v[152:155], v[200:203], v[30:33]
	v_mfma_f32_16x16x32_bf16 v[26:29], v[160:163], v[200:203], v[26:29]
	v_mfma_f32_16x16x32_bf16 v[14:17], v[152:155], v[208:211], v[14:17]
	v_mfma_f32_16x16x32_bf16 v[10:13], v[160:163], v[208:211], v[10:13]
	v_mfma_f32_16x16x32_bf16 v[54:57], v[164:167], v[180:183], v[54:57]
	v_mfma_f32_16x16x32_bf16 v[50:53], v[172:175], v[180:183], v[50:53]
	v_mfma_f32_16x16x32_bf16 v[38:41], v[164:167], v[188:191], v[38:41]
	v_mfma_f32_16x16x32_bf16 v[34:37], v[172:175], v[188:191], v[34:37]
	v_mfma_f32_16x16x32_bf16 v[22:25], v[164:167], v[196:199], v[22:25]
	v_mfma_f32_16x16x32_bf16 v[18:21], v[172:175], v[196:199], v[18:21]
	v_mfma_f32_16x16x32_bf16 v[6:9], v[164:167], v[204:207], v[6:9]
	v_mfma_f32_16x16x32_bf16 v[2:5], v[172:175], v[204:207], v[2:5]
	v_mfma_f32_16x16x32_bf16 v[54:57], v[168:171], v[184:187], v[54:57]
	v_mfma_f32_16x16x32_bf16 v[50:53], v[176:179], v[184:187], v[50:53]
	v_mfma_f32_16x16x32_bf16 v[38:41], v[168:171], v[192:195], v[38:41]
	v_mfma_f32_16x16x32_bf16 v[34:37], v[176:179], v[192:195], v[34:37]
	v_mfma_f32_16x16x32_bf16 v[22:25], v[168:171], v[200:203], v[22:25]
	v_mfma_f32_16x16x32_bf16 v[18:21], v[176:179], v[200:203], v[18:21]
	v_mfma_f32_16x16x32_bf16 v[6:9], v[168:171], v[208:211], v[6:9]
	v_mfma_f32_16x16x32_bf16 v[2:5], v[176:179], v[208:211], v[2:5]
	s_barrier
	s_setprio 0
	s_add_i32 s41, s41, 2
	s_add_u32 s48, s48, 0x100
	s_addc_u32 s49, s49, 0
	s_add_u32 s27, s27, 0x100
	s_addc_u32 s39, s39, 0
	s_cmp_gt_u32 s41, 29
	s_cbranch_scc0 .LBB0_1763
	s_and_b64 vcc, exec, s[36:37]
	s_cbranch_vccz .LBB0_1766
	s_barrier

; #define PG8_STAGE(bufoff, gbase, voff) do { _Pragma("unroll") for (int _i = 0; _i < 2; ++_i) \
;         __builtin_amdgcn_global_load_lds((const unsigned*)((const char*)(gbase) + (voff)[_i]), (LAS unsigned*)(lds + (bufoff) + ldsw + _i * 8192), 16, 0, 0); } while (0)
; #define PG8_LDA(dst, b, h) do { _Pragma("unroll") for (int m = 0; m < 4; ++m) _Pragma("unroll") for (int k = 0; k < 2; ++k) dst[m][k] = *(const LAS bf16x8*)(lds + PG8_SA(b, h) + aoff + m * 2048 + k * 1024); } while (0)
; #define PG8_LDB(dst, b, h) do { _Pragma("unroll") for (int n = 0; n < 2; ++n) _Pragma("unroll") for (int k = 0; k < 2; ++k) dst[n][k] = *(const LAS bf16x8*)(lds + PG8_SB(b, h) + boff + n * 2048 + k * 1024); } while (0)
; #define PG8_MMA(ai, bj, At, Bt) do { __builtin_amdgcn_s_setprio(1); _Pragma("unroll") for (int m = 0; m < 4; ++m) _Pragma("unroll") for (int n = 0; n < 2; ++n) _Pragma("unroll") for (int k = 0; k < 2; ++k) \
;         acc[ai][bj][m][n] = __builtin_amdgcn_mfma_f32_16x16x32_bf16(Bt[n][k], At[m][k], acc[ai][bj][m][n], 0, 0, 0); __builtin_amdgcn_s_setprio(0); } while (0)
; #define PG8_WAIT_V(n) asm volatile("s_waitcnt vmcnt(" #n ")" ::: "memory")
; #define PG8_WAIT_L(n) asm volatile("s_waitcnt lgkmcnt(" #n ")" ::: "memory")
; template <class Epi, class Sched, bool ALIGN_EPI, bool LAST_FUSED = false, bool PERM = false, bool CARRY = false>
; __device__ __forceinline__ void gemm_phase(LAS unsigned char* lds, const int tid, const int K, const int lda, const int ldb, const Sched& S, const Epi& E) {
;     ...
;         for (int t = 0; t < nt; t += 2) {
;             const bool last = (t == nt - 2);
;             const char* a1 = cA + (size_t)(t + 1) * kstep;
;             const char* a2 = last ? nA : cA + (size_t)(t + 2) * kstep; const char* b2 = last ? nB : cB + (size_t)(t + 2) * kstep;
;             const char* a3 = a2 + kstep; const char* b3 = b2 + kstep;
;             PG8_LDB(B0, 0, 0); PG8_LDB(B1, 0, 1); PG8_SCHED; PG8_LDA(At, 0, 0); PG8_STAGE(PG8_SA(1, 1), a1 + hstepA, voffA);
;             PG8_WAIT_V(8); PG8_WAIT_L(0); PG8_BAR; PG8_MMA(0, 0, At, B0); PG8_MMA(0, 1, At, B1); PG8_BAR; PG8_SCHED;
;             PG8_LDA(At, 0, 1); PG8_STAGE(PG8_SB(0, 0), b2, voffB); PG8_STAGE(PG8_SB(0, 1), b2 + hstepB, voffB); PG8_STAGE(PG8_SA(0, 0), a2, voffA);
;             PG8_WAIT_V(8); PG8_WAIT_L(0); PG8_BAR; PG8_MMA(1, 0, At, B0); PG8_MMA(1, 1, At, B1); PG8_BAR; PG8_SCHED;
.LBB0_1854:
	s_add_u32 s16, s66, vcc_lo
	s_addc_u32 s17, s67, vcc_hi
	s_add_u32 s52, s50, vcc_lo
	s_addc_u32 s53, s51, vcc_hi
	s_add_i32 s92, 0, 0x10000
	s_cmp_eq_u32 s87, s60
	s_cselect_b32 s57, s24, s17
	s_cselect_b32 s56, s91, s16
	v_add_u32_e32 v154, s92, v140
	s_cselect_b32 s53, s70, s53
	s_cselect_b32 s52, s71, s52
	s_add_i32 s93, 0, 0x14000
	ds_read_b128 v[142:145], v154
	ds_read_b128 v[146:149], v154 offset:1024
	ds_read_b128 v[150:153], v154 offset:2048
	ds_read_b128 v[158:161], v154 offset:3072
	v_add_u32_e32 v154, s93, v140
	ds_read_b128 v[162:165], v154
	ds_read_b128 v[166:169], v154 offset:1024
	ds_read_b128 v[170:173], v154 offset:2048
	ds_read_b128 v[174:177], v154 offset:3072
	v_lshl_add_u64 v[154:155], s[66:67], 0, v[138:139]
	s_add_i32 m0, s28, 0xc000
	ds_read_b128 v[178:181], v141
	ds_read_b128 v[182:185], v141 offset:1024
	ds_read_b128 v[186:189], v141 offset:2048
	ds_read_b128 v[190:193], v141 offset:3072
	ds_read_b128 v[194:197], v141 offset:4096
	ds_read_b128 v[198:201], v141 offset:5120
	ds_read_b128 v[202:205], v141 offset:6144
	ds_read_b128 v[206:209], v141 offset:7168
	global_load_lds_dwordx4 v[154:155], off
	v_lshl_add_u64 v[154:155], s[66:67], 0, v[128:129]
	s_add_i32 m0, s28, 0xe000
	s_nop 0
	global_load_lds_dwordx4 v[154:155], off
	s_waitcnt vmcnt(8)
	s_waitcnt lgkmcnt(0)
	s_barrier
	s_setprio 1
	v_mfma_f32_16x16x32_bf16 v[118:121], v[142:145], v[178:181], v[118:121]
	v_mfma_f32_16x16x32_bf16 v[114:117], v[150:153], v[178:181], v[114:117]
	v_mfma_f32_16x16x32_bf16 v[110:113], v[142:145], v[186:189], v[110:113]
	v_mfma_f32_16x16x32_bf16 v[106:109], v[150:153], v[186:189], v[106:109]
	v_mfma_f32_16x16x32_bf16 v[86:89], v[142:145], v[194:197], v[86:89]
	v_mfma_f32_16x16x32_bf16 v[82:85], v[150:153], v[194:197], v[82:85]
	v_mfma_f32_16x16x32_bf16 v[78:81], v[142:145], v[202:205], v[78:81]
	v_mfma_f32_16x16x32_bf16 v[74:77], v[150:153], v[202:205], v[74:77]
	v_mfma_f32_16x16x32_bf16 v[118:121], v[146:149], v[182:185], v[118:121]
	v_mfma_f32_16x16x32_bf16 v[114:117], v[158:161], v[182:185], v[114:117]
	v_mfma_f32_16x16x32_bf16 v[110:113], v[146:149], v[190:193], v[110:113]
	v_mfma_f32_16x16x32_bf16 v[106:109], v[158:161], v[190:193], v[106:109]
	v_mfma_f32_16x16x32_bf16 v[86:89], v[146:149], v[198:201], v[86:89]
	v_mfma_f32_16x16x32_bf16 v[82:85], v[158:161], v[198:201], v[82:85]
	v_mfma_f32_16x16x32_bf16 v[78:81], v[146:149], v[206:209], v[78:81]
	v_mfma_f32_16x16x32_bf16 v[74:77], v[158:161], v[206:209], v[74:77]
	v_mfma_f32_16x16x32_bf16 v[98:101], v[162:165], v[178:181], v[98:101]
	v_mfma_f32_16x16x32_bf16 v[102:105], v[170:173], v[178:181], v[102:105]
	v_mfma_f32_16x16x32_bf16 v[90:93], v[162:165], v[186:189], v[90:93]
	v_mfma_f32_16x16x32_bf16 v[94:97], v[170:173], v[186:189], v[94:97]
	v_mfma_f32_16x16x32_bf16 v[66:69], v[162:165], v[194:197], v[66:69]
	v_mfma_f32_16x16x32_bf16 v[70:73], v[170:173], v[194:197], v[70:73]
	v_mfma_f32_16x16x32_bf16 v[50:53], v[162:165], v[202:205], v[50:53]
	v_mfma_f32_16x16x32_bf16 v[54:57], v[170:173], v[202:205], v[54:57]
	v_mfma_f32_16x16x32_bf16 v[98:101], v[166:169], v[182:185], v[98:101]
	v_mfma_f32_16x16x32_bf16 v[102:105], v[174:177], v[182:185], v[102:105]
	v_mfma_f32_16x16x32_bf16 v[90:93], v[166:169], v[190:193], v[90:93]
	v_mfma_f32_16x16x32_bf16 v[94:97], v[174:177], v[190:193], v[94:97]
	v_mfma_f32_16x16x32_bf16 v[66:69], v[166:169], v[198:201], v[66:69]
	v_mfma_f32_16x16x32_bf16 v[70:73], v[174:177], v[198:201], v[70:73]
	v_mfma_f32_16x16x32_bf16 v[50:53], v[166:169], v[206:209], v[50:53]
	v_mfma_f32_16x16x32_bf16 v[54:57], v[174:177], v[206:209], v[54:57]
	s_barrier
	s_setprio 0
	s_add_i32 s16, s92, s95
	v_lshl_add_u64 v[154:155], s[52:53], 0, v[0:1]
	s_mov_b32 m0, s16
	ds_read_b128 v[178:181], v141 offset:16384
	ds_read_b128 v[182:185], v141 offset:17408
	ds_read_b128 v[186:189], v141 offset:18432
	ds_read_b128 v[190:193], v141 offset:19456
	ds_read_b128 v[194:197], v141 offset:20480
	ds_read_b128 v[198:201], v141 offset:21504
	ds_read_b128 v[202:205], v141 offset:22528
	ds_read_b128 v[206:209], v141 offset:23552
	global_load_lds_dwordx4 v[154:155], off
	s_add_i32 m0, s16, 0x2000
	s_add_u32 s16, s52, 0x200000
	v_lshl_add_u64 v[210:211], s[52:53], 0, v[122:123]
	s_addc_u32 s17, s53, 0
	s_add_i32 s92, s93, s95
	global_load_lds_dwordx4 v[210:211], off
	v_lshl_add_u64 v[212:213], s[16:17], 0, v[0:1]
	s_mov_b32 m0, s92
	v_lshl_add_u64 v[214:215], s[56:57], 0, v[122:123]
	global_load_lds_dwordx4 v[212:213], off
	v_lshl_add_u64 v[212:213], s[16:17], 0, v[122:123]
	s_add_i32 m0, s92, 0x2000
	s_nop 0
	global_load_lds_dwordx4 v[212:213], off
	v_lshl_add_u64 v[212:213], s[56:57], 0, v[0:1]
	s_mov_b32 m0, s28
	s_nop 0
	global_load_lds_dwordx4 v[212:213], off
	s_mov_b32 m0, s29
	s_nop 0
	global_load_lds_dwordx4 v[214:215], off
	s_waitcnt vmcnt(8)
	s_waitcnt lgkmcnt(0)
	s_barrier
; #define PG8_STAGE(bufoff, gbase, voff) do { _Pragma("unroll") for (int _i = 0; _i < 2; ++_i) \
;         __builtin_amdgcn_global_load_lds((const unsigned*)((const char*)(gbase) + (voff)[_i]), (LAS unsigned*)(lds + (bufoff) + ldsw + _i * 8192), 16, 0, 0); } while (0)
; #define PG8_LDA(dst, b, h) do { _Pragma("unroll") for (int m = 0; m < 4; ++m) _Pragma("unroll") for (int k = 0; k < 2; ++k) dst[m][k] = *(const LAS bf16x8*)(lds + PG8_SA(b, h) + aoff + m * 2048 + k * 1024); } while (0)
; #define PG8_LDB(dst, b, h) do { _Pragma("unroll") for (int n = 0; n < 2; ++n) _Pragma("unroll") for (int k = 0; k < 2; ++k) dst[n][k] = *(const LAS bf16x8*)(lds + PG8_SB(b, h) + boff + n * 2048 + k * 1024); } while (0)
; #define PG8_MMA(ai, bj, At, Bt) do { __builtin_amdgcn_s_setprio(1); _Pragma("unroll") for (int m = 0; m < 4; ++m) _Pragma("unroll") for (int n = 0; n < 2; ++n) _Pragma("unroll") for (int k = 0; k < 2; ++k) \
;         acc[ai][bj][m][n] = __builtin_amdgcn_mfma_f32_16x16x32_bf16(Bt[n][k], At[m][k], acc[ai][bj][m][n], 0, 0, 0); __builtin_amdgcn_s_setprio(0); } while (0)
; #define PG8_WAIT_V(n) asm volatile("s_waitcnt vmcnt(" #n ")" ::: "memory")
; #define PG8_WAIT_L(n) asm volatile("s_waitcnt lgkmcnt(" #n ")" ::: "memory")
; #define PG8_BAR __builtin_amdgcn_s_barrier()
; #define PG8_SCHED __builtin_amdgcn_sched_barrier(0)
; template <class Epi, class Sched, bool ALIGN_EPI, bool LAST_FUSED = false, bool PERM = false, bool CARRY = false>
; __device__ __forceinline__ void gemm_phase(LAS unsigned char* lds, const int tid, const int K, const int lda, const int ldb, const Sched& S, const Epi& E) {
;     ...
;             PG8_WAIT_V(8); PG8_WAIT_L(0); PG8_BAR; PG8_MMA(1, 0, At, B0); PG8_MMA(1, 1, At, B1); PG8_BAR; PG8_SCHED;
;             PG8_LDB(B0, 1, 0); PG8_LDB(B1, 1, 1); PG8_SCHED; PG8_LDA(At, 1, 0); PG8_STAGE(PG8_SA(0, 1), a2 + hstepA, voffA);
;             PG8_WAIT_V(8); PG8_WAIT_L(0); PG8_BAR; PG8_MMA(0, 0, At, B0); PG8_MMA(0, 1, At, B1); PG8_BAR; PG8_SCHED;
	s_setprio 1
	v_mfma_f32_16x16x32_bf16 v[62:65], v[142:145], v[178:181], v[62:65]
	v_mfma_f32_16x16x32_bf16 v[58:61], v[150:153], v[178:181], v[58:61]
	v_mfma_f32_16x16x32_bf16 v[38:41], v[142:145], v[186:189], v[38:41]
	v_mfma_f32_16x16x32_bf16 v[34:37], v[150:153], v[186:189], v[34:37]
	v_mfma_f32_16x16x32_bf16 v[22:25], v[142:145], v[194:197], v[22:25]
	v_mfma_f32_16x16x32_bf16 v[18:21], v[150:153], v[194:197], v[18:21]
	v_mfma_f32_16x16x32_bf16 v[134:137], v[142:145], v[202:205], v[134:137]
	v_mfma_f32_16x16x32_bf16 v[130:133], v[150:153], v[202:205], v[130:133]
	v_mfma_f32_16x16x32_bf16 v[62:65], v[146:149], v[182:185], v[62:65]
	v_mfma_f32_16x16x32_bf16 v[58:61], v[158:161], v[182:185], v[58:61]
	v_mfma_f32_16x16x32_bf16 v[38:41], v[146:149], v[190:193], v[38:41]
	v_mfma_f32_16x16x32_bf16 v[34:37], v[158:161], v[190:193], v[34:37]
	v_mfma_f32_16x16x32_bf16 v[22:25], v[146:149], v[198:201], v[22:25]
	v_mfma_f32_16x16x32_bf16 v[18:21], v[158:161], v[198:201], v[18:21]
	v_mfma_f32_16x16x32_bf16 v[134:137], v[146:149], v[206:209], v[134:137]
	v_mfma_f32_16x16x32_bf16 v[130:133], v[158:161], v[206:209], v[130:133]
	v_mfma_f32_16x16x32_bf16 v[42:45], v[162:165], v[178:181], v[42:45]
	v_mfma_f32_16x16x32_bf16 v[46:49], v[170:173], v[178:181], v[46:49]
	v_mfma_f32_16x16x32_bf16 v[26:29], v[162:165], v[186:189], v[26:29]
	v_mfma_f32_16x16x32_bf16 v[30:33], v[170:173], v[186:189], v[30:33]
	v_mfma_f32_16x16x32_bf16 v[14:17], v[162:165], v[194:197], v[14:17]
	v_mfma_f32_16x16x32_bf16 v[10:13], v[170:173], v[194:197], v[10:13]
	v_mfma_f32_16x16x32_bf16 v[6:9], v[162:165], v[202:205], v[6:9]
	v_mfma_f32_16x16x32_bf16 v[2:5], v[170:173], v[202:205], v[2:5]
	v_mfma_f32_16x16x32_bf16 v[42:45], v[166:169], v[182:185], v[42:45]
	v_mfma_f32_16x16x32_bf16 v[46:49], v[174:177], v[182:185], v[46:49]
	v_mfma_f32_16x16x32_bf16 v[26:29], v[166:169], v[190:193], v[26:29]
	v_mfma_f32_16x16x32_bf16 v[30:33], v[174:177], v[190:193], v[30:33]
	v_mfma_f32_16x16x32_bf16 v[14:17], v[166:169], v[198:201], v[14:17]
	v_mfma_f32_16x16x32_bf16 v[10:13], v[174:177], v[198:201], v[10:13]
	v_mfma_f32_16x16x32_bf16 v[6:9], v[166:169], v[206:209], v[6:9]
	v_mfma_f32_16x16x32_bf16 v[2:5], v[174:177], v[206:209], v[2:5]
	s_barrier
	s_setprio 0
	s_add_i32 s92, 0, 0x18000
	s_add_i32 s93, 0, 0x1c000
	v_add_u32_e32 v158, s92, v140
	v_add_u32_e32 v174, s93, v140
	ds_read_b128 v[142:145], v158
	ds_read_b128 v[146:149], v158 offset:1024
	ds_read_b128 v[150:153], v158 offset:2048
	ds_read_b128 v[158:161], v158 offset:3072
	ds_read_b128 v[162:165], v174
	ds_read_b128 v[166:169], v174 offset:1024
	ds_read_b128 v[170:173], v174 offset:2048
	ds_read_b128 v[174:177], v174 offset:3072
	s_add_u32 s16, s56, 0x200000
	s_addc_u32 s17, s57, 0
	s_mov_b32 m0, s14
	v_lshl_add_u64 v[216:217], s[16:17], 0, v[0:1]
	ds_read_b128 v[178:181], v141 offset:32768
	ds_read_b128 v[182:185], v141 offset:33792
	ds_read_b128 v[186:189], v141 offset:34816
	ds_read_b128 v[190:193], v141 offset:35840
	ds_read_b128 v[194:197], v141 offset:36864
	ds_read_b128 v[198:201], v141 offset:37888
	ds_read_b128 v[202:205], v141 offset:38912
	ds_read_b128 v[206:209], v141 offset:39936
	global_load_lds_dwordx4 v[216:217], off
	v_lshl_add_u64 v[216:217], s[16:17], 0, v[122:123]
	s_mov_b32 m0, s22
	s_nop 0
	global_load_lds_dwordx4 v[216:217], off
	s_waitcnt vmcnt(8)
	s_waitcnt lgkmcnt(0)
	s_barrier
	s_setprio 1
	v_mfma_f32_16x16x32_bf16 v[118:121], v[142:145], v[178:181], v[118:121]
	v_mfma_f32_16x16x32_bf16 v[114:117], v[150:153], v[178:181], v[114:117]
	v_mfma_f32_16x16x32_bf16 v[110:113], v[142:145], v[186:189], v[110:113]
	v_mfma_f32_16x16x32_bf16 v[106:109], v[150:153], v[186:189], v[106:109]
	v_mfma_f32_16x16x32_bf16 v[86:89], v[142:145], v[194:197], v[86:89]
	v_mfma_f32_16x16x32_bf16 v[82:85], v[150:153], v[194:197], v[82:85]
	v_mfma_f32_16x16x32_bf16 v[78:81], v[142:145], v[202:205], v[78:81]
	v_mfma_f32_16x16x32_bf16 v[74:77], v[150:153], v[202:205], v[74:77]
	v_mfma_f32_16x16x32_bf16 v[118:121], v[146:149], v[182:185], v[118:121]
	v_mfma_f32_16x16x32_bf16 v[114:117], v[158:161], v[182:185], v[114:117]
	v_mfma_f32_16x16x32_bf16 v[110:113], v[146:149], v[190:193], v[110:113]
	v_mfma_f32_16x16x32_bf16 v[106:109], v[158:161], v[190:193], v[106:109]
	v_mfma_f32_16x16x32_bf16 v[86:89], v[146:149], v[198:201], v[86:89]
	v_mfma_f32_16x16x32_bf16 v[82:85], v[158:161], v[198:201], v[82:85]
	v_mfma_f32_16x16x32_bf16 v[78:81], v[146:149], v[206:209], v[78:81]
	v_mfma_f32_16x16x32_bf16 v[74:77], v[158:161], v[206:209], v[74:77]
	v_mfma_f32_16x16x32_bf16 v[98:101], v[162:165], v[178:181], v[98:101]
	v_mfma_f32_16x16x32_bf16 v[102:105], v[170:173], v[178:181], v[102:105]
	v_mfma_f32_16x16x32_bf16 v[90:93], v[162:165], v[186:189], v[90:93]
	v_mfma_f32_16x16x32_bf16 v[94:97], v[170:173], v[186:189], v[94:97]
	v_mfma_f32_16x16x32_bf16 v[66:69], v[162:165], v[194:197], v[66:69]
	v_mfma_f32_16x16x32_bf16 v[70:73], v[170:173], v[194:197], v[70:73]
	v_mfma_f32_16x16x32_bf16 v[50:53], v[162:165], v[202:205], v[50:53]
	v_mfma_f32_16x16x32_bf16 v[54:57], v[170:173], v[202:205], v[54:57]
	v_mfma_f32_16x16x32_bf16 v[98:101], v[166:169], v[182:185], v[98:101]
	v_mfma_f32_16x16x32_bf16 v[102:105], v[174:177], v[182:185], v[102:105]
	v_mfma_f32_16x16x32_bf16 v[90:93], v[166:169], v[190:193], v[90:93]
	v_mfma_f32_16x16x32_bf16 v[94:97], v[174:177], v[190:193], v[94:97]
	v_mfma_f32_16x16x32_bf16 v[66:69], v[166:169], v[198:201], v[66:69]
	v_mfma_f32_16x16x32_bf16 v[70:73], v[174:177], v[198:201], v[70:73]
	v_mfma_f32_16x16x32_bf16 v[50:53], v[166:169], v[206:209], v[50:53]
	v_mfma_f32_16x16x32_bf16 v[54:57], v[174:177], v[206:209], v[54:57]
	s_barrier
; #define PG8_STAGE(bufoff, gbase, voff) do { _Pragma("unroll") for (int _i = 0; _i < 2; ++_i) \
;         __builtin_amdgcn_global_load_lds((const unsigned*)((const char*)(gbase) + (voff)[_i]), (LAS unsigned*)(lds + (bufoff) + ldsw + _i * 8192), 16, 0, 0); } while (0)
; #define PG8_LDA(dst, b, h) do { _Pragma("unroll") for (int m = 0; m < 4; ++m) _Pragma("unroll") for (int k = 0; k < 2; ++k) dst[m][k] = *(const LAS bf16x8*)(lds + PG8_SA(b, h) + aoff + m * 2048 + k * 1024); } while (0)
; #define PG8_MMA(ai, bj, At, Bt) do { __builtin_amdgcn_s_setprio(1); _Pragma("unroll") for (int m = 0; m < 4; ++m) _Pragma("unroll") for (int n = 0; n < 2; ++n) _Pragma("unroll") for (int k = 0; k < 2; ++k) \
;         acc[ai][bj][m][n] = __builtin_amdgcn_mfma_f32_16x16x32_bf16(Bt[n][k], At[m][k], acc[ai][bj][m][n], 0, 0, 0); __builtin_amdgcn_s_setprio(0); } while (0)
; #define PG8_WAIT_V(n) asm volatile("s_waitcnt vmcnt(" #n ")" ::: "memory")
; #define PG8_WAIT_L(n) asm volatile("s_waitcnt lgkmcnt(" #n ")" ::: "memory")
; #define PG8_BAR __builtin_amdgcn_s_barrier()
; #define PG8_SCHED __builtin_amdgcn_sched_barrier(0)
; template <class Epi, class Sched, bool ALIGN_EPI, bool LAST_FUSED = false, bool PERM = false, bool CARRY = false>
; __device__ __forceinline__ void gemm_phase(LAS unsigned char* lds, const int tid, const int K, const int lda, const int ldb, const Sched& S, const Epi& E) {
;     ...
;             PG8_LDA(At, 1, 1); PG8_STAGE(PG8_SB(1, 0), b3, voffB); PG8_STAGE(PG8_SB(1, 1), b3 + hstepB, voffB); PG8_STAGE(PG8_SA(1, 0), a3, voffA);
;             PG8_WAIT_V(8); PG8_WAIT_L(0); PG8_BAR; PG8_MMA(1, 0, At, B0); PG8_MMA(1, 1, At, B1); PG8_BAR; PG8_SCHED;
;         }
;         if constexpr (ALIGN_EPI) { if (wr == 0) PG8_BAR; }
	s_setprio 0
	s_add_i32 s16, s92, s95
	v_lshl_add_u64 v[154:155], v[154:155], 0, s[68:69]
	s_mov_b32 m0, s16
	ds_read_b128 v[178:181], v141 offset:49152
	ds_read_b128 v[182:185], v141 offset:50176
	ds_read_b128 v[186:189], v141 offset:51200
	ds_read_b128 v[190:193], v141 offset:52224
	ds_read_b128 v[194:197], v141 offset:53248
	ds_read_b128 v[198:201], v141 offset:54272
	ds_read_b128 v[202:205], v141 offset:55296
	ds_read_b128 v[206:209], v141 offset:56320
	global_load_lds_dwordx4 v[154:155], off
	s_add_i32 m0, s16, 0x2000
	s_add_u32 s16, s52, 0x200080
	v_lshl_add_u64 v[154:155], v[210:211], 0, s[68:69]
	s_addc_u32 s17, s53, 0
	s_add_i32 s52, s93, s95
	global_load_lds_dwordx4 v[154:155], off
	v_lshl_add_u64 v[154:155], s[16:17], 0, v[0:1]
	s_mov_b32 m0, s52
	s_nop 0
	global_load_lds_dwordx4 v[154:155], off
	v_lshl_add_u64 v[154:155], s[16:17], 0, v[122:123]
	s_add_i32 m0, s52, 0x2000
	s_nop 0
	global_load_lds_dwordx4 v[154:155], off
	v_lshl_add_u64 v[154:155], v[212:213], 0, s[68:69]
	s_mov_b32 m0, s96
	s_nop 0
	global_load_lds_dwordx4 v[154:155], off
	v_lshl_add_u64 v[154:155], v[214:215], 0, s[68:69]
	s_mov_b32 m0, s97
	s_nop 0
	global_load_lds_dwordx4 v[154:155], off
	s_waitcnt vmcnt(8)
	s_waitcnt lgkmcnt(0)
	s_barrier
	s_setprio 1
	v_mfma_f32_16x16x32_bf16 v[62:65], v[142:145], v[178:181], v[62:65]
	v_mfma_f32_16x16x32_bf16 v[58:61], v[150:153], v[178:181], v[58:61]
	v_mfma_f32_16x16x32_bf16 v[38:41], v[142:145], v[186:189], v[38:41]
	v_mfma_f32_16x16x32_bf16 v[34:37], v[150:153], v[186:189], v[34:37]
	v_mfma_f32_16x16x32_bf16 v[22:25], v[142:145], v[194:197], v[22:25]
	v_mfma_f32_16x16x32_bf16 v[18:21], v[150:153], v[194:197], v[18:21]
	v_mfma_f32_16x16x32_bf16 v[134:137], v[142:145], v[202:205], v[134:137]
	v_mfma_f32_16x16x32_bf16 v[130:133], v[150:153], v[202:205], v[130:133]
	v_mfma_f32_16x16x32_bf16 v[62:65], v[146:149], v[182:185], v[62:65]
	v_mfma_f32_16x16x32_bf16 v[58:61], v[158:161], v[182:185], v[58:61]
	v_mfma_f32_16x16x32_bf16 v[38:41], v[146:149], v[190:193], v[38:41]
	v_mfma_f32_16x16x32_bf16 v[34:37], v[158:161], v[190:193], v[34:37]
	v_mfma_f32_16x16x32_bf16 v[22:25], v[146:149], v[198:201], v[22:25]
	v_mfma_f32_16x16x32_bf16 v[18:21], v[158:161], v[198:201], v[18:21]
	v_mfma_f32_16x16x32_bf16 v[134:137], v[146:149], v[206:209], v[134:137]
	v_mfma_f32_16x16x32_bf16 v[130:133], v[158:161], v[206:209], v[130:133]
	v_mfma_f32_16x16x32_bf16 v[42:45], v[162:165], v[178:181], v[42:45]
	v_mfma_f32_16x16x32_bf16 v[46:49], v[170:173], v[178:181], v[46:49]
	v_mfma_f32_16x16x32_bf16 v[26:29], v[162:165], v[186:189], v[26:29]
	v_mfma_f32_16x16x32_bf16 v[30:33], v[170:173], v[186:189], v[30:33]
	v_mfma_f32_16x16x32_bf16 v[14:17], v[162:165], v[194:197], v[14:17]
	v_mfma_f32_16x16x32_bf16 v[10:13], v[170:173], v[194:197], v[10:13]
	v_mfma_f32_16x16x32_bf16 v[6:9], v[162:165], v[202:205], v[6:9]
	v_mfma_f32_16x16x32_bf16 v[2:5], v[170:173], v[202:205], v[2:5]
	v_mfma_f32_16x16x32_bf16 v[42:45], v[166:169], v[182:185], v[42:45]
	v_mfma_f32_16x16x32_bf16 v[46:49], v[174:177], v[182:185], v[46:49]
	v_mfma_f32_16x16x32_bf16 v[26:29], v[166:169], v[190:193], v[26:29]
	v_mfma_f32_16x16x32_bf16 v[30:33], v[174:177], v[190:193], v[30:33]
	v_mfma_f32_16x16x32_bf16 v[14:17], v[166:169], v[198:201], v[14:17]
	v_mfma_f32_16x16x32_bf16 v[10:13], v[174:177], v[198:201], v[10:13]
	v_mfma_f32_16x16x32_bf16 v[6:9], v[166:169], v[206:209], v[6:9]
	v_mfma_f32_16x16x32_bf16 v[2:5], v[174:177], v[206:209], v[2:5]
	s_barrier
	s_setprio 0
	s_add_i32 s16, s60, 2
	s_add_u32 vcc_lo, vcc_lo, 0x100
	s_addc_u32 vcc_hi, vcc_hi, 0
	v_lshl_add_u64 v[138:139], v[138:139], 0, s[72:73]
	v_lshl_add_u64 v[128:129], v[128:129], 0, s[72:73]
	s_cmp_ge_i32 s60, s87
	s_mov_b32 s60, s16
	s_cbranch_scc0 .LBB0_1854
	s_and_b64 vcc, exec, s[40:41]
	s_cbranch_vccz .LBB0_1857
	s_barrier
